# K-loops: per-iteration address arithmetic moved behind the first MFMAs; m0 writes hoisted above the preceding MFMA
# baseline (speedup 1.0000x reference)
.LBB0_147:
	s_waitcnt lgkmcnt(0)
	s_nop 0
	v_mfma_f32_32x32x16_bf16 v[112:127], v[150:153], v[142:145], v[112:127]
	v_mfma_f32_32x32x16_bf16 v[96:111], v[150:153], v[130:133], v[96:111]
	s_and_b32 s13, s12, 0x18000
	v_add_u32_e32 v222, s13, v180
	s_add_i32 s13, s12, 0xfffe8000
	s_and_b32 s13, s13, 0x18000
	v_or_b32_e32 v223, s13, v179
	v_add_u32_e32 v233, s13, v176
	s_waitcnt vmcnt(8)
	s_barrier
	v_add_u32_e32 v206, v223, v177
	v_add_u32_e32 v234, v233, v177
	ds_read_b128 v[202:205], v206 offset:16384
	ds_read_b128 v[206:209], v206 offset:18432
	ds_read_b128 v[210:213], v234
	v_mfma_f32_32x32x16_bf16 v[80:95], v[146:149], v[142:145], v[80:95]
	v_readfirstlane_b32 s13, v222
	s_mov_b32 m0, s13
	v_mfma_f32_32x32x16_bf16 v[64:79], v[146:149], v[130:133], v[64:79]
	ds_read_b128 v[214:217], v234 offset:2048
	global_load_lds_dwordx4 v[170:171], off
	v_mfma_f32_32x32x16_bf16 v[48:63], v[138:141], v[142:145], v[48:63]
	s_add_i32 s14, s13, 0x2000
	v_lshl_add_u64 v[150:151], v[170:171], 0, s[34:35]
	s_mov_b32 m0, s14
	v_mfma_f32_32x32x16_bf16 v[32:47], v[138:141], v[130:133], v[32:47]
	ds_read_b128 v[224:227], v234 offset:4096
	global_load_lds_dwordx4 v[150:151], off
	v_mfma_f32_32x32x16_bf16 v[16:31], v[134:137], v[142:145], v[16:31]
	v_mfma_f32_32x32x16_bf16 v[0:15], v[134:137], v[130:133], v[0:15]
	ds_read_b128 v[234:237], v234 offset:6144
	s_waitcnt lgkmcnt(3)
	v_mfma_f32_32x32x16_bf16 v[112:127], v[210:213], v[202:205], v[112:127]
	v_add_u32_e32 v130, v223, v178
	v_add_u32_e32 v134, v233, v178
	ds_read_b128 v[142:145], v130 offset:16384
	s_add_i32 s14, s13, 0x6000
	s_addk_i32 s13, 0x4000
	s_mov_b32 m0, s13
	v_mfma_f32_32x32x16_bf16 v[96:111], v[210:213], v[206:209], v[96:111]
	ds_read_b128 v[130:133], v130 offset:18432
	global_load_lds_dwordx4 v[172:173], off
	s_waitcnt lgkmcnt(4)
	v_mfma_f32_32x32x16_bf16 v[80:95], v[214:217], v[202:205], v[80:95]
	ds_read_b128 v[150:153], v134
	v_mfma_f32_32x32x16_bf16 v[64:79], v[214:217], v[206:209], v[64:79]
	ds_read_b128 v[146:149], v134 offset:2048
	s_waitcnt lgkmcnt(5)
	v_mfma_f32_32x32x16_bf16 v[48:63], v[224:227], v[202:205], v[48:63]
	ds_read_b128 v[138:141], v134 offset:4096
	v_lshl_add_u64 v[222:223], v[172:173], 0, s[34:35]
	s_mov_b32 m0, s14
	v_mfma_f32_32x32x16_bf16 v[32:47], v[224:227], v[206:209], v[32:47]
	ds_read_b128 v[134:137], v134 offset:6144
	global_load_lds_dwordx4 v[222:223], off
	s_waitcnt lgkmcnt(6)
	v_mfma_f32_32x32x16_bf16 v[16:31], v[234:237], v[202:205], v[16:31]
	s_add_i32 s12, s12, 0x8000
	v_lshl_add_u64 v[170:171], v[170:171], 0, 64
	v_lshl_add_u64 v[172:173], v[172:173], 0, 64
	s_cmp_eq_u32 s12, 0x100000
	v_mfma_f32_32x32x16_bf16 v[0:15], v[234:237], v[206:209], v[0:15]
	s_cbranch_scc0 .LBB0_147
	s_waitcnt vmcnt(8) lgkmcnt(0)
	s_barrier
	v_add_u32_e32 v202, v179, v177
	v_add_u32_e32 v222, v176, v177
	ds_read_b128 v[170:173], v202 offset:49152
	ds_read_b128 v[202:205], v202 offset:51200
	ds_read_b128 v[206:209], v222 offset:32768
	ds_read_b128 v[210:213], v222 offset:34816
	ds_read_b128 v[214:217], v222 offset:36864
	ds_read_b128 v[224:227], v222 offset:38912
	s_waitcnt lgkmcnt(9)
	v_mfma_f32_32x32x16_bf16 v[112:127], v[150:153], v[142:145], v[112:127]
	v_mfma_f32_32x32x16_bf16 v[96:111], v[150:153], v[130:133], v[96:111]
	s_waitcnt lgkmcnt(8)
	v_mfma_f32_32x32x16_bf16 v[80:95], v[146:149], v[142:145], v[80:95]
	v_mfma_f32_32x32x16_bf16 v[64:79], v[146:149], v[130:133], v[64:79]
	s_waitcnt lgkmcnt(7)
	v_mfma_f32_32x32x16_bf16 v[48:63], v[138:141], v[142:145], v[48:63]
	v_mfma_f32_32x32x16_bf16 v[32:47], v[138:141], v[130:133], v[32:47]
	s_waitcnt lgkmcnt(6)
	v_mfma_f32_32x32x16_bf16 v[16:31], v[134:137], v[142:145], v[16:31]
	v_mfma_f32_32x32x16_bf16 v[0:15], v[134:137], v[130:133], v[0:15]
	v_add_u32_e32 v134, v179, v178
	v_add_u32_e32 v150, v176, v178
	ds_read_b128 v[130:133], v134 offset:49152
	ds_read_b128 v[134:137], v134 offset:51200
	ds_read_b128 v[138:141], v150 offset:32768
	ds_read_b128 v[142:145], v150 offset:34816
	ds_read_b128 v[146:149], v150 offset:36864
	ds_read_b128 v[150:153], v150 offset:38912
	s_waitcnt lgkmcnt(9)
	v_mfma_f32_32x32x16_bf16 v[112:127], v[206:209], v[170:173], v[112:127]
	v_mfma_f32_32x32x16_bf16 v[96:111], v[206:209], v[202:205], v[96:111]
	s_waitcnt lgkmcnt(8)
	v_mfma_f32_32x32x16_bf16 v[80:95], v[210:213], v[170:173], v[80:95]
	v_mfma_f32_32x32x16_bf16 v[64:79], v[210:213], v[202:205], v[64:79]
	s_waitcnt lgkmcnt(7)
	v_mfma_f32_32x32x16_bf16 v[48:63], v[214:217], v[170:173], v[48:63]
	v_mfma_f32_32x32x16_bf16 v[32:47], v[214:217], v[202:205], v[32:47]
	s_waitcnt lgkmcnt(6)
	v_mfma_f32_32x32x16_bf16 v[0:15], v[224:227], v[202:205], v[0:15]
	s_waitcnt vmcnt(4) lgkmcnt(0)
	s_barrier
	v_add_u32_e32 v202, v199, v177
	v_add_u32_e32 v222, v200, v177
	v_mfma_f32_32x32x16_bf16 v[16:31], v[224:227], v[170:173], v[16:31]
	ds_read_b128 v[170:173], v202 offset:16384
	ds_read_b128 v[202:205], v202 offset:18432
	ds_read_b128 v[206:209], v222
	ds_read_b128 v[210:213], v222 offset:2048
	ds_read_b128 v[214:217], v222 offset:4096
	ds_read_b128 v[224:227], v222 offset:6144
	s_waitcnt lgkmcnt(9)
	v_mfma_f32_32x32x16_bf16 v[112:127], v[138:141], v[130:133], v[112:127]
	v_mfma_f32_32x32x16_bf16 v[96:111], v[138:141], v[134:137], v[96:111]
	s_waitcnt lgkmcnt(8)
	v_mfma_f32_32x32x16_bf16 v[80:95], v[142:145], v[130:133], v[80:95]
	v_mfma_f32_32x32x16_bf16 v[64:79], v[142:145], v[134:137], v[64:79]
	s_waitcnt lgkmcnt(7)
	v_mfma_f32_32x32x16_bf16 v[48:63], v[146:149], v[130:133], v[48:63]
	v_mfma_f32_32x32x16_bf16 v[32:47], v[146:149], v[134:137], v[32:47]
	s_waitcnt lgkmcnt(6)
	v_mfma_f32_32x32x16_bf16 v[16:31], v[150:153], v[130:133], v[16:31]
	v_mfma_f32_32x32x16_bf16 v[0:15], v[150:153], v[134:137], v[0:15]
	v_add_u32_e32 v134, v199, v178
	v_add_u32_e32 v150, v200, v178
	ds_read_b128 v[130:133], v134 offset:16384
	ds_read_b128 v[134:137], v134 offset:18432
	ds_read_b128 v[138:141], v150
	ds_read_b128 v[142:145], v150 offset:2048
	ds_read_b128 v[146:149], v150 offset:4096
	ds_read_b128 v[150:153], v150 offset:6144
	s_waitcnt lgkmcnt(9)
	v_mfma_f32_32x32x16_bf16 v[112:127], v[206:209], v[170:173], v[112:127]
	v_mfma_f32_32x32x16_bf16 v[96:111], v[206:209], v[202:205], v[96:111]
	s_waitcnt lgkmcnt(8)
	v_mfma_f32_32x32x16_bf16 v[80:95], v[210:213], v[170:173], v[80:95]
	v_mfma_f32_32x32x16_bf16 v[64:79], v[210:213], v[202:205], v[64:79]
	s_waitcnt lgkmcnt(7)
	v_mfma_f32_32x32x16_bf16 v[48:63], v[214:217], v[170:173], v[48:63]
	v_mfma_f32_32x32x16_bf16 v[32:47], v[214:217], v[202:205], v[32:47]
	s_waitcnt lgkmcnt(6)
	v_mfma_f32_32x32x16_bf16 v[0:15], v[224:227], v[202:205], v[0:15]
	s_waitcnt vmcnt(0) lgkmcnt(0)
	s_barrier
	v_add_u32_e32 v202, v197, v177
	v_add_u32_e32 v222, v198, v177
	v_mfma_f32_32x32x16_bf16 v[16:31], v[224:227], v[170:173], v[16:31]
	ds_read_b128 v[170:173], v202 offset:16384
	ds_read_b128 v[202:205], v202 offset:18432
	ds_read_b128 v[206:209], v222
	ds_read_b128 v[210:213], v222 offset:2048
	ds_read_b128 v[214:217], v222 offset:4096
	ds_read_b128 v[224:227], v222 offset:6144
	s_waitcnt lgkmcnt(9)
	v_mfma_f32_32x32x16_bf16 v[112:127], v[138:141], v[130:133], v[112:127]
	v_mfma_f32_32x32x16_bf16 v[96:111], v[138:141], v[134:137], v[96:111]
	s_waitcnt lgkmcnt(8)
	v_mfma_f32_32x32x16_bf16 v[80:95], v[142:145], v[130:133], v[80:95]
	v_mfma_f32_32x32x16_bf16 v[64:79], v[142:145], v[134:137], v[64:79]
	s_waitcnt lgkmcnt(7)
	v_mfma_f32_32x32x16_bf16 v[48:63], v[146:149], v[130:133], v[48:63]
	v_mfma_f32_32x32x16_bf16 v[32:47], v[146:149], v[134:137], v[32:47]
	s_waitcnt lgkmcnt(6)
	v_mfma_f32_32x32x16_bf16 v[16:31], v[150:153], v[130:133], v[16:31]
	v_mfma_f32_32x32x16_bf16 v[0:15], v[150:153], v[134:137], v[0:15]
	v_add_u32_e32 v134, v197, v178
	v_add_u32_e32 v150, v198, v178
	ds_read_b128 v[130:133], v134 offset:16384
	ds_read_b128 v[134:137], v134 offset:18432
	ds_read_b128 v[138:141], v150
	ds_read_b128 v[142:145], v150 offset:2048
	ds_read_b128 v[146:149], v150 offset:4096
	ds_read_b128 v[150:153], v150 offset:6144
	s_waitcnt lgkmcnt(9)
	v_mfma_f32_32x32x16_bf16 v[112:127], v[206:209], v[170:173], v[112:127]
	v_mfma_f32_32x32x16_bf16 v[96:111], v[206:209], v[202:205], v[96:111]
	s_waitcnt lgkmcnt(8)
	v_mfma_f32_32x32x16_bf16 v[80:95], v[210:213], v[170:173], v[80:95]
	v_mfma_f32_32x32x16_bf16 v[64:79], v[210:213], v[202:205], v[64:79]
	s_waitcnt lgkmcnt(7)
	v_mfma_f32_32x32x16_bf16 v[48:63], v[214:217], v[170:173], v[48:63]
	v_mfma_f32_32x32x16_bf16 v[32:47], v[214:217], v[202:205], v[32:47]
	s_waitcnt lgkmcnt(6)
	v_mfma_f32_32x32x16_bf16 v[16:31], v[224:227], v[170:173], v[16:31]
	v_mfma_f32_32x32x16_bf16 v[0:15], v[224:227], v[202:205], v[0:15]
	s_waitcnt lgkmcnt(3)
	v_mfma_f32_32x32x16_bf16 v[96:111], v[138:141], v[134:137], v[96:111]
	v_mfma_f32_32x32x16_bf16 v[112:127], v[138:141], v[130:133], v[112:127]
	s_nop 10
	v_cvt_pk_bf16_f32 v96, v96, s0
	v_cvt_pk_bf16_f32 v98, v98, s0
	s_waitcnt lgkmcnt(2)
	v_mfma_f32_32x32x16_bf16 v[80:95], v[142:145], v[130:133], v[80:95]
	v_cvt_pk_bf16_f32 v112, v112, s0
	s_waitcnt lgkmcnt(1)
	v_mfma_f32_32x32x16_bf16 v[48:63], v[146:149], v[130:133], v[48:63]
	s_nop 8
	v_cvt_pk_bf16_f32 v80, v80, s0
	s_waitcnt lgkmcnt(0)
	v_mfma_f32_32x32x16_bf16 v[16:31], v[150:153], v[130:133], v[16:31]
	v_or_b32_e32 v130, s11, v174
	v_ashrrev_i32_e32 v131, 31, v130
	v_lshl_add_u64 v[130:131], v[130:131], 1, v[158:159]
	v_cvt_pk_bf16_f32 v48, v48, s0
	v_mfma_f32_32x32x16_bf16 v[64:79], v[142:145], v[134:137], v[64:79]
	s_nop 6
	v_cvt_pk_bf16_f32 v16, v16, s0
	v_mfma_f32_32x32x16_bf16 v[32:47], v[146:149], v[134:137], v[32:47]
	s_nop 2
	v_cvt_pk_bf16_f32 v64, v64, s0
	v_cvt_pk_bf16_f32 v66, v66, s0
	v_mfma_f32_32x32x16_bf16 v[0:15], v[150:153], v[134:137], v[0:15]
	v_add_u32_e32 v134, s7, v128
	v_or_b32_e32 v132, v134, v181
	s_movk_i32 s7, 0x1800
	v_mad_i64_i32 v[132:133], s[12:13], v132, s7, v[130:131]
	global_store_short v[132:133], v96, off offset:64
	v_or_b32_e32 v96, v134, v182
	global_store_short v[132:133], v112, off
	v_mad_i64_i32 v[132:133], s[12:13], v96, s7, v[130:131]
	v_cvt_pk_bf16_f32 v96, v113, s0
	global_store_short v[132:133], v96, off
	v_cvt_pk_bf16_f32 v96, v97, s0
	global_store_short v[132:133], v96, off offset:64
	v_or_b32_e32 v96, v134, v183
	v_mad_i64_i32 v[96:97], s[12:13], v96, s7, v[130:131]
	v_cvt_pk_bf16_f32 v112, v114, s0
	global_store_short v[96:97], v112, off
	global_store_short v[96:97], v98, off offset:64
	v_or_b32_e32 v96, v134, v184
	v_mad_i64_i32 v[96:97], s[12:13], v96, s7, v[130:131]
	v_cvt_pk_bf16_f32 v98, v115, s0
	global_store_short v[96:97], v98, off
	v_cvt_pk_bf16_f32 v98, v99, s0
	global_store_short v[96:97], v98, off offset:64
	v_or_b32_e32 v96, v134, v185
	v_mad_i64_i32 v[96:97], s[12:13], v96, s7, v[130:131]
	v_cvt_pk_bf16_f32 v98, v116, s0
	global_store_short v[96:97], v98, off
	v_cvt_pk_bf16_f32 v98, v100, s0
	global_store_short v[96:97], v98, off offset:64
	v_or_b32_e32 v96, v134, v186
	v_mad_i64_i32 v[96:97], s[12:13], v96, s7, v[130:131]
	v_cvt_pk_bf16_f32 v98, v117, s0
	global_store_short v[96:97], v98, off
	v_cvt_pk_bf16_f32 v98, v101, s0
	global_store_short v[96:97], v98, off offset:64
	v_or_b32_e32 v96, v134, v187
	v_mad_i64_i32 v[96:97], s[12:13], v96, s7, v[130:131]
	v_cvt_pk_bf16_f32 v98, v118, s0
	global_store_short v[96:97], v98, off
	v_cvt_pk_bf16_f32 v98, v102, s0
	global_store_short v[96:97], v98, off offset:64
	v_or_b32_e32 v96, v134, v188
	v_mad_i64_i32 v[96:97], s[12:13], v96, s7, v[130:131]
	v_cvt_pk_bf16_f32 v98, v119, s0
	global_store_short v[96:97], v98, off
	v_cvt_pk_bf16_f32 v98, v103, s0
	global_store_short v[96:97], v98, off offset:64
	v_or_b32_e32 v96, v134, v189
	v_mad_i64_i32 v[96:97], s[12:13], v96, s7, v[130:131]
	v_cvt_pk_bf16_f32 v98, v120, s0
	global_store_short v[96:97], v98, off
	v_cvt_pk_bf16_f32 v98, v104, s0
	global_store_short v[96:97], v98, off offset:64
	v_or_b32_e32 v96, v134, v190
	v_mad_i64_i32 v[96:97], s[12:13], v96, s7, v[130:131]
	v_cvt_pk_bf16_f32 v98, v121, s0
	global_store_short v[96:97], v98, off
	v_cvt_pk_bf16_f32 v98, v105, s0
	global_store_short v[96:97], v98, off offset:64
	v_or_b32_e32 v96, v134, v191
	v_mad_i64_i32 v[96:97], s[12:13], v96, s7, v[130:131]
	v_cvt_pk_bf16_f32 v98, v122, s0
	global_store_short v[96:97], v98, off
	v_cvt_pk_bf16_f32 v98, v106, s0
	global_store_short v[96:97], v98, off offset:64
	v_or_b32_e32 v96, v134, v192
	v_mad_i64_i32 v[96:97], s[12:13], v96, s7, v[130:131]
	v_cvt_pk_bf16_f32 v98, v123, s0
	global_store_short v[96:97], v98, off
	v_cvt_pk_bf16_f32 v98, v107, s0
	global_store_short v[96:97], v98, off offset:64
	v_or_b32_e32 v96, v134, v193
	v_mad_i64_i32 v[96:97], s[12:13], v96, s7, v[130:131]
	v_cvt_pk_bf16_f32 v98, v124, s0
	global_store_short v[96:97], v98, off
	v_cvt_pk_bf16_f32 v98, v108, s0
	global_store_short v[96:97], v98, off offset:64
	v_or_b32_e32 v96, v134, v194
	v_mad_i64_i32 v[96:97], s[12:13], v96, s7, v[130:131]
	v_cvt_pk_bf16_f32 v98, v125, s0
	global_store_short v[96:97], v98, off
	v_cvt_pk_bf16_f32 v98, v109, s0
	global_store_short v[96:97], v98, off offset:64
	v_or_b32_e32 v96, v134, v195
	v_mad_i64_i32 v[96:97], s[12:13], v96, s7, v[130:131]
	v_cvt_pk_bf16_f32 v98, v126, s0
	global_store_short v[96:97], v98, off
	v_cvt_pk_bf16_f32 v98, v110, s0
	global_store_short v[96:97], v98, off offset:64
	v_or_b32_e32 v96, v134, v196
	v_mad_i64_i32 v[96:97], s[12:13], v96, s7, v[130:131]
	v_cvt_pk_bf16_f32 v98, v127, s0
	global_store_short v[96:97], v98, off
	v_cvt_pk_bf16_f32 v98, v111, s0
	global_store_short v[96:97], v98, off offset:64
	v_or_b32_e32 v98, 32, v134
	v_or_b32_e32 v96, v98, v181
	v_mad_i64_i32 v[96:97], s[12:13], v96, s7, v[130:131]
	global_store_short v[96:97], v64, off offset:64
	v_or_b32_e32 v64, v98, v182
	global_store_short v[96:97], v80, off
	v_mad_i64_i32 v[96:97], s[12:13], v64, s7, v[130:131]
	v_cvt_pk_bf16_f32 v64, v81, s0
	global_store_short v[96:97], v64, off
	v_cvt_pk_bf16_f32 v64, v65, s0
	global_store_short v[96:97], v64, off offset:64
	v_or_b32_e32 v64, v98, v183
	v_mad_i64_i32 v[64:65], s[12:13], v64, s7, v[130:131]
	v_cvt_pk_bf16_f32 v80, v82, s0
	global_store_short v[64:65], v80, off
	global_store_short v[64:65], v66, off offset:64
	v_or_b32_e32 v64, v98, v184
	v_mad_i64_i32 v[64:65], s[12:13], v64, s7, v[130:131]
	v_cvt_pk_bf16_f32 v66, v83, s0
	global_store_short v[64:65], v66, off
	v_cvt_pk_bf16_f32 v66, v67, s0
	global_store_short v[64:65], v66, off offset:64
	v_or_b32_e32 v64, v98, v185
	v_mad_i64_i32 v[64:65], s[12:13], v64, s7, v[130:131]
	v_cvt_pk_bf16_f32 v66, v84, s0
	global_store_short v[64:65], v66, off
	v_cvt_pk_bf16_f32 v66, v68, s0
	global_store_short v[64:65], v66, off offset:64
	v_or_b32_e32 v64, v98, v186
	v_mad_i64_i32 v[64:65], s[12:13], v64, s7, v[130:131]
	v_cvt_pk_bf16_f32 v66, v85, s0
	global_store_short v[64:65], v66, off
	v_cvt_pk_bf16_f32 v66, v69, s0
	global_store_short v[64:65], v66, off offset:64
	v_or_b32_e32 v64, v98, v187
	v_mad_i64_i32 v[64:65], s[12:13], v64, s7, v[130:131]
	v_cvt_pk_bf16_f32 v66, v86, s0
	global_store_short v[64:65], v66, off
	v_cvt_pk_bf16_f32 v66, v70, s0
	global_store_short v[64:65], v66, off offset:64
	v_or_b32_e32 v64, v98, v188
	v_mad_i64_i32 v[64:65], s[12:13], v64, s7, v[130:131]
	v_cvt_pk_bf16_f32 v66, v87, s0
	global_store_short v[64:65], v66, off
	v_cvt_pk_bf16_f32 v66, v71, s0
	global_store_short v[64:65], v66, off offset:64
	v_or_b32_e32 v64, v98, v189
	v_mad_i64_i32 v[64:65], s[12:13], v64, s7, v[130:131]
	v_cvt_pk_bf16_f32 v66, v88, s0
	global_store_short v[64:65], v66, off
	v_cvt_pk_bf16_f32 v66, v72, s0
	global_store_short v[64:65], v66, off offset:64
	v_or_b32_e32 v64, v98, v190
	v_mad_i64_i32 v[64:65], s[12:13], v64, s7, v[130:131]
	v_cvt_pk_bf16_f32 v66, v89, s0
	global_store_short v[64:65], v66, off
	v_cvt_pk_bf16_f32 v66, v73, s0
	global_store_short v[64:65], v66, off offset:64
	v_or_b32_e32 v64, v98, v191
	v_mad_i64_i32 v[64:65], s[12:13], v64, s7, v[130:131]
	v_cvt_pk_bf16_f32 v66, v90, s0
	global_store_short v[64:65], v66, off
	v_cvt_pk_bf16_f32 v66, v74, s0
	global_store_short v[64:65], v66, off offset:64
	v_or_b32_e32 v64, v98, v192
	v_mad_i64_i32 v[64:65], s[12:13], v64, s7, v[130:131]
	v_cvt_pk_bf16_f32 v66, v91, s0
	global_store_short v[64:65], v66, off
	v_cvt_pk_bf16_f32 v66, v75, s0
	global_store_short v[64:65], v66, off offset:64
	v_or_b32_e32 v64, v98, v193
	v_mad_i64_i32 v[64:65], s[12:13], v64, s7, v[130:131]
	v_cvt_pk_bf16_f32 v66, v92, s0
	global_store_short v[64:65], v66, off
	v_cvt_pk_bf16_f32 v66, v76, s0
	global_store_short v[64:65], v66, off offset:64
	v_or_b32_e32 v64, v98, v194
	v_mad_i64_i32 v[64:65], s[12:13], v64, s7, v[130:131]
	v_cvt_pk_bf16_f32 v66, v93, s0
	global_store_short v[64:65], v66, off
	v_cvt_pk_bf16_f32 v66, v77, s0
	global_store_short v[64:65], v66, off offset:64
	v_or_b32_e32 v64, v98, v195
	v_mad_i64_i32 v[64:65], s[12:13], v64, s7, v[130:131]
	v_cvt_pk_bf16_f32 v66, v94, s0
	global_store_short v[64:65], v66, off
	v_cvt_pk_bf16_f32 v66, v78, s0
	global_store_short v[64:65], v66, off offset:64
	v_or_b32_e32 v64, v98, v196
	v_mad_i64_i32 v[64:65], s[12:13], v64, s7, v[130:131]
	v_cvt_pk_bf16_f32 v66, v95, s0
	global_store_short v[64:65], v66, off
	v_cvt_pk_bf16_f32 v66, v79, s0
	global_store_short v[64:65], v66, off offset:64
	v_or_b32_e32 v66, 64, v134
	v_or_b32_e32 v64, v66, v181
	v_mad_i64_i32 v[64:65], s[12:13], v64, s7, v[130:131]
	v_cvt_pk_bf16_f32 v32, v32, s0
	global_store_short v[64:65], v32, off offset:64
	v_or_b32_e32 v32, v66, v182
	global_store_short v[64:65], v48, off
	v_mad_i64_i32 v[64:65], s[12:13], v32, s7, v[130:131]
	v_cvt_pk_bf16_f32 v32, v49, s0
	global_store_short v[64:65], v32, off
	v_cvt_pk_bf16_f32 v32, v33, s0
	global_store_short v[64:65], v32, off offset:64
	v_or_b32_e32 v32, v66, v183
	v_mad_i64_i32 v[32:33], s[12:13], v32, s7, v[130:131]
	v_cvt_pk_bf16_f32 v48, v50, s0
	v_cvt_pk_bf16_f32 v34, v34, s0
	global_store_short v[32:33], v48, off
	global_store_short v[32:33], v34, off offset:64
	v_or_b32_e32 v32, v66, v184
	v_mad_i64_i32 v[32:33], s[12:13], v32, s7, v[130:131]
	v_cvt_pk_bf16_f32 v34, v51, s0
	global_store_short v[32:33], v34, off
	v_cvt_pk_bf16_f32 v34, v35, s0
	global_store_short v[32:33], v34, off offset:64
	v_or_b32_e32 v32, v66, v185
	v_mad_i64_i32 v[32:33], s[12:13], v32, s7, v[130:131]
	v_cvt_pk_bf16_f32 v34, v52, s0
	global_store_short v[32:33], v34, off
	v_cvt_pk_bf16_f32 v34, v36, s0
	global_store_short v[32:33], v34, off offset:64
	v_or_b32_e32 v32, v66, v186
	v_mad_i64_i32 v[32:33], s[12:13], v32, s7, v[130:131]
	v_cvt_pk_bf16_f32 v34, v53, s0
	global_store_short v[32:33], v34, off
	v_cvt_pk_bf16_f32 v34, v37, s0
	global_store_short v[32:33], v34, off offset:64
	v_or_b32_e32 v32, v66, v187
	v_mad_i64_i32 v[32:33], s[12:13], v32, s7, v[130:131]
	v_cvt_pk_bf16_f32 v34, v54, s0
	global_store_short v[32:33], v34, off
	v_cvt_pk_bf16_f32 v34, v38, s0
	global_store_short v[32:33], v34, off offset:64
	v_or_b32_e32 v32, v66, v188
	v_mad_i64_i32 v[32:33], s[12:13], v32, s7, v[130:131]
	v_cvt_pk_bf16_f32 v34, v55, s0
	global_store_short v[32:33], v34, off
	v_cvt_pk_bf16_f32 v34, v39, s0
	global_store_short v[32:33], v34, off offset:64
	v_or_b32_e32 v32, v66, v189
	v_mad_i64_i32 v[32:33], s[12:13], v32, s7, v[130:131]
	v_cvt_pk_bf16_f32 v34, v56, s0
	global_store_short v[32:33], v34, off
	v_cvt_pk_bf16_f32 v34, v40, s0
	global_store_short v[32:33], v34, off offset:64
	v_or_b32_e32 v32, v66, v190
	v_mad_i64_i32 v[32:33], s[12:13], v32, s7, v[130:131]
	v_cvt_pk_bf16_f32 v34, v57, s0
	global_store_short v[32:33], v34, off
	v_cvt_pk_bf16_f32 v34, v41, s0
	global_store_short v[32:33], v34, off offset:64
	v_or_b32_e32 v32, v66, v191
	v_mad_i64_i32 v[32:33], s[12:13], v32, s7, v[130:131]
	v_cvt_pk_bf16_f32 v34, v58, s0
	global_store_short v[32:33], v34, off
	v_cvt_pk_bf16_f32 v34, v42, s0
	global_store_short v[32:33], v34, off offset:64
	v_or_b32_e32 v32, v66, v192
	v_mad_i64_i32 v[32:33], s[12:13], v32, s7, v[130:131]
	v_cvt_pk_bf16_f32 v34, v59, s0
	global_store_short v[32:33], v34, off
	v_cvt_pk_bf16_f32 v34, v43, s0
	global_store_short v[32:33], v34, off offset:64
	v_or_b32_e32 v32, v66, v193
	v_mad_i64_i32 v[32:33], s[12:13], v32, s7, v[130:131]
	v_cvt_pk_bf16_f32 v34, v60, s0
	global_store_short v[32:33], v34, off
	v_cvt_pk_bf16_f32 v34, v44, s0
	global_store_short v[32:33], v34, off offset:64
	v_or_b32_e32 v32, v66, v194
	v_mad_i64_i32 v[32:33], s[12:13], v32, s7, v[130:131]
	v_cvt_pk_bf16_f32 v34, v61, s0
	global_store_short v[32:33], v34, off
	v_cvt_pk_bf16_f32 v34, v45, s0
	global_store_short v[32:33], v34, off offset:64
	v_or_b32_e32 v32, v66, v195
	v_mad_i64_i32 v[32:33], s[12:13], v32, s7, v[130:131]
	v_cvt_pk_bf16_f32 v34, v62, s0
	global_store_short v[32:33], v34, off
	v_cvt_pk_bf16_f32 v34, v46, s0
	global_store_short v[32:33], v34, off offset:64
	v_or_b32_e32 v32, v66, v196
	v_mad_i64_i32 v[32:33], s[12:13], v32, s7, v[130:131]
	v_cvt_pk_bf16_f32 v34, v63, s0
	global_store_short v[32:33], v34, off
	v_cvt_pk_bf16_f32 v34, v47, s0
	global_store_short v[32:33], v34, off offset:64
	v_or_b32_e32 v34, 0x60, v134
	v_or_b32_e32 v32, v34, v181
	v_mad_i64_i32 v[32:33], s[12:13], v32, s7, v[130:131]
	v_cvt_pk_bf16_f32 v0, v0, s0
	global_store_short v[32:33], v0, off offset:64
	v_or_b32_e32 v0, v34, v182
	global_store_short v[32:33], v16, off
	v_mad_i64_i32 v[32:33], s[12:13], v0, s7, v[130:131]
	v_cvt_pk_bf16_f32 v0, v17, s0
	global_store_short v[32:33], v0, off
	v_cvt_pk_bf16_f32 v0, v1, s0
	global_store_short v[32:33], v0, off offset:64
	v_or_b32_e32 v0, v34, v183
	v_mad_i64_i32 v[0:1], s[12:13], v0, s7, v[130:131]
	v_cvt_pk_bf16_f32 v16, v18, s0
	v_cvt_pk_bf16_f32 v2, v2, s0
	global_store_short v[0:1], v16, off
	global_store_short v[0:1], v2, off offset:64
	v_or_b32_e32 v0, v34, v184
	v_mad_i64_i32 v[0:1], s[12:13], v0, s7, v[130:131]
	v_cvt_pk_bf16_f32 v2, v19, s0
	global_store_short v[0:1], v2, off
	v_cvt_pk_bf16_f32 v2, v3, s0
	global_store_short v[0:1], v2, off offset:64
	v_or_b32_e32 v0, v34, v185
	v_mad_i64_i32 v[0:1], s[12:13], v0, s7, v[130:131]
	v_cvt_pk_bf16_f32 v2, v20, s0
	global_store_short v[0:1], v2, off
	v_cvt_pk_bf16_f32 v2, v4, s0
	global_store_short v[0:1], v2, off offset:64
	v_or_b32_e32 v0, v34, v186
	v_mad_i64_i32 v[0:1], s[12:13], v0, s7, v[130:131]
	v_cvt_pk_bf16_f32 v2, v21, s0
	global_store_short v[0:1], v2, off
	v_cvt_pk_bf16_f32 v2, v5, s0
	global_store_short v[0:1], v2, off offset:64
	v_or_b32_e32 v0, v34, v187
	v_mad_i64_i32 v[0:1], s[12:13], v0, s7, v[130:131]
	v_cvt_pk_bf16_f32 v2, v22, s0
	global_store_short v[0:1], v2, off
	v_cvt_pk_bf16_f32 v2, v6, s0
	global_store_short v[0:1], v2, off offset:64
	v_or_b32_e32 v0, v34, v188
	v_mad_i64_i32 v[0:1], s[12:13], v0, s7, v[130:131]
	v_cvt_pk_bf16_f32 v2, v23, s0
	global_store_short v[0:1], v2, off
	v_cvt_pk_bf16_f32 v2, v7, s0
	global_store_short v[0:1], v2, off offset:64
	v_or_b32_e32 v0, v34, v189
	v_mad_i64_i32 v[0:1], s[12:13], v0, s7, v[130:131]
	v_cvt_pk_bf16_f32 v2, v24, s0
	global_store_short v[0:1], v2, off
	v_cvt_pk_bf16_f32 v2, v8, s0
	global_store_short v[0:1], v2, off offset:64
	v_or_b32_e32 v0, v34, v190
	v_mad_i64_i32 v[0:1], s[12:13], v0, s7, v[130:131]
	v_cvt_pk_bf16_f32 v2, v25, s0
	global_store_short v[0:1], v2, off
	v_cvt_pk_bf16_f32 v2, v9, s0
	global_store_short v[0:1], v2, off offset:64
	v_or_b32_e32 v0, v34, v191
	v_mad_i64_i32 v[0:1], s[12:13], v0, s7, v[130:131]
	v_cvt_pk_bf16_f32 v2, v26, s0
	global_store_short v[0:1], v2, off
	v_cvt_pk_bf16_f32 v2, v10, s0
	global_store_short v[0:1], v2, off offset:64
	v_or_b32_e32 v0, v34, v192
	v_mad_i64_i32 v[0:1], s[12:13], v0, s7, v[130:131]
	v_cvt_pk_bf16_f32 v2, v27, s0
	global_store_short v[0:1], v2, off
	v_cvt_pk_bf16_f32 v2, v11, s0
	global_store_short v[0:1], v2, off offset:64
	v_or_b32_e32 v0, v34, v193
	v_mad_i64_i32 v[0:1], s[12:13], v0, s7, v[130:131]
	v_cvt_pk_bf16_f32 v2, v28, s0
	global_store_short v[0:1], v2, off
	v_cvt_pk_bf16_f32 v2, v12, s0
	global_store_short v[0:1], v2, off offset:64
	v_or_b32_e32 v0, v34, v194
	v_mad_i64_i32 v[0:1], s[12:13], v0, s7, v[130:131]
	v_cvt_pk_bf16_f32 v2, v29, s0
	global_store_short v[0:1], v2, off
	v_cvt_pk_bf16_f32 v2, v13, s0
	global_store_short v[0:1], v2, off offset:64
	v_or_b32_e32 v0, v34, v195
	v_mad_i64_i32 v[0:1], s[12:13], v0, s7, v[130:131]
	v_cvt_pk_bf16_f32 v2, v30, s0
	global_store_short v[0:1], v2, off
	v_cvt_pk_bf16_f32 v2, v14, s0
	global_store_short v[0:1], v2, off offset:64
	v_or_b32_e32 v0, v34, v196
	v_mad_i64_i32 v[0:1], s[12:13], v0, s7, v[130:131]
	v_readlane_b32 s7, v252, 7
	s_add_i32 s10, s10, s7
	s_add_i32 s4, s4, s7
	v_readlane_b32 s7, v252, 8
	v_cvt_pk_bf16_f32 v2, v31, s0
	s_add_i32 s6, s6, s7
	global_store_short v[0:1], v2, off
	v_cvt_pk_bf16_f32 v2, v15, s0
	s_cmpk_gt_i32 s10, 0x5f
	global_store_short v[0:1], v2, off offset:64
	s_cbranch_scc0 .LBB0_146

.LBB0_263:
	s_waitcnt lgkmcnt(0)
	s_nop 0
	v_mfma_f32_32x32x16_bf16 v[112:127], v[150:153], v[142:145], v[112:127]
	v_mfma_f32_32x32x16_bf16 v[96:111], v[150:153], v[130:133], v[96:111]
	s_and_b32 s11, s10, 0x18000
	v_add_u32_e32 v222, s11, v180
	s_add_i32 s11, s10, 0xfffe8000
	s_and_b32 s11, s11, 0x18000
	v_or_b32_e32 v223, s11, v179
	v_add_u32_e32 v233, s11, v176
	s_waitcnt vmcnt(8)
	s_barrier
	v_add_u32_e32 v206, v223, v177
	v_add_u32_e32 v234, v233, v177
	ds_read_b128 v[202:205], v206 offset:16384
	ds_read_b128 v[206:209], v206 offset:18432
	ds_read_b128 v[210:213], v234
	v_mfma_f32_32x32x16_bf16 v[80:95], v[146:149], v[142:145], v[80:95]
	v_readfirstlane_b32 s11, v222
	s_mov_b32 m0, s11
	v_mfma_f32_32x32x16_bf16 v[64:79], v[146:149], v[130:133], v[64:79]
	ds_read_b128 v[214:217], v234 offset:2048
	global_load_lds_dwordx4 v[170:171], off
	v_mfma_f32_32x32x16_bf16 v[48:63], v[138:141], v[142:145], v[48:63]
	s_add_i32 s12, s11, 0x2000
	v_lshl_add_u64 v[150:151], v[170:171], 0, s[34:35]
	s_mov_b32 m0, s12
	v_mfma_f32_32x32x16_bf16 v[32:47], v[138:141], v[130:133], v[32:47]
	ds_read_b128 v[224:227], v234 offset:4096
	global_load_lds_dwordx4 v[150:151], off
	v_mfma_f32_32x32x16_bf16 v[16:31], v[134:137], v[142:145], v[16:31]
	v_mfma_f32_32x32x16_bf16 v[0:15], v[134:137], v[130:133], v[0:15]
	ds_read_b128 v[234:237], v234 offset:6144
	s_waitcnt lgkmcnt(3)
	v_mfma_f32_32x32x16_bf16 v[112:127], v[210:213], v[202:205], v[112:127]
	v_add_u32_e32 v130, v223, v178
	v_add_u32_e32 v134, v233, v178
	ds_read_b128 v[142:145], v130 offset:16384
	s_add_i32 s12, s11, 0x6000
	s_addk_i32 s11, 0x4000
	s_mov_b32 m0, s11
	v_mfma_f32_32x32x16_bf16 v[96:111], v[210:213], v[206:209], v[96:111]
	ds_read_b128 v[130:133], v130 offset:18432
	global_load_lds_dwordx4 v[172:173], off
	s_waitcnt lgkmcnt(4)
	v_mfma_f32_32x32x16_bf16 v[80:95], v[214:217], v[202:205], v[80:95]
	ds_read_b128 v[150:153], v134
	v_mfma_f32_32x32x16_bf16 v[64:79], v[214:217], v[206:209], v[64:79]
	ds_read_b128 v[146:149], v134 offset:2048
	s_waitcnt lgkmcnt(5)
	v_mfma_f32_32x32x16_bf16 v[48:63], v[224:227], v[202:205], v[48:63]
	ds_read_b128 v[138:141], v134 offset:4096
	v_lshl_add_u64 v[222:223], v[172:173], 0, s[34:35]
	s_mov_b32 m0, s12
	v_mfma_f32_32x32x16_bf16 v[32:47], v[224:227], v[206:209], v[32:47]
	ds_read_b128 v[134:137], v134 offset:6144
	global_load_lds_dwordx4 v[222:223], off
	s_waitcnt lgkmcnt(6)
	v_mfma_f32_32x32x16_bf16 v[16:31], v[234:237], v[202:205], v[16:31]
	s_add_i32 s10, s10, 0x8000
	v_lshl_add_u64 v[170:171], v[170:171], 0, 64
	v_lshl_add_u64 v[172:173], v[172:173], 0, 64
	s_cmp_eq_u32 s10, 0x100000
	v_mfma_f32_32x32x16_bf16 v[0:15], v[234:237], v[206:209], v[0:15]
	s_cbranch_scc0 .LBB0_263
	s_waitcnt vmcnt(8) lgkmcnt(0)
	s_barrier
	v_add_u32_e32 v202, v179, v177
	v_add_u32_e32 v222, v176, v177
	ds_read_b128 v[170:173], v202 offset:49152
	ds_read_b128 v[202:205], v202 offset:51200
	ds_read_b128 v[206:209], v222 offset:32768
	ds_read_b128 v[210:213], v222 offset:34816
	ds_read_b128 v[214:217], v222 offset:36864
	ds_read_b128 v[224:227], v222 offset:38912
	s_waitcnt lgkmcnt(9)
	v_mfma_f32_32x32x16_bf16 v[112:127], v[150:153], v[142:145], v[112:127]
	v_mfma_f32_32x32x16_bf16 v[96:111], v[150:153], v[130:133], v[96:111]
	s_waitcnt lgkmcnt(8)
	v_mfma_f32_32x32x16_bf16 v[80:95], v[146:149], v[142:145], v[80:95]
	v_mfma_f32_32x32x16_bf16 v[64:79], v[146:149], v[130:133], v[64:79]
	s_waitcnt lgkmcnt(7)
	v_mfma_f32_32x32x16_bf16 v[48:63], v[138:141], v[142:145], v[48:63]
	v_mfma_f32_32x32x16_bf16 v[32:47], v[138:141], v[130:133], v[32:47]
	s_waitcnt lgkmcnt(6)
	v_mfma_f32_32x32x16_bf16 v[16:31], v[134:137], v[142:145], v[16:31]
	v_mfma_f32_32x32x16_bf16 v[0:15], v[134:137], v[130:133], v[0:15]
	v_add_u32_e32 v134, v179, v178
	v_add_u32_e32 v150, v176, v178
	ds_read_b128 v[130:133], v134 offset:49152
	ds_read_b128 v[134:137], v134 offset:51200
	ds_read_b128 v[138:141], v150 offset:32768
	ds_read_b128 v[142:145], v150 offset:34816
	ds_read_b128 v[146:149], v150 offset:36864
	ds_read_b128 v[150:153], v150 offset:38912
	s_waitcnt lgkmcnt(9)
	v_mfma_f32_32x32x16_bf16 v[112:127], v[206:209], v[170:173], v[112:127]
	v_mfma_f32_32x32x16_bf16 v[96:111], v[206:209], v[202:205], v[96:111]
	s_waitcnt lgkmcnt(8)
	v_mfma_f32_32x32x16_bf16 v[80:95], v[210:213], v[170:173], v[80:95]
	v_mfma_f32_32x32x16_bf16 v[64:79], v[210:213], v[202:205], v[64:79]
	s_waitcnt lgkmcnt(7)
	v_mfma_f32_32x32x16_bf16 v[48:63], v[214:217], v[170:173], v[48:63]
	v_mfma_f32_32x32x16_bf16 v[32:47], v[214:217], v[202:205], v[32:47]
	s_waitcnt lgkmcnt(6)
	v_mfma_f32_32x32x16_bf16 v[0:15], v[224:227], v[202:205], v[0:15]
	s_waitcnt vmcnt(4) lgkmcnt(0)
	s_barrier
	v_add_u32_e32 v202, v199, v177
	v_add_u32_e32 v222, v200, v177
	v_mfma_f32_32x32x16_bf16 v[16:31], v[224:227], v[170:173], v[16:31]
	ds_read_b128 v[170:173], v202 offset:16384
	ds_read_b128 v[202:205], v202 offset:18432
	ds_read_b128 v[206:209], v222
	ds_read_b128 v[210:213], v222 offset:2048
	ds_read_b128 v[214:217], v222 offset:4096
	ds_read_b128 v[224:227], v222 offset:6144
	s_waitcnt lgkmcnt(9)
	v_mfma_f32_32x32x16_bf16 v[112:127], v[138:141], v[130:133], v[112:127]
	v_mfma_f32_32x32x16_bf16 v[96:111], v[138:141], v[134:137], v[96:111]
	s_waitcnt lgkmcnt(8)
	v_mfma_f32_32x32x16_bf16 v[80:95], v[142:145], v[130:133], v[80:95]
	v_mfma_f32_32x32x16_bf16 v[64:79], v[142:145], v[134:137], v[64:79]
	s_waitcnt lgkmcnt(7)
	v_mfma_f32_32x32x16_bf16 v[48:63], v[146:149], v[130:133], v[48:63]
	v_mfma_f32_32x32x16_bf16 v[32:47], v[146:149], v[134:137], v[32:47]
	s_waitcnt lgkmcnt(6)
	v_mfma_f32_32x32x16_bf16 v[16:31], v[150:153], v[130:133], v[16:31]
	v_mfma_f32_32x32x16_bf16 v[0:15], v[150:153], v[134:137], v[0:15]
	v_add_u32_e32 v134, v199, v178
	v_add_u32_e32 v150, v200, v178
	ds_read_b128 v[130:133], v134 offset:16384
	ds_read_b128 v[134:137], v134 offset:18432
	ds_read_b128 v[138:141], v150
	ds_read_b128 v[142:145], v150 offset:2048
	ds_read_b128 v[146:149], v150 offset:4096
	ds_read_b128 v[150:153], v150 offset:6144
	s_waitcnt lgkmcnt(9)
	v_mfma_f32_32x32x16_bf16 v[112:127], v[206:209], v[170:173], v[112:127]
	v_mfma_f32_32x32x16_bf16 v[96:111], v[206:209], v[202:205], v[96:111]
	s_waitcnt lgkmcnt(8)
	v_mfma_f32_32x32x16_bf16 v[80:95], v[210:213], v[170:173], v[80:95]
	v_mfma_f32_32x32x16_bf16 v[64:79], v[210:213], v[202:205], v[64:79]
	s_waitcnt lgkmcnt(7)
	v_mfma_f32_32x32x16_bf16 v[48:63], v[214:217], v[170:173], v[48:63]
	v_mfma_f32_32x32x16_bf16 v[32:47], v[214:217], v[202:205], v[32:47]
	s_waitcnt lgkmcnt(6)
	v_mfma_f32_32x32x16_bf16 v[0:15], v[224:227], v[202:205], v[0:15]
	s_waitcnt vmcnt(0) lgkmcnt(0)
	s_barrier
	v_add_u32_e32 v202, v197, v177
	v_add_u32_e32 v222, v198, v177
	v_mfma_f32_32x32x16_bf16 v[16:31], v[224:227], v[170:173], v[16:31]
	ds_read_b128 v[170:173], v202 offset:16384
	ds_read_b128 v[202:205], v202 offset:18432
	ds_read_b128 v[206:209], v222
	ds_read_b128 v[210:213], v222 offset:2048
	ds_read_b128 v[214:217], v222 offset:4096
	ds_read_b128 v[224:227], v222 offset:6144
	s_waitcnt lgkmcnt(9)
	v_mfma_f32_32x32x16_bf16 v[112:127], v[138:141], v[130:133], v[112:127]
	v_mfma_f32_32x32x16_bf16 v[96:111], v[138:141], v[134:137], v[96:111]
	s_waitcnt lgkmcnt(8)
	v_mfma_f32_32x32x16_bf16 v[80:95], v[142:145], v[130:133], v[80:95]
	v_mfma_f32_32x32x16_bf16 v[64:79], v[142:145], v[134:137], v[64:79]
	s_waitcnt lgkmcnt(7)
	v_mfma_f32_32x32x16_bf16 v[48:63], v[146:149], v[130:133], v[48:63]
	v_mfma_f32_32x32x16_bf16 v[32:47], v[146:149], v[134:137], v[32:47]
	s_waitcnt lgkmcnt(6)
	v_mfma_f32_32x32x16_bf16 v[16:31], v[150:153], v[130:133], v[16:31]
	v_mfma_f32_32x32x16_bf16 v[0:15], v[150:153], v[134:137], v[0:15]
	v_add_u32_e32 v134, v197, v178
	v_add_u32_e32 v150, v198, v178
	ds_read_b128 v[130:133], v134 offset:16384
	ds_read_b128 v[134:137], v134 offset:18432
	ds_read_b128 v[138:141], v150
	ds_read_b128 v[142:145], v150 offset:2048
	ds_read_b128 v[146:149], v150 offset:4096
	ds_read_b128 v[150:153], v150 offset:6144
	s_waitcnt lgkmcnt(9)
	v_mfma_f32_32x32x16_bf16 v[112:127], v[206:209], v[170:173], v[112:127]
	v_mfma_f32_32x32x16_bf16 v[96:111], v[206:209], v[202:205], v[96:111]
	s_waitcnt lgkmcnt(8)
	v_mfma_f32_32x32x16_bf16 v[80:95], v[210:213], v[170:173], v[80:95]
	v_mfma_f32_32x32x16_bf16 v[64:79], v[210:213], v[202:205], v[64:79]
	s_waitcnt lgkmcnt(7)
	v_mfma_f32_32x32x16_bf16 v[48:63], v[214:217], v[170:173], v[48:63]
	v_mfma_f32_32x32x16_bf16 v[32:47], v[214:217], v[202:205], v[32:47]
	s_waitcnt lgkmcnt(6)
	v_mfma_f32_32x32x16_bf16 v[16:31], v[224:227], v[170:173], v[16:31]
	v_mfma_f32_32x32x16_bf16 v[0:15], v[224:227], v[202:205], v[0:15]
	s_waitcnt lgkmcnt(3)
	v_mfma_f32_32x32x16_bf16 v[112:127], v[138:141], v[130:133], v[112:127]
	v_mfma_f32_32x32x16_bf16 v[96:111], v[138:141], v[134:137], v[96:111]
	s_nop 10
	v_cvt_pk_bf16_f32 v112, v112, s0
	s_waitcnt lgkmcnt(2)
	v_mfma_f32_32x32x16_bf16 v[80:95], v[142:145], v[130:133], v[80:95]
	v_cvt_pk_bf16_f32 v96, v96, s0
	v_cvt_pk_bf16_f32 v98, v98, s0
	s_waitcnt lgkmcnt(1)
	v_mfma_f32_32x32x16_bf16 v[48:63], v[146:149], v[130:133], v[48:63]
	s_nop 7
	v_cvt_pk_bf16_f32 v80, v80, s0
	s_waitcnt lgkmcnt(0)
	v_mfma_f32_32x32x16_bf16 v[16:31], v[150:153], v[130:133], v[16:31]
	v_add_u32_e32 v132, s5, v128
	v_or_b32_e32 v130, s7, v174
	v_ashrrev_i32_e32 v131, 31, v130
	v_lshl_add_u64 v[130:131], v[130:131], 1, v[158:159]
	v_cvt_pk_bf16_f32 v48, v48, s0
	v_readlane_b32 s5, v252, 7
	s_add_i32 s6, s6, s5
	v_mfma_f32_32x32x16_bf16 v[64:79], v[142:145], v[134:137], v[64:79]
	s_nop 3
	v_cvt_pk_bf16_f32 v16, v16, s0
	s_add_i32 s2, s2, s5
	v_readlane_b32 s5, v252, 8
	s_add_i32 s4, s4, s5
	s_cmp_gt_i32 s6, 31
	s_nop 2
	v_cvt_pk_bf16_f32 v64, v64, s0
	v_mfma_f32_32x32x16_bf16 v[32:47], v[146:149], v[134:137], v[32:47]
	v_cvt_pk_bf16_f32 v66, v66, s0
	v_mfma_f32_32x32x16_bf16 v[0:15], v[150:153], v[134:137], v[0:15]
	v_or_b32_e32 v134, v132, v181
	v_ashrrev_i32_e32 v135, 31, v134
	v_lshlrev_b64 v[134:135], 11, v[134:135]
	v_lshl_add_u64 v[134:135], v[130:131], 0, v[134:135]
	global_store_short v[134:135], v112, off
	global_store_short v[134:135], v96, off offset:64
	v_or_b32_e32 v134, v132, v182
	v_ashrrev_i32_e32 v135, 31, v134
	v_lshlrev_b64 v[134:135], 11, v[134:135]
	v_lshl_add_u64 v[134:135], v[130:131], 0, v[134:135]
	v_cvt_pk_bf16_f32 v96, v113, s0
	global_store_short v[134:135], v96, off
	v_cvt_pk_bf16_f32 v96, v97, s0
	global_store_short v[134:135], v96, off offset:64
	v_or_b32_e32 v96, v132, v183
	v_ashrrev_i32_e32 v97, 31, v96
	v_lshlrev_b64 v[96:97], 11, v[96:97]
	v_lshl_add_u64 v[96:97], v[130:131], 0, v[96:97]
	v_cvt_pk_bf16_f32 v112, v114, s0
	global_store_short v[96:97], v112, off
	global_store_short v[96:97], v98, off offset:64
	v_or_b32_e32 v96, v132, v184
	v_ashrrev_i32_e32 v97, 31, v96
	v_lshlrev_b64 v[96:97], 11, v[96:97]
	v_lshl_add_u64 v[96:97], v[130:131], 0, v[96:97]
	v_cvt_pk_bf16_f32 v98, v115, s0
	global_store_short v[96:97], v98, off
	v_cvt_pk_bf16_f32 v98, v99, s0
	global_store_short v[96:97], v98, off offset:64
	v_or_b32_e32 v96, v132, v185
	v_ashrrev_i32_e32 v97, 31, v96
	v_lshlrev_b64 v[96:97], 11, v[96:97]
	v_lshl_add_u64 v[96:97], v[130:131], 0, v[96:97]
	v_cvt_pk_bf16_f32 v98, v116, s0
	global_store_short v[96:97], v98, off
	v_cvt_pk_bf16_f32 v98, v100, s0
	global_store_short v[96:97], v98, off offset:64
	v_or_b32_e32 v96, v132, v186
	v_ashrrev_i32_e32 v97, 31, v96
	v_lshlrev_b64 v[96:97], 11, v[96:97]
	v_lshl_add_u64 v[96:97], v[130:131], 0, v[96:97]
	v_cvt_pk_bf16_f32 v98, v117, s0
	global_store_short v[96:97], v98, off
	v_cvt_pk_bf16_f32 v98, v101, s0
	global_store_short v[96:97], v98, off offset:64
	v_or_b32_e32 v96, v132, v187
	v_ashrrev_i32_e32 v97, 31, v96
	v_lshlrev_b64 v[96:97], 11, v[96:97]
	v_lshl_add_u64 v[96:97], v[130:131], 0, v[96:97]
	v_cvt_pk_bf16_f32 v98, v118, s0
	global_store_short v[96:97], v98, off
	v_cvt_pk_bf16_f32 v98, v102, s0
	global_store_short v[96:97], v98, off offset:64
	v_or_b32_e32 v96, v132, v188
	v_ashrrev_i32_e32 v97, 31, v96
	v_lshlrev_b64 v[96:97], 11, v[96:97]
	v_lshl_add_u64 v[96:97], v[130:131], 0, v[96:97]
	v_cvt_pk_bf16_f32 v98, v119, s0
	global_store_short v[96:97], v98, off
	v_cvt_pk_bf16_f32 v98, v103, s0
	global_store_short v[96:97], v98, off offset:64
	v_or_b32_e32 v96, v132, v189
	v_ashrrev_i32_e32 v97, 31, v96
	v_lshlrev_b64 v[96:97], 11, v[96:97]
	v_lshl_add_u64 v[96:97], v[130:131], 0, v[96:97]
	v_cvt_pk_bf16_f32 v98, v120, s0
	global_store_short v[96:97], v98, off
	v_cvt_pk_bf16_f32 v98, v104, s0
	global_store_short v[96:97], v98, off offset:64
	v_or_b32_e32 v96, v132, v190
	v_ashrrev_i32_e32 v97, 31, v96
	v_lshlrev_b64 v[96:97], 11, v[96:97]
	v_lshl_add_u64 v[96:97], v[130:131], 0, v[96:97]
	v_cvt_pk_bf16_f32 v98, v121, s0
	global_store_short v[96:97], v98, off
	v_cvt_pk_bf16_f32 v98, v105, s0
	global_store_short v[96:97], v98, off offset:64
	v_or_b32_e32 v96, v132, v191
	v_ashrrev_i32_e32 v97, 31, v96
	v_lshlrev_b64 v[96:97], 11, v[96:97]
	v_lshl_add_u64 v[96:97], v[130:131], 0, v[96:97]
	v_cvt_pk_bf16_f32 v98, v122, s0
	global_store_short v[96:97], v98, off
	v_cvt_pk_bf16_f32 v98, v106, s0
	global_store_short v[96:97], v98, off offset:64
	v_or_b32_e32 v96, v132, v192
	v_ashrrev_i32_e32 v97, 31, v96
	v_lshlrev_b64 v[96:97], 11, v[96:97]
	v_lshl_add_u64 v[96:97], v[130:131], 0, v[96:97]
	v_cvt_pk_bf16_f32 v98, v123, s0
	global_store_short v[96:97], v98, off
	v_cvt_pk_bf16_f32 v98, v107, s0
	global_store_short v[96:97], v98, off offset:64
	v_or_b32_e32 v96, v132, v193
	v_ashrrev_i32_e32 v97, 31, v96
	v_lshlrev_b64 v[96:97], 11, v[96:97]
	v_lshl_add_u64 v[96:97], v[130:131], 0, v[96:97]
	v_cvt_pk_bf16_f32 v98, v124, s0
	global_store_short v[96:97], v98, off
	v_cvt_pk_bf16_f32 v98, v108, s0
	global_store_short v[96:97], v98, off offset:64
	v_or_b32_e32 v96, v132, v194
	v_ashrrev_i32_e32 v97, 31, v96
	v_lshlrev_b64 v[96:97], 11, v[96:97]
	v_lshl_add_u64 v[96:97], v[130:131], 0, v[96:97]
	v_cvt_pk_bf16_f32 v98, v125, s0
	global_store_short v[96:97], v98, off
	v_cvt_pk_bf16_f32 v98, v109, s0
	global_store_short v[96:97], v98, off offset:64
	v_or_b32_e32 v96, v132, v195
	v_ashrrev_i32_e32 v97, 31, v96
	v_lshlrev_b64 v[96:97], 11, v[96:97]
	v_lshl_add_u64 v[96:97], v[130:131], 0, v[96:97]
	v_cvt_pk_bf16_f32 v98, v126, s0
	global_store_short v[96:97], v98, off
	v_cvt_pk_bf16_f32 v98, v110, s0
	global_store_short v[96:97], v98, off offset:64
	v_or_b32_e32 v96, v132, v196
	v_ashrrev_i32_e32 v97, 31, v96
	v_lshlrev_b64 v[96:97], 11, v[96:97]
	v_lshl_add_u64 v[96:97], v[130:131], 0, v[96:97]
	v_cvt_pk_bf16_f32 v98, v127, s0
	global_store_short v[96:97], v98, off
	v_cvt_pk_bf16_f32 v98, v111, s0
	global_store_short v[96:97], v98, off offset:64
	v_or_b32_e32 v98, 32, v132
	v_or_b32_e32 v96, v98, v181
	v_ashrrev_i32_e32 v97, 31, v96
	v_lshlrev_b64 v[96:97], 11, v[96:97]
	v_lshl_add_u64 v[96:97], v[130:131], 0, v[96:97]
	global_store_short v[96:97], v80, off
	global_store_short v[96:97], v64, off offset:64
	v_or_b32_e32 v96, v98, v182
	v_ashrrev_i32_e32 v97, 31, v96
	v_lshlrev_b64 v[96:97], 11, v[96:97]
	v_lshl_add_u64 v[96:97], v[130:131], 0, v[96:97]
	v_cvt_pk_bf16_f32 v64, v81, s0
	global_store_short v[96:97], v64, off
	v_cvt_pk_bf16_f32 v64, v65, s0
	global_store_short v[96:97], v64, off offset:64
	v_or_b32_e32 v64, v98, v183
	v_ashrrev_i32_e32 v65, 31, v64
	v_lshlrev_b64 v[64:65], 11, v[64:65]
	v_lshl_add_u64 v[64:65], v[130:131], 0, v[64:65]
	v_cvt_pk_bf16_f32 v80, v82, s0
	global_store_short v[64:65], v80, off
	global_store_short v[64:65], v66, off offset:64
	v_or_b32_e32 v64, v98, v184
	v_ashrrev_i32_e32 v65, 31, v64
	v_lshlrev_b64 v[64:65], 11, v[64:65]
	v_lshl_add_u64 v[64:65], v[130:131], 0, v[64:65]
	v_cvt_pk_bf16_f32 v66, v83, s0
	global_store_short v[64:65], v66, off
	v_cvt_pk_bf16_f32 v66, v67, s0
	global_store_short v[64:65], v66, off offset:64
	v_or_b32_e32 v64, v98, v185
	v_ashrrev_i32_e32 v65, 31, v64
	v_lshlrev_b64 v[64:65], 11, v[64:65]
	v_lshl_add_u64 v[64:65], v[130:131], 0, v[64:65]
	v_cvt_pk_bf16_f32 v66, v84, s0
	global_store_short v[64:65], v66, off
	v_cvt_pk_bf16_f32 v66, v68, s0
	global_store_short v[64:65], v66, off offset:64
	v_or_b32_e32 v64, v98, v186
	v_ashrrev_i32_e32 v65, 31, v64
	v_lshlrev_b64 v[64:65], 11, v[64:65]
	v_lshl_add_u64 v[64:65], v[130:131], 0, v[64:65]
	v_cvt_pk_bf16_f32 v66, v85, s0
	global_store_short v[64:65], v66, off
	v_cvt_pk_bf16_f32 v66, v69, s0
	global_store_short v[64:65], v66, off offset:64
	v_or_b32_e32 v64, v98, v187
	v_ashrrev_i32_e32 v65, 31, v64
	v_lshlrev_b64 v[64:65], 11, v[64:65]
	v_lshl_add_u64 v[64:65], v[130:131], 0, v[64:65]
	v_cvt_pk_bf16_f32 v66, v86, s0
	global_store_short v[64:65], v66, off
	v_cvt_pk_bf16_f32 v66, v70, s0
	global_store_short v[64:65], v66, off offset:64
	v_or_b32_e32 v64, v98, v188
	v_ashrrev_i32_e32 v65, 31, v64
	v_lshlrev_b64 v[64:65], 11, v[64:65]
	v_lshl_add_u64 v[64:65], v[130:131], 0, v[64:65]
	v_cvt_pk_bf16_f32 v66, v87, s0
	global_store_short v[64:65], v66, off
	v_cvt_pk_bf16_f32 v66, v71, s0
	global_store_short v[64:65], v66, off offset:64
	v_or_b32_e32 v64, v98, v189
	v_ashrrev_i32_e32 v65, 31, v64
	v_lshlrev_b64 v[64:65], 11, v[64:65]
	v_lshl_add_u64 v[64:65], v[130:131], 0, v[64:65]
	v_cvt_pk_bf16_f32 v66, v88, s0
	global_store_short v[64:65], v66, off
	v_cvt_pk_bf16_f32 v66, v72, s0
	global_store_short v[64:65], v66, off offset:64
	v_or_b32_e32 v64, v98, v190
	v_ashrrev_i32_e32 v65, 31, v64
	v_lshlrev_b64 v[64:65], 11, v[64:65]
	v_lshl_add_u64 v[64:65], v[130:131], 0, v[64:65]
	v_cvt_pk_bf16_f32 v66, v89, s0
	global_store_short v[64:65], v66, off
	v_cvt_pk_bf16_f32 v66, v73, s0
	global_store_short v[64:65], v66, off offset:64
	v_or_b32_e32 v64, v98, v191
	v_ashrrev_i32_e32 v65, 31, v64
	v_lshlrev_b64 v[64:65], 11, v[64:65]
	v_lshl_add_u64 v[64:65], v[130:131], 0, v[64:65]
	v_cvt_pk_bf16_f32 v66, v90, s0
	global_store_short v[64:65], v66, off
	v_cvt_pk_bf16_f32 v66, v74, s0
	global_store_short v[64:65], v66, off offset:64
	v_or_b32_e32 v64, v98, v192
	v_ashrrev_i32_e32 v65, 31, v64
	v_lshlrev_b64 v[64:65], 11, v[64:65]
	v_lshl_add_u64 v[64:65], v[130:131], 0, v[64:65]
	v_cvt_pk_bf16_f32 v66, v91, s0
	global_store_short v[64:65], v66, off
	v_cvt_pk_bf16_f32 v66, v75, s0
	global_store_short v[64:65], v66, off offset:64
	v_or_b32_e32 v64, v98, v193
	v_ashrrev_i32_e32 v65, 31, v64
	v_lshlrev_b64 v[64:65], 11, v[64:65]
	v_lshl_add_u64 v[64:65], v[130:131], 0, v[64:65]
	v_cvt_pk_bf16_f32 v66, v92, s0
	global_store_short v[64:65], v66, off
	v_cvt_pk_bf16_f32 v66, v76, s0
	global_store_short v[64:65], v66, off offset:64
	v_or_b32_e32 v64, v98, v194
	v_ashrrev_i32_e32 v65, 31, v64
	v_lshlrev_b64 v[64:65], 11, v[64:65]
	v_lshl_add_u64 v[64:65], v[130:131], 0, v[64:65]
	v_cvt_pk_bf16_f32 v66, v93, s0
	global_store_short v[64:65], v66, off
	v_cvt_pk_bf16_f32 v66, v77, s0
	global_store_short v[64:65], v66, off offset:64
	v_or_b32_e32 v64, v98, v195
	v_ashrrev_i32_e32 v65, 31, v64
	v_lshlrev_b64 v[64:65], 11, v[64:65]
	v_lshl_add_u64 v[64:65], v[130:131], 0, v[64:65]
	v_cvt_pk_bf16_f32 v66, v94, s0
	global_store_short v[64:65], v66, off
	v_cvt_pk_bf16_f32 v66, v78, s0
	global_store_short v[64:65], v66, off offset:64
	v_or_b32_e32 v64, v98, v196
	v_ashrrev_i32_e32 v65, 31, v64
	v_lshlrev_b64 v[64:65], 11, v[64:65]
	v_lshl_add_u64 v[64:65], v[130:131], 0, v[64:65]
	v_cvt_pk_bf16_f32 v66, v95, s0
	global_store_short v[64:65], v66, off
	v_cvt_pk_bf16_f32 v66, v79, s0
	global_store_short v[64:65], v66, off offset:64
	v_or_b32_e32 v66, 64, v132
	v_or_b32_e32 v64, v66, v181
	v_ashrrev_i32_e32 v65, 31, v64
	v_lshlrev_b64 v[64:65], 11, v[64:65]
	v_lshl_add_u64 v[64:65], v[130:131], 0, v[64:65]
	v_cvt_pk_bf16_f32 v32, v32, s0
	global_store_short v[64:65], v48, off
	global_store_short v[64:65], v32, off offset:64
	v_or_b32_e32 v64, v66, v182
	v_ashrrev_i32_e32 v65, 31, v64
	v_lshlrev_b64 v[64:65], 11, v[64:65]
	v_lshl_add_u64 v[64:65], v[130:131], 0, v[64:65]
	v_cvt_pk_bf16_f32 v32, v49, s0
	global_store_short v[64:65], v32, off
	v_cvt_pk_bf16_f32 v32, v33, s0
	global_store_short v[64:65], v32, off offset:64
	v_or_b32_e32 v32, v66, v183
	v_ashrrev_i32_e32 v33, 31, v32
	v_lshlrev_b64 v[32:33], 11, v[32:33]
	v_lshl_add_u64 v[32:33], v[130:131], 0, v[32:33]
	v_cvt_pk_bf16_f32 v48, v50, s0
	v_cvt_pk_bf16_f32 v34, v34, s0
	global_store_short v[32:33], v48, off
	global_store_short v[32:33], v34, off offset:64
	v_or_b32_e32 v32, v66, v184
	v_ashrrev_i32_e32 v33, 31, v32
	v_lshlrev_b64 v[32:33], 11, v[32:33]
	v_lshl_add_u64 v[32:33], v[130:131], 0, v[32:33]
	v_cvt_pk_bf16_f32 v34, v51, s0
	global_store_short v[32:33], v34, off
	v_cvt_pk_bf16_f32 v34, v35, s0
	global_store_short v[32:33], v34, off offset:64
	v_or_b32_e32 v32, v66, v185
	v_ashrrev_i32_e32 v33, 31, v32
	v_lshlrev_b64 v[32:33], 11, v[32:33]
	v_lshl_add_u64 v[32:33], v[130:131], 0, v[32:33]
	v_cvt_pk_bf16_f32 v34, v52, s0
	global_store_short v[32:33], v34, off
	v_cvt_pk_bf16_f32 v34, v36, s0
	global_store_short v[32:33], v34, off offset:64
	v_or_b32_e32 v32, v66, v186
	v_ashrrev_i32_e32 v33, 31, v32
	v_lshlrev_b64 v[32:33], 11, v[32:33]
	v_lshl_add_u64 v[32:33], v[130:131], 0, v[32:33]
	v_cvt_pk_bf16_f32 v34, v53, s0
	global_store_short v[32:33], v34, off
	v_cvt_pk_bf16_f32 v34, v37, s0
	global_store_short v[32:33], v34, off offset:64
	v_or_b32_e32 v32, v66, v187
	v_ashrrev_i32_e32 v33, 31, v32
	v_lshlrev_b64 v[32:33], 11, v[32:33]
	v_lshl_add_u64 v[32:33], v[130:131], 0, v[32:33]
	v_cvt_pk_bf16_f32 v34, v54, s0
	global_store_short v[32:33], v34, off
	v_cvt_pk_bf16_f32 v34, v38, s0
	global_store_short v[32:33], v34, off offset:64
	v_or_b32_e32 v32, v66, v188
	v_ashrrev_i32_e32 v33, 31, v32
	v_lshlrev_b64 v[32:33], 11, v[32:33]
	v_lshl_add_u64 v[32:33], v[130:131], 0, v[32:33]
	v_cvt_pk_bf16_f32 v34, v55, s0
	global_store_short v[32:33], v34, off
	v_cvt_pk_bf16_f32 v34, v39, s0
	global_store_short v[32:33], v34, off offset:64
	v_or_b32_e32 v32, v66, v189
	v_ashrrev_i32_e32 v33, 31, v32
	v_lshlrev_b64 v[32:33], 11, v[32:33]
	v_lshl_add_u64 v[32:33], v[130:131], 0, v[32:33]
	v_cvt_pk_bf16_f32 v34, v56, s0
	global_store_short v[32:33], v34, off
	v_cvt_pk_bf16_f32 v34, v40, s0
	global_store_short v[32:33], v34, off offset:64
	v_or_b32_e32 v32, v66, v190
	v_ashrrev_i32_e32 v33, 31, v32
	v_lshlrev_b64 v[32:33], 11, v[32:33]
	v_lshl_add_u64 v[32:33], v[130:131], 0, v[32:33]
	v_cvt_pk_bf16_f32 v34, v57, s0
	global_store_short v[32:33], v34, off
	v_cvt_pk_bf16_f32 v34, v41, s0
	global_store_short v[32:33], v34, off offset:64
	v_or_b32_e32 v32, v66, v191
	v_ashrrev_i32_e32 v33, 31, v32
	v_lshlrev_b64 v[32:33], 11, v[32:33]
	v_lshl_add_u64 v[32:33], v[130:131], 0, v[32:33]
	v_cvt_pk_bf16_f32 v34, v58, s0
	global_store_short v[32:33], v34, off
	v_cvt_pk_bf16_f32 v34, v42, s0
	global_store_short v[32:33], v34, off offset:64
	v_or_b32_e32 v32, v66, v192
	v_ashrrev_i32_e32 v33, 31, v32
	v_lshlrev_b64 v[32:33], 11, v[32:33]
	v_lshl_add_u64 v[32:33], v[130:131], 0, v[32:33]
	v_cvt_pk_bf16_f32 v34, v59, s0
	global_store_short v[32:33], v34, off
	v_cvt_pk_bf16_f32 v34, v43, s0
	global_store_short v[32:33], v34, off offset:64
	v_or_b32_e32 v32, v66, v193
	v_ashrrev_i32_e32 v33, 31, v32
	v_lshlrev_b64 v[32:33], 11, v[32:33]
	v_lshl_add_u64 v[32:33], v[130:131], 0, v[32:33]
	v_cvt_pk_bf16_f32 v34, v60, s0
	global_store_short v[32:33], v34, off
	v_cvt_pk_bf16_f32 v34, v44, s0
	global_store_short v[32:33], v34, off offset:64
	v_or_b32_e32 v32, v66, v194
	v_ashrrev_i32_e32 v33, 31, v32
	v_lshlrev_b64 v[32:33], 11, v[32:33]
	v_lshl_add_u64 v[32:33], v[130:131], 0, v[32:33]
	v_cvt_pk_bf16_f32 v34, v61, s0
	global_store_short v[32:33], v34, off
	v_cvt_pk_bf16_f32 v34, v45, s0
	global_store_short v[32:33], v34, off offset:64
	v_or_b32_e32 v32, v66, v195
	v_ashrrev_i32_e32 v33, 31, v32
	v_lshlrev_b64 v[32:33], 11, v[32:33]
	v_lshl_add_u64 v[32:33], v[130:131], 0, v[32:33]
	v_cvt_pk_bf16_f32 v34, v62, s0
	global_store_short v[32:33], v34, off
	v_cvt_pk_bf16_f32 v34, v46, s0
	global_store_short v[32:33], v34, off offset:64
	v_or_b32_e32 v32, v66, v196
	v_ashrrev_i32_e32 v33, 31, v32
	v_lshlrev_b64 v[32:33], 11, v[32:33]
	v_lshl_add_u64 v[32:33], v[130:131], 0, v[32:33]
	v_cvt_pk_bf16_f32 v34, v63, s0
	global_store_short v[32:33], v34, off
	v_cvt_pk_bf16_f32 v34, v47, s0
	global_store_short v[32:33], v34, off offset:64
	v_or_b32_e32 v34, 0x60, v132
	v_or_b32_e32 v32, v34, v181
	v_ashrrev_i32_e32 v33, 31, v32
	v_lshlrev_b64 v[32:33], 11, v[32:33]
	v_lshl_add_u64 v[32:33], v[130:131], 0, v[32:33]
	v_cvt_pk_bf16_f32 v0, v0, s0
	global_store_short v[32:33], v16, off
	global_store_short v[32:33], v0, off offset:64
	v_or_b32_e32 v32, v34, v182
	v_ashrrev_i32_e32 v33, 31, v32
	v_lshlrev_b64 v[32:33], 11, v[32:33]
	v_lshl_add_u64 v[32:33], v[130:131], 0, v[32:33]
	v_cvt_pk_bf16_f32 v0, v17, s0
	global_store_short v[32:33], v0, off
	v_cvt_pk_bf16_f32 v0, v1, s0
	global_store_short v[32:33], v0, off offset:64
	v_or_b32_e32 v0, v34, v183
	v_ashrrev_i32_e32 v1, 31, v0
	v_lshlrev_b64 v[0:1], 11, v[0:1]
	v_lshl_add_u64 v[0:1], v[130:131], 0, v[0:1]
	v_cvt_pk_bf16_f32 v16, v18, s0
	v_cvt_pk_bf16_f32 v2, v2, s0
	global_store_short v[0:1], v16, off
	global_store_short v[0:1], v2, off offset:64
	v_or_b32_e32 v0, v34, v184
	v_ashrrev_i32_e32 v1, 31, v0
	v_lshlrev_b64 v[0:1], 11, v[0:1]
	v_lshl_add_u64 v[0:1], v[130:131], 0, v[0:1]
	v_cvt_pk_bf16_f32 v2, v19, s0
	global_store_short v[0:1], v2, off
	v_cvt_pk_bf16_f32 v2, v3, s0
	global_store_short v[0:1], v2, off offset:64
	v_or_b32_e32 v0, v34, v185
	v_ashrrev_i32_e32 v1, 31, v0
	v_lshlrev_b64 v[0:1], 11, v[0:1]
	v_lshl_add_u64 v[0:1], v[130:131], 0, v[0:1]
	v_cvt_pk_bf16_f32 v2, v20, s0
	global_store_short v[0:1], v2, off
	v_cvt_pk_bf16_f32 v2, v4, s0
	global_store_short v[0:1], v2, off offset:64
	v_or_b32_e32 v0, v34, v186
	v_ashrrev_i32_e32 v1, 31, v0
	v_lshlrev_b64 v[0:1], 11, v[0:1]
	v_lshl_add_u64 v[0:1], v[130:131], 0, v[0:1]
	v_cvt_pk_bf16_f32 v2, v21, s0
	global_store_short v[0:1], v2, off
	v_cvt_pk_bf16_f32 v2, v5, s0
	global_store_short v[0:1], v2, off offset:64
	v_or_b32_e32 v0, v34, v187
	v_ashrrev_i32_e32 v1, 31, v0
	v_lshlrev_b64 v[0:1], 11, v[0:1]
	v_lshl_add_u64 v[0:1], v[130:131], 0, v[0:1]
	v_cvt_pk_bf16_f32 v2, v22, s0
	global_store_short v[0:1], v2, off
	v_cvt_pk_bf16_f32 v2, v6, s0
	global_store_short v[0:1], v2, off offset:64
	v_or_b32_e32 v0, v34, v188
	v_ashrrev_i32_e32 v1, 31, v0
	v_lshlrev_b64 v[0:1], 11, v[0:1]
	v_lshl_add_u64 v[0:1], v[130:131], 0, v[0:1]
	v_cvt_pk_bf16_f32 v2, v23, s0
	global_store_short v[0:1], v2, off
	v_cvt_pk_bf16_f32 v2, v7, s0
	global_store_short v[0:1], v2, off offset:64
	v_or_b32_e32 v0, v34, v189
	v_ashrrev_i32_e32 v1, 31, v0
	v_lshlrev_b64 v[0:1], 11, v[0:1]
	v_lshl_add_u64 v[0:1], v[130:131], 0, v[0:1]
	v_cvt_pk_bf16_f32 v2, v24, s0
	global_store_short v[0:1], v2, off
	v_cvt_pk_bf16_f32 v2, v8, s0
	global_store_short v[0:1], v2, off offset:64
	v_or_b32_e32 v0, v34, v190
	v_ashrrev_i32_e32 v1, 31, v0
	v_lshlrev_b64 v[0:1], 11, v[0:1]
	v_lshl_add_u64 v[0:1], v[130:131], 0, v[0:1]
	v_cvt_pk_bf16_f32 v2, v25, s0
	global_store_short v[0:1], v2, off
	v_cvt_pk_bf16_f32 v2, v9, s0
	global_store_short v[0:1], v2, off offset:64
	v_or_b32_e32 v0, v34, v191
	v_ashrrev_i32_e32 v1, 31, v0
	v_lshlrev_b64 v[0:1], 11, v[0:1]
	v_lshl_add_u64 v[0:1], v[130:131], 0, v[0:1]
	v_cvt_pk_bf16_f32 v2, v26, s0
	global_store_short v[0:1], v2, off
	v_cvt_pk_bf16_f32 v2, v10, s0
	global_store_short v[0:1], v2, off offset:64
	v_or_b32_e32 v0, v34, v192
	v_ashrrev_i32_e32 v1, 31, v0
	v_lshlrev_b64 v[0:1], 11, v[0:1]
	v_lshl_add_u64 v[0:1], v[130:131], 0, v[0:1]
	v_cvt_pk_bf16_f32 v2, v27, s0
	global_store_short v[0:1], v2, off
	v_cvt_pk_bf16_f32 v2, v11, s0
	global_store_short v[0:1], v2, off offset:64
	v_or_b32_e32 v0, v34, v193
	v_ashrrev_i32_e32 v1, 31, v0
	v_lshlrev_b64 v[0:1], 11, v[0:1]
	v_lshl_add_u64 v[0:1], v[130:131], 0, v[0:1]
	v_cvt_pk_bf16_f32 v2, v28, s0
	global_store_short v[0:1], v2, off
	v_cvt_pk_bf16_f32 v2, v12, s0
	global_store_short v[0:1], v2, off offset:64
	v_or_b32_e32 v0, v34, v194
	v_ashrrev_i32_e32 v1, 31, v0
	v_lshlrev_b64 v[0:1], 11, v[0:1]
	v_lshl_add_u64 v[0:1], v[130:131], 0, v[0:1]
	v_cvt_pk_bf16_f32 v2, v29, s0
	global_store_short v[0:1], v2, off
	v_cvt_pk_bf16_f32 v2, v13, s0
	global_store_short v[0:1], v2, off offset:64
	v_or_b32_e32 v0, v34, v195
	v_ashrrev_i32_e32 v1, 31, v0
	v_lshlrev_b64 v[0:1], 11, v[0:1]
	v_lshl_add_u64 v[0:1], v[130:131], 0, v[0:1]
	v_cvt_pk_bf16_f32 v2, v30, s0
	global_store_short v[0:1], v2, off
	v_cvt_pk_bf16_f32 v2, v14, s0
	global_store_short v[0:1], v2, off offset:64
	v_or_b32_e32 v0, v34, v196
	v_ashrrev_i32_e32 v1, 31, v0
	v_lshlrev_b64 v[0:1], 11, v[0:1]
	v_lshl_add_u64 v[0:1], v[130:131], 0, v[0:1]
	v_cvt_pk_bf16_f32 v2, v31, s0
	global_store_short v[0:1], v2, off
	v_cvt_pk_bf16_f32 v2, v15, s0
	global_store_short v[0:1], v2, off offset:64
	s_cbranch_scc0 .LBB0_262

.LBB0_330:
	s_waitcnt lgkmcnt(0)
	s_nop 0
	v_mfma_f32_32x32x16_bf16 v[112:127], v[150:153], v[142:145], v[112:127]
	v_mfma_f32_32x32x16_bf16 v[96:111], v[150:153], v[130:133], v[96:111]
	s_and_b32 s3, s2, 0x18000
	v_add_u32_e32 v128, s3, v182
	s_add_i32 s3, s2, 0xfffe8000
	s_and_b32 s3, s3, 0x18000
	v_or_b32_e32 v214, s3, v181
	v_add_u32_e32 v215, s3, v178
	s_waitcnt vmcnt(8)
	s_barrier
	v_add_u32_e32 v194, v214, v179
	v_add_u32_e32 v210, v215, v179
	ds_read_b128 v[190:193], v194 offset:16384
	ds_read_b128 v[194:197], v194 offset:18432
	ds_read_b128 v[198:201], v210
	v_mfma_f32_32x32x16_bf16 v[80:95], v[146:149], v[142:145], v[80:95]
	v_readfirstlane_b32 s3, v128
	s_mov_b32 m0, s3
	v_mfma_f32_32x32x16_bf16 v[64:79], v[146:149], v[130:133], v[64:79]
	ds_read_b128 v[202:205], v210 offset:2048
	global_load_lds_dwordx4 v[172:173], off
	v_mfma_f32_32x32x16_bf16 v[48:63], v[138:141], v[142:145], v[48:63]
	s_add_i32 s24, s3, 0x2000
	v_lshl_add_u64 v[150:151], v[172:173], 0, s[26:27]
	s_mov_b32 m0, s24
	v_mfma_f32_32x32x16_bf16 v[32:47], v[138:141], v[130:133], v[32:47]
	ds_read_b128 v[206:209], v210 offset:4096
	global_load_lds_dwordx4 v[150:151], off
	v_mfma_f32_32x32x16_bf16 v[16:31], v[134:137], v[142:145], v[16:31]
	v_mfma_f32_32x32x16_bf16 v[0:15], v[134:137], v[130:133], v[0:15]
	ds_read_b128 v[210:213], v210 offset:6144
	s_waitcnt lgkmcnt(3)
	v_mfma_f32_32x32x16_bf16 v[112:127], v[198:201], v[190:193], v[112:127]
	v_add_u32_e32 v128, v214, v180
	ds_read_b128 v[142:145], v128 offset:16384
	s_add_i32 s24, s3, 0x6000
	s_addk_i32 s3, 0x4000
	s_mov_b32 m0, s3
	v_mfma_f32_32x32x16_bf16 v[96:111], v[198:201], v[194:197], v[96:111]
	ds_read_b128 v[130:133], v128 offset:18432
	global_load_lds_dwordx4 v[174:175], off
	s_waitcnt lgkmcnt(4)
	v_mfma_f32_32x32x16_bf16 v[80:95], v[202:205], v[190:193], v[80:95]
	v_add_u32_e32 v128, v215, v180
	ds_read_b128 v[150:153], v128
	v_mfma_f32_32x32x16_bf16 v[64:79], v[202:205], v[194:197], v[64:79]
	ds_read_b128 v[146:149], v128 offset:2048
	s_waitcnt lgkmcnt(5)
	v_mfma_f32_32x32x16_bf16 v[48:63], v[206:209], v[190:193], v[48:63]
	ds_read_b128 v[138:141], v128 offset:4096
	v_lshl_add_u64 v[214:215], v[174:175], 0, s[26:27]
	s_mov_b32 m0, s24
	v_mfma_f32_32x32x16_bf16 v[32:47], v[206:209], v[194:197], v[32:47]
	ds_read_b128 v[134:137], v128 offset:6144
	global_load_lds_dwordx4 v[214:215], off
	s_waitcnt lgkmcnt(6)
	v_mfma_f32_32x32x16_bf16 v[16:31], v[210:213], v[190:193], v[16:31]
	s_add_i32 s2, s2, 0x8000
	v_lshl_add_u64 v[172:173], v[172:173], 0, 64
	v_lshl_add_u64 v[174:175], v[174:175], 0, 64
	s_cmp_eq_u32 s2, 0x100000
	v_mfma_f32_32x32x16_bf16 v[0:15], v[210:213], v[194:197], v[0:15]
	s_cbranch_scc0 .LBB0_330
	s_waitcnt vmcnt(8) lgkmcnt(0)
	s_barrier
	v_add_u32_e32 v128, v181, v179
	ds_read_b128 v[172:175], v128 offset:49152
	ds_read_b128 v[190:193], v128 offset:51200
	v_add_u32_e32 v128, v178, v179
	ds_read_b128 v[194:197], v128 offset:32768
	ds_read_b128 v[198:201], v128 offset:34816
	ds_read_b128 v[202:205], v128 offset:36864
	ds_read_b128 v[206:209], v128 offset:38912
	s_waitcnt lgkmcnt(9)
	v_mfma_f32_32x32x16_bf16 v[112:127], v[150:153], v[142:145], v[112:127]
	v_mfma_f32_32x32x16_bf16 v[96:111], v[150:153], v[130:133], v[96:111]
	s_waitcnt lgkmcnt(8)
	v_mfma_f32_32x32x16_bf16 v[80:95], v[146:149], v[142:145], v[80:95]
	v_mfma_f32_32x32x16_bf16 v[64:79], v[146:149], v[130:133], v[64:79]
	s_waitcnt lgkmcnt(7)
	v_mfma_f32_32x32x16_bf16 v[48:63], v[138:141], v[142:145], v[48:63]
	v_mfma_f32_32x32x16_bf16 v[32:47], v[138:141], v[130:133], v[32:47]
	s_waitcnt lgkmcnt(6)
	v_mfma_f32_32x32x16_bf16 v[16:31], v[134:137], v[142:145], v[16:31]
	v_mfma_f32_32x32x16_bf16 v[0:15], v[134:137], v[130:133], v[0:15]
	v_add_u32_e32 v128, v181, v180
	ds_read_b128 v[130:133], v128 offset:49152
	ds_read_b128 v[134:137], v128 offset:51200
	v_add_u32_e32 v128, v178, v180
	ds_read_b128 v[138:141], v128 offset:32768
	ds_read_b128 v[142:145], v128 offset:34816
	ds_read_b128 v[146:149], v128 offset:36864
	ds_read_b128 v[150:153], v128 offset:38912
	s_waitcnt lgkmcnt(9)
	v_mfma_f32_32x32x16_bf16 v[112:127], v[194:197], v[172:175], v[112:127]
	v_mfma_f32_32x32x16_bf16 v[96:111], v[194:197], v[190:193], v[96:111]
	s_waitcnt lgkmcnt(8)
	v_mfma_f32_32x32x16_bf16 v[80:95], v[198:201], v[172:175], v[80:95]
	v_mfma_f32_32x32x16_bf16 v[64:79], v[198:201], v[190:193], v[64:79]
	s_waitcnt lgkmcnt(7)
	v_mfma_f32_32x32x16_bf16 v[48:63], v[202:205], v[172:175], v[48:63]
	v_mfma_f32_32x32x16_bf16 v[32:47], v[202:205], v[190:193], v[32:47]
	s_waitcnt vmcnt(4) lgkmcnt(0)
	s_barrier
	v_add_u32_e32 v128, v187, v179
	s_waitcnt lgkmcnt(6)
	v_mfma_f32_32x32x16_bf16 v[16:31], v[206:209], v[172:175], v[16:31]
	v_mfma_f32_32x32x16_bf16 v[0:15], v[206:209], v[190:193], v[0:15]
	ds_read_b128 v[172:175], v128 offset:16384
	ds_read_b128 v[190:193], v128 offset:18432
	v_add_u32_e32 v128, v188, v179
	ds_read_b128 v[194:197], v128
	ds_read_b128 v[198:201], v128 offset:2048
	ds_read_b128 v[202:205], v128 offset:4096
	ds_read_b128 v[206:209], v128 offset:6144
	s_waitcnt lgkmcnt(9)
	v_mfma_f32_32x32x16_bf16 v[112:127], v[138:141], v[130:133], v[112:127]
	v_mfma_f32_32x32x16_bf16 v[96:111], v[138:141], v[134:137], v[96:111]
	s_waitcnt lgkmcnt(8)
	v_mfma_f32_32x32x16_bf16 v[80:95], v[142:145], v[130:133], v[80:95]
	v_mfma_f32_32x32x16_bf16 v[64:79], v[142:145], v[134:137], v[64:79]
	s_waitcnt lgkmcnt(7)
	v_mfma_f32_32x32x16_bf16 v[48:63], v[146:149], v[130:133], v[48:63]
	v_mfma_f32_32x32x16_bf16 v[32:47], v[146:149], v[134:137], v[32:47]
	s_waitcnt lgkmcnt(6)
	v_mfma_f32_32x32x16_bf16 v[16:31], v[150:153], v[130:133], v[16:31]
	v_mfma_f32_32x32x16_bf16 v[0:15], v[150:153], v[134:137], v[0:15]
	v_add_u32_e32 v128, v187, v180
	ds_read_b128 v[130:133], v128 offset:16384
	ds_read_b128 v[134:137], v128 offset:18432
	v_add_u32_e32 v128, v188, v180
	ds_read_b128 v[138:141], v128
	ds_read_b128 v[142:145], v128 offset:2048
	ds_read_b128 v[146:149], v128 offset:4096
	ds_read_b128 v[150:153], v128 offset:6144
	s_waitcnt lgkmcnt(9)
	v_mfma_f32_32x32x16_bf16 v[112:127], v[194:197], v[172:175], v[112:127]
	v_mfma_f32_32x32x16_bf16 v[96:111], v[194:197], v[190:193], v[96:111]
	s_waitcnt lgkmcnt(8)
	v_mfma_f32_32x32x16_bf16 v[80:95], v[198:201], v[172:175], v[80:95]
	v_mfma_f32_32x32x16_bf16 v[64:79], v[198:201], v[190:193], v[64:79]
	s_waitcnt lgkmcnt(7)
	v_mfma_f32_32x32x16_bf16 v[48:63], v[202:205], v[172:175], v[48:63]
	v_mfma_f32_32x32x16_bf16 v[32:47], v[202:205], v[190:193], v[32:47]
	s_waitcnt vmcnt(0) lgkmcnt(0)
	s_barrier
	v_add_u32_e32 v128, v185, v179
	s_waitcnt lgkmcnt(6)
	v_mfma_f32_32x32x16_bf16 v[16:31], v[206:209], v[172:175], v[16:31]
	v_mfma_f32_32x32x16_bf16 v[0:15], v[206:209], v[190:193], v[0:15]
	ds_read_b128 v[172:175], v128 offset:16384
	ds_read_b128 v[190:193], v128 offset:18432
	v_add_u32_e32 v128, v186, v179
	ds_read_b128 v[194:197], v128
	ds_read_b128 v[198:201], v128 offset:2048
	ds_read_b128 v[202:205], v128 offset:4096
	ds_read_b128 v[206:209], v128 offset:6144
	s_waitcnt lgkmcnt(9)
	v_mfma_f32_32x32x16_bf16 v[112:127], v[138:141], v[130:133], v[112:127]
	v_mfma_f32_32x32x16_bf16 v[96:111], v[138:141], v[134:137], v[96:111]
	s_waitcnt lgkmcnt(8)
	v_mfma_f32_32x32x16_bf16 v[80:95], v[142:145], v[130:133], v[80:95]
	v_mfma_f32_32x32x16_bf16 v[64:79], v[142:145], v[134:137], v[64:79]
	s_waitcnt lgkmcnt(7)
	v_mfma_f32_32x32x16_bf16 v[48:63], v[146:149], v[130:133], v[48:63]
	v_mfma_f32_32x32x16_bf16 v[32:47], v[146:149], v[134:137], v[32:47]
	s_waitcnt lgkmcnt(6)
	v_mfma_f32_32x32x16_bf16 v[16:31], v[150:153], v[130:133], v[16:31]
	v_mfma_f32_32x32x16_bf16 v[0:15], v[150:153], v[134:137], v[0:15]
	v_add_u32_e32 v128, v185, v180
	ds_read_b128 v[130:133], v128 offset:16384
	ds_read_b128 v[138:141], v128 offset:18432
	v_add_u32_e32 v128, v186, v180
	ds_read_b128 v[134:137], v128
	ds_read_b128 v[142:145], v128 offset:2048
	ds_read_b128 v[146:149], v128 offset:4096
	ds_read_b128 v[210:213], v128 offset:6144
	s_waitcnt lgkmcnt(9)
	v_mfma_f32_32x32x16_bf16 v[112:127], v[194:197], v[172:175], v[112:127]
	v_mfma_f32_32x32x16_bf16 v[96:111], v[194:197], v[190:193], v[96:111]
	s_waitcnt lgkmcnt(8)
	v_mfma_f32_32x32x16_bf16 v[80:95], v[198:201], v[172:175], v[80:95]
	v_mfma_f32_32x32x16_bf16 v[64:79], v[198:201], v[190:193], v[64:79]
	s_waitcnt lgkmcnt(7)
	v_mfma_f32_32x32x16_bf16 v[48:63], v[202:205], v[172:175], v[48:63]
	v_mfma_f32_32x32x16_bf16 v[32:47], v[202:205], v[190:193], v[32:47]
	s_waitcnt lgkmcnt(6)
	v_mfma_f32_32x32x16_bf16 v[16:31], v[206:209], v[172:175], v[16:31]
	v_add_u32_e32 v150, s0, v157
	s_movk_i32 s2, 0x2000
	s_movk_i32 s0, 0x1fff
	v_cmp_gt_i32_e32 vcc, s2, v150
	s_movk_i32 s2, 0x7ff
	v_mfma_f32_32x32x16_bf16 v[0:15], v[206:209], v[190:193], v[0:15]
	s_waitcnt lgkmcnt(3)
	v_mfma_f32_32x32x16_bf16 v[112:127], v[134:137], v[130:133], v[112:127]
	v_mfma_f32_32x32x16_bf16 v[96:111], v[134:137], v[138:141], v[96:111]
	v_or_b32_e32 v136, s1, v176
	v_cmp_lt_i32_e64 s[0:1], s0, v150
	v_cmp_lt_i32_e64 s[2:3], s2, v136
	s_waitcnt lgkmcnt(2)
	v_mfma_f32_32x32x16_bf16 v[80:95], v[142:145], v[130:133], v[80:95]
	v_mfma_f32_32x32x16_bf16 v[64:79], v[142:145], v[138:141], v[64:79]
	s_waitcnt lgkmcnt(1)
	v_mfma_f32_32x32x16_bf16 v[48:63], v[146:149], v[130:133], v[48:63]
	v_mfma_f32_32x32x16_bf16 v[32:47], v[146:149], v[138:141], v[32:47]
	s_waitcnt lgkmcnt(0)
	v_mfma_f32_32x32x16_bf16 v[16:31], v[210:213], v[130:133], v[16:31]
	v_or_b32_e32 v130, v150, v183
	v_mfma_f32_32x32x16_bf16 v[0:15], v[210:213], v[138:141], v[0:15]
	s_and_saveexec_b64 s[24:25], s[2:3]
	s_xor_b64 s[2:3], exec, s[24:25]
	s_cbranch_execz .LBB0_461
	v_ashrrev_i32_e32 v134, 8, v150
	v_ashrrev_i32_e32 v135, 31, v134
	s_and_saveexec_b64 s[24:25], vcc
	s_xor_b64 s[24:25], exec, s[24:25]
	v_lshlrev_b64 v[140:141], 18, v[134:135]
	v_and_b32_e32 v128, 0x84, v130
	s_or_saveexec_b64 s[24:25], s[24:25]
	v_mov_b64_e32 v[138:139], 0x100
	s_xor_b64 exec, exec, s[24:25]
	v_add_u32_e32 v128, 0xffffe000, v150
	v_lshrrev_b32_e32 v128, 11, v128
	s_mov_b32 s26, 0x240000
	v_mad_u64_u32 v[140:141], s[26:27], v128, s26, v[166:167]
	v_and_b32_e32 v128, 0x784, v130
	v_add_u32_e32 v128, 0x100, v128
	v_mov_b64_e32 v[138:139], 0x900
	s_or_b64 exec, exec, s[24:25]
	v_add_u32_e32 v132, v136, v184
	v_or_b32_e32 v142, 1, v130
	v_or_b32_e32 v144, 2, v130
	v_or_b32_e32 v146, 3, v130
	v_lshl_add_u64 v[140:141], v[140:141], 1, s[6:7]
	v_mad_u64_u32 v[152:153], s[24:25], v138, v132, 0
	v_ashrrev_i32_e32 v131, 31, v130
	v_ashrrev_i32_e32 v143, 31, v142
	v_ashrrev_i32_e32 v145, 31, v144
	v_ashrrev_i32_e32 v147, 31, v146
	v_lshl_add_u64 v[152:153], v[152:153], 1, v[140:141]
	v_lshlrev_b64 v[136:137], 12, v[130:131]
	v_lshlrev_b64 v[142:143], 12, v[142:143]
	v_lshlrev_b64 v[144:145], 12, v[144:145]
	v_lshlrev_b64 v[146:147], 12, v[146:147]
	v_cvt_pk_bf16_f32 v148, v112, v113
	v_cvt_pk_bf16_f32 v149, v114, v115
	v_mov_b32_e32 v133, v129
	v_lshl_add_u64 v[152:153], v[128:129], 1, v[152:153]
	global_store_dwordx2 v[152:153], v[148:149], off
	v_lshl_add_u64 v[148:149], s[18:19], 0, v[136:137]
	v_lshlrev_b64 v[136:137], 2, v[132:133]
	v_lshl_add_u64 v[152:153], s[18:19], 0, v[142:143]
	v_lshl_add_u64 v[172:173], s[18:19], 0, v[144:145]
	v_lshl_add_u64 v[174:175], s[18:19], 0, v[146:147]
	v_lshl_add_u64 v[142:143], v[148:149], 0, v[136:137]
	v_lshl_add_u64 v[144:145], v[152:153], 0, v[136:137]
	v_lshl_add_u64 v[146:147], v[172:173], 0, v[136:137]
	v_lshl_add_u64 v[148:149], v[174:175], 0, v[136:137]
	s_and_saveexec_b64 s[24:25], vcc
	s_cbranch_execz .LBB0_338
	global_store_dword v[142:143], v112, off nt
	global_store_dword v[144:145], v113, off nt
	global_store_dword v[146:147], v114, off nt
	global_store_dword v[148:149], v115, off nt

.LBB0_1102:
	s_waitcnt lgkmcnt(0)
	s_nop 0
	v_mfma_f32_32x32x16_bf16 v[112:127], v[150:153], v[142:145], v[112:127]
	v_mfma_f32_32x32x16_bf16 v[96:111], v[150:153], v[130:133], v[96:111]
	s_and_b32 s7, s6, 0x18000
	v_add_u32_e32 v222, s7, v180
	s_add_i32 s7, s6, 0xfffe8000
	s_and_b32 s7, s7, 0x18000
	v_or_b32_e32 v223, s7, v179
	v_add_u32_e32 v233, s7, v176
	s_waitcnt vmcnt(8)
	s_barrier
	v_add_u32_e32 v206, v223, v177
	v_add_u32_e32 v234, v233, v177
	ds_read_b128 v[202:205], v206 offset:16384
	ds_read_b128 v[206:209], v206 offset:18432
	ds_read_b128 v[210:213], v234
	v_mfma_f32_32x32x16_bf16 v[80:95], v[146:149], v[142:145], v[80:95]
	v_readfirstlane_b32 s7, v222
	s_mov_b32 m0, s7
	v_mfma_f32_32x32x16_bf16 v[64:79], v[146:149], v[130:133], v[64:79]
	ds_read_b128 v[214:217], v234 offset:2048
	global_load_lds_dwordx4 v[170:171], off
	v_mfma_f32_32x32x16_bf16 v[48:63], v[138:141], v[142:145], v[48:63]
	s_add_i32 s10, s7, 0x2000
	v_lshl_add_u64 v[150:151], v[170:171], 0, s[34:35]
	s_mov_b32 m0, s10
	v_mfma_f32_32x32x16_bf16 v[32:47], v[138:141], v[130:133], v[32:47]
	ds_read_b128 v[224:227], v234 offset:4096
	global_load_lds_dwordx4 v[150:151], off
	v_mfma_f32_32x32x16_bf16 v[16:31], v[134:137], v[142:145], v[16:31]
	v_mfma_f32_32x32x16_bf16 v[0:15], v[134:137], v[130:133], v[0:15]
	ds_read_b128 v[234:237], v234 offset:6144
	s_waitcnt lgkmcnt(3)
	v_mfma_f32_32x32x16_bf16 v[112:127], v[210:213], v[202:205], v[112:127]
	v_add_u32_e32 v130, v223, v178
	v_add_u32_e32 v134, v233, v178
	ds_read_b128 v[142:145], v130 offset:16384
	s_add_i32 s10, s7, 0x6000
	s_addk_i32 s7, 0x4000
	s_mov_b32 m0, s7
	v_mfma_f32_32x32x16_bf16 v[96:111], v[210:213], v[206:209], v[96:111]
	ds_read_b128 v[130:133], v130 offset:18432
	global_load_lds_dwordx4 v[172:173], off
	s_waitcnt lgkmcnt(4)
	v_mfma_f32_32x32x16_bf16 v[80:95], v[214:217], v[202:205], v[80:95]
	ds_read_b128 v[150:153], v134
	v_mfma_f32_32x32x16_bf16 v[64:79], v[214:217], v[206:209], v[64:79]
	ds_read_b128 v[146:149], v134 offset:2048
	s_waitcnt lgkmcnt(5)
	v_mfma_f32_32x32x16_bf16 v[48:63], v[224:227], v[202:205], v[48:63]
	ds_read_b128 v[138:141], v134 offset:4096
	v_lshl_add_u64 v[222:223], v[172:173], 0, s[34:35]
	s_mov_b32 m0, s10
	v_mfma_f32_32x32x16_bf16 v[32:47], v[224:227], v[206:209], v[32:47]
	ds_read_b128 v[134:137], v134 offset:6144
	global_load_lds_dwordx4 v[222:223], off
	s_waitcnt lgkmcnt(6)
	v_mfma_f32_32x32x16_bf16 v[16:31], v[234:237], v[202:205], v[16:31]
	s_add_i32 s6, s6, 0x8000
	v_lshl_add_u64 v[170:171], v[170:171], 0, 64
	v_lshl_add_u64 v[172:173], v[172:173], 0, 64
	s_cmp_eq_u32 s6, 0x100000
	v_mfma_f32_32x32x16_bf16 v[0:15], v[234:237], v[206:209], v[0:15]
	s_cbranch_scc0 .LBB0_1102
	s_waitcnt vmcnt(8) lgkmcnt(0)
	s_barrier
	v_add_u32_e32 v202, v179, v177
	v_add_u32_e32 v222, v176, v177
	ds_read_b128 v[170:173], v202 offset:49152
	ds_read_b128 v[202:205], v202 offset:51200
	ds_read_b128 v[206:209], v222 offset:32768
	ds_read_b128 v[210:213], v222 offset:34816
	ds_read_b128 v[214:217], v222 offset:36864
	ds_read_b128 v[224:227], v222 offset:38912
	s_waitcnt lgkmcnt(9)
	v_mfma_f32_32x32x16_bf16 v[112:127], v[150:153], v[142:145], v[112:127]
	v_mfma_f32_32x32x16_bf16 v[96:111], v[150:153], v[130:133], v[96:111]
	s_waitcnt lgkmcnt(8)
	v_mfma_f32_32x32x16_bf16 v[80:95], v[146:149], v[142:145], v[80:95]
	v_mfma_f32_32x32x16_bf16 v[64:79], v[146:149], v[130:133], v[64:79]
	s_waitcnt lgkmcnt(7)
	v_mfma_f32_32x32x16_bf16 v[48:63], v[138:141], v[142:145], v[48:63]
	v_mfma_f32_32x32x16_bf16 v[32:47], v[138:141], v[130:133], v[32:47]
	s_waitcnt lgkmcnt(6)
	v_mfma_f32_32x32x16_bf16 v[16:31], v[134:137], v[142:145], v[16:31]
	v_mfma_f32_32x32x16_bf16 v[0:15], v[134:137], v[130:133], v[0:15]
	v_add_u32_e32 v134, v179, v178
	v_add_u32_e32 v150, v176, v178
	ds_read_b128 v[130:133], v134 offset:49152
	ds_read_b128 v[134:137], v134 offset:51200
	ds_read_b128 v[138:141], v150 offset:32768
	ds_read_b128 v[142:145], v150 offset:34816
	ds_read_b128 v[146:149], v150 offset:36864
	ds_read_b128 v[150:153], v150 offset:38912
	s_waitcnt lgkmcnt(9)
	v_mfma_f32_32x32x16_bf16 v[112:127], v[206:209], v[170:173], v[112:127]
	v_mfma_f32_32x32x16_bf16 v[96:111], v[206:209], v[202:205], v[96:111]
	s_waitcnt lgkmcnt(8)
	v_mfma_f32_32x32x16_bf16 v[80:95], v[210:213], v[170:173], v[80:95]
	v_mfma_f32_32x32x16_bf16 v[64:79], v[210:213], v[202:205], v[64:79]
	s_waitcnt lgkmcnt(7)
	v_mfma_f32_32x32x16_bf16 v[48:63], v[214:217], v[170:173], v[48:63]
	v_mfma_f32_32x32x16_bf16 v[32:47], v[214:217], v[202:205], v[32:47]
	s_waitcnt lgkmcnt(6)
	v_mfma_f32_32x32x16_bf16 v[0:15], v[224:227], v[202:205], v[0:15]
	s_waitcnt vmcnt(4) lgkmcnt(0)
	s_barrier
	v_add_u32_e32 v202, v199, v177
	v_add_u32_e32 v222, v200, v177
	v_mfma_f32_32x32x16_bf16 v[16:31], v[224:227], v[170:173], v[16:31]
	ds_read_b128 v[170:173], v202 offset:16384
	ds_read_b128 v[202:205], v202 offset:18432
	ds_read_b128 v[206:209], v222
	ds_read_b128 v[210:213], v222 offset:2048
	ds_read_b128 v[214:217], v222 offset:4096
	ds_read_b128 v[224:227], v222 offset:6144
	s_waitcnt lgkmcnt(9)
	v_mfma_f32_32x32x16_bf16 v[112:127], v[138:141], v[130:133], v[112:127]
	v_mfma_f32_32x32x16_bf16 v[96:111], v[138:141], v[134:137], v[96:111]
	s_waitcnt lgkmcnt(8)
	v_mfma_f32_32x32x16_bf16 v[80:95], v[142:145], v[130:133], v[80:95]
	v_mfma_f32_32x32x16_bf16 v[64:79], v[142:145], v[134:137], v[64:79]
	s_waitcnt lgkmcnt(7)
	v_mfma_f32_32x32x16_bf16 v[48:63], v[146:149], v[130:133], v[48:63]
	v_mfma_f32_32x32x16_bf16 v[32:47], v[146:149], v[134:137], v[32:47]
	s_waitcnt lgkmcnt(6)
	v_mfma_f32_32x32x16_bf16 v[16:31], v[150:153], v[130:133], v[16:31]
	v_mfma_f32_32x32x16_bf16 v[0:15], v[150:153], v[134:137], v[0:15]
	v_add_u32_e32 v134, v199, v178
	v_add_u32_e32 v150, v200, v178
	ds_read_b128 v[130:133], v134 offset:16384
	ds_read_b128 v[134:137], v134 offset:18432
	ds_read_b128 v[138:141], v150
	ds_read_b128 v[142:145], v150 offset:2048
	ds_read_b128 v[146:149], v150 offset:4096
	ds_read_b128 v[150:153], v150 offset:6144
	s_waitcnt lgkmcnt(9)
	v_mfma_f32_32x32x16_bf16 v[112:127], v[206:209], v[170:173], v[112:127]
	v_mfma_f32_32x32x16_bf16 v[96:111], v[206:209], v[202:205], v[96:111]
	s_waitcnt lgkmcnt(8)
	v_mfma_f32_32x32x16_bf16 v[80:95], v[210:213], v[170:173], v[80:95]
	v_mfma_f32_32x32x16_bf16 v[64:79], v[210:213], v[202:205], v[64:79]
	s_waitcnt lgkmcnt(7)
	v_mfma_f32_32x32x16_bf16 v[48:63], v[214:217], v[170:173], v[48:63]
	v_mfma_f32_32x32x16_bf16 v[32:47], v[214:217], v[202:205], v[32:47]
	s_waitcnt lgkmcnt(6)
	v_mfma_f32_32x32x16_bf16 v[0:15], v[224:227], v[202:205], v[0:15]
	s_waitcnt vmcnt(0) lgkmcnt(0)
	s_barrier
	v_add_u32_e32 v202, v197, v177
	v_add_u32_e32 v222, v198, v177
	v_mfma_f32_32x32x16_bf16 v[16:31], v[224:227], v[170:173], v[16:31]
	ds_read_b128 v[170:173], v202 offset:16384
	ds_read_b128 v[202:205], v202 offset:18432
	ds_read_b128 v[206:209], v222
	ds_read_b128 v[210:213], v222 offset:2048
	ds_read_b128 v[214:217], v222 offset:4096
	ds_read_b128 v[224:227], v222 offset:6144
	s_waitcnt lgkmcnt(9)
	v_mfma_f32_32x32x16_bf16 v[112:127], v[138:141], v[130:133], v[112:127]
	v_mfma_f32_32x32x16_bf16 v[96:111], v[138:141], v[134:137], v[96:111]
	s_waitcnt lgkmcnt(8)
	v_mfma_f32_32x32x16_bf16 v[80:95], v[142:145], v[130:133], v[80:95]
	v_mfma_f32_32x32x16_bf16 v[64:79], v[142:145], v[134:137], v[64:79]
	s_waitcnt lgkmcnt(7)
	v_mfma_f32_32x32x16_bf16 v[48:63], v[146:149], v[130:133], v[48:63]
	v_mfma_f32_32x32x16_bf16 v[32:47], v[146:149], v[134:137], v[32:47]
	s_waitcnt lgkmcnt(6)
	v_mfma_f32_32x32x16_bf16 v[16:31], v[150:153], v[130:133], v[16:31]
	v_mfma_f32_32x32x16_bf16 v[0:15], v[150:153], v[134:137], v[0:15]
	v_add_u32_e32 v134, v197, v178
	v_add_u32_e32 v150, v198, v178
	ds_read_b128 v[130:133], v134 offset:16384
	ds_read_b128 v[134:137], v134 offset:18432
	ds_read_b128 v[138:141], v150
	ds_read_b128 v[142:145], v150 offset:2048
	ds_read_b128 v[146:149], v150 offset:4096
	ds_read_b128 v[150:153], v150 offset:6144
	s_waitcnt lgkmcnt(9)
	v_mfma_f32_32x32x16_bf16 v[112:127], v[206:209], v[170:173], v[112:127]
	v_mfma_f32_32x32x16_bf16 v[96:111], v[206:209], v[202:205], v[96:111]
	s_waitcnt lgkmcnt(8)
	v_mfma_f32_32x32x16_bf16 v[80:95], v[210:213], v[170:173], v[80:95]
	v_mfma_f32_32x32x16_bf16 v[64:79], v[210:213], v[202:205], v[64:79]
	s_waitcnt lgkmcnt(7)
	v_mfma_f32_32x32x16_bf16 v[48:63], v[214:217], v[170:173], v[48:63]
	v_mfma_f32_32x32x16_bf16 v[32:47], v[214:217], v[202:205], v[32:47]
	s_waitcnt lgkmcnt(6)
	v_mfma_f32_32x32x16_bf16 v[16:31], v[224:227], v[170:173], v[16:31]
	v_mfma_f32_32x32x16_bf16 v[0:15], v[224:227], v[202:205], v[0:15]
	s_waitcnt lgkmcnt(3)
	v_mfma_f32_32x32x16_bf16 v[112:127], v[138:141], v[130:133], v[112:127]
	v_mfma_f32_32x32x16_bf16 v[96:111], v[138:141], v[134:137], v[96:111]
	s_nop 10
	v_cvt_pk_bf16_f32 v112, v112, s0
	s_waitcnt lgkmcnt(2)
	v_mfma_f32_32x32x16_bf16 v[80:95], v[142:145], v[130:133], v[80:95]
	v_cvt_pk_bf16_f32 v96, v96, s0
	v_cvt_pk_bf16_f32 v98, v98, s0
	s_waitcnt lgkmcnt(1)
	v_mfma_f32_32x32x16_bf16 v[48:63], v[146:149], v[130:133], v[48:63]
	s_nop 7
	v_cvt_pk_bf16_f32 v80, v80, s0
	s_waitcnt lgkmcnt(0)
	v_mfma_f32_32x32x16_bf16 v[16:31], v[150:153], v[130:133], v[16:31]
	v_add_u32_e32 v132, s3, v128
	v_or_b32_e32 v130, s5, v174
	v_ashrrev_i32_e32 v131, 31, v130
	v_lshl_add_u64 v[130:131], v[130:131], 1, v[158:159]
	v_cvt_pk_bf16_f32 v48, v48, s0
	v_readlane_b32 s3, v252, 7
	s_add_i32 s4, s4, s3
	v_mfma_f32_32x32x16_bf16 v[64:79], v[142:145], v[134:137], v[64:79]
	s_nop 3
	v_cvt_pk_bf16_f32 v16, v16, s0
	v_mfma_f32_32x32x16_bf16 v[32:47], v[146:149], v[134:137], v[32:47]
	s_nop 5
	v_cvt_pk_bf16_f32 v64, v64, s0
	v_cvt_pk_bf16_f32 v66, v66, s0
	v_mfma_f32_32x32x16_bf16 v[0:15], v[150:153], v[134:137], v[0:15]
	v_or_b32_e32 v134, v132, v181
	v_ashrrev_i32_e32 v135, 31, v134
	v_lshlrev_b64 v[134:135], 11, v[134:135]
	v_lshl_add_u64 v[134:135], v[130:131], 0, v[134:135]
	global_store_short v[134:135], v112, off
	global_store_short v[134:135], v96, off offset:64
	v_or_b32_e32 v134, v132, v182
	v_ashrrev_i32_e32 v135, 31, v134
	v_lshlrev_b64 v[134:135], 11, v[134:135]
	v_lshl_add_u64 v[134:135], v[130:131], 0, v[134:135]
	v_cvt_pk_bf16_f32 v96, v113, s0
	global_store_short v[134:135], v96, off
	v_cvt_pk_bf16_f32 v96, v97, s0
	global_store_short v[134:135], v96, off offset:64
	v_or_b32_e32 v96, v132, v183
	v_ashrrev_i32_e32 v97, 31, v96
	v_lshlrev_b64 v[96:97], 11, v[96:97]
	v_lshl_add_u64 v[96:97], v[130:131], 0, v[96:97]
	v_cvt_pk_bf16_f32 v112, v114, s0
	global_store_short v[96:97], v112, off
	global_store_short v[96:97], v98, off offset:64
	v_or_b32_e32 v96, v132, v184
	v_ashrrev_i32_e32 v97, 31, v96
	v_lshlrev_b64 v[96:97], 11, v[96:97]
	v_lshl_add_u64 v[96:97], v[130:131], 0, v[96:97]
	v_cvt_pk_bf16_f32 v98, v115, s0
	global_store_short v[96:97], v98, off
	v_cvt_pk_bf16_f32 v98, v99, s0
	global_store_short v[96:97], v98, off offset:64
	v_or_b32_e32 v96, v132, v185
	v_ashrrev_i32_e32 v97, 31, v96
	v_lshlrev_b64 v[96:97], 11, v[96:97]
	v_lshl_add_u64 v[96:97], v[130:131], 0, v[96:97]
	v_cvt_pk_bf16_f32 v98, v116, s0
	global_store_short v[96:97], v98, off
	v_cvt_pk_bf16_f32 v98, v100, s0
	global_store_short v[96:97], v98, off offset:64
	v_or_b32_e32 v96, v132, v186
	v_ashrrev_i32_e32 v97, 31, v96
	v_lshlrev_b64 v[96:97], 11, v[96:97]
	v_lshl_add_u64 v[96:97], v[130:131], 0, v[96:97]
	v_cvt_pk_bf16_f32 v98, v117, s0
	global_store_short v[96:97], v98, off
	v_cvt_pk_bf16_f32 v98, v101, s0
	global_store_short v[96:97], v98, off offset:64
	v_or_b32_e32 v96, v132, v187
	v_ashrrev_i32_e32 v97, 31, v96
	v_lshlrev_b64 v[96:97], 11, v[96:97]
	v_lshl_add_u64 v[96:97], v[130:131], 0, v[96:97]
	v_cvt_pk_bf16_f32 v98, v118, s0
	global_store_short v[96:97], v98, off
	v_cvt_pk_bf16_f32 v98, v102, s0
	global_store_short v[96:97], v98, off offset:64
	v_or_b32_e32 v96, v132, v188
	v_ashrrev_i32_e32 v97, 31, v96
	v_lshlrev_b64 v[96:97], 11, v[96:97]
	v_lshl_add_u64 v[96:97], v[130:131], 0, v[96:97]
	v_cvt_pk_bf16_f32 v98, v119, s0
	global_store_short v[96:97], v98, off
	v_cvt_pk_bf16_f32 v98, v103, s0
	global_store_short v[96:97], v98, off offset:64
	v_or_b32_e32 v96, v132, v189
	v_ashrrev_i32_e32 v97, 31, v96
	v_lshlrev_b64 v[96:97], 11, v[96:97]
	v_lshl_add_u64 v[96:97], v[130:131], 0, v[96:97]
	v_cvt_pk_bf16_f32 v98, v120, s0
	global_store_short v[96:97], v98, off
	v_cvt_pk_bf16_f32 v98, v104, s0
	global_store_short v[96:97], v98, off offset:64
	v_or_b32_e32 v96, v132, v190
	v_ashrrev_i32_e32 v97, 31, v96
	v_lshlrev_b64 v[96:97], 11, v[96:97]
	v_lshl_add_u64 v[96:97], v[130:131], 0, v[96:97]
	v_cvt_pk_bf16_f32 v98, v121, s0
	global_store_short v[96:97], v98, off
	v_cvt_pk_bf16_f32 v98, v105, s0
	global_store_short v[96:97], v98, off offset:64
	v_or_b32_e32 v96, v132, v191
	v_ashrrev_i32_e32 v97, 31, v96
	v_lshlrev_b64 v[96:97], 11, v[96:97]
	v_lshl_add_u64 v[96:97], v[130:131], 0, v[96:97]
	v_cvt_pk_bf16_f32 v98, v122, s0
	global_store_short v[96:97], v98, off
	v_cvt_pk_bf16_f32 v98, v106, s0
	global_store_short v[96:97], v98, off offset:64
	v_or_b32_e32 v96, v132, v192
	v_ashrrev_i32_e32 v97, 31, v96
	v_lshlrev_b64 v[96:97], 11, v[96:97]
	v_lshl_add_u64 v[96:97], v[130:131], 0, v[96:97]
	v_cvt_pk_bf16_f32 v98, v123, s0
	global_store_short v[96:97], v98, off
	v_cvt_pk_bf16_f32 v98, v107, s0
	global_store_short v[96:97], v98, off offset:64
	v_or_b32_e32 v96, v132, v193
	v_ashrrev_i32_e32 v97, 31, v96
	v_lshlrev_b64 v[96:97], 11, v[96:97]
	v_lshl_add_u64 v[96:97], v[130:131], 0, v[96:97]
	v_cvt_pk_bf16_f32 v98, v124, s0
	global_store_short v[96:97], v98, off
	v_cvt_pk_bf16_f32 v98, v108, s0
	global_store_short v[96:97], v98, off offset:64
	v_or_b32_e32 v96, v132, v194
	v_ashrrev_i32_e32 v97, 31, v96
	v_lshlrev_b64 v[96:97], 11, v[96:97]
	v_lshl_add_u64 v[96:97], v[130:131], 0, v[96:97]
	v_cvt_pk_bf16_f32 v98, v125, s0
	global_store_short v[96:97], v98, off
	v_cvt_pk_bf16_f32 v98, v109, s0
	global_store_short v[96:97], v98, off offset:64
	v_or_b32_e32 v96, v132, v195
	v_ashrrev_i32_e32 v97, 31, v96
	v_lshlrev_b64 v[96:97], 11, v[96:97]
	v_lshl_add_u64 v[96:97], v[130:131], 0, v[96:97]
	v_cvt_pk_bf16_f32 v98, v126, s0
	global_store_short v[96:97], v98, off
	v_cvt_pk_bf16_f32 v98, v110, s0
	global_store_short v[96:97], v98, off offset:64
	v_or_b32_e32 v96, v132, v196
	v_ashrrev_i32_e32 v97, 31, v96
	v_lshlrev_b64 v[96:97], 11, v[96:97]
	v_lshl_add_u64 v[96:97], v[130:131], 0, v[96:97]
	v_cvt_pk_bf16_f32 v98, v127, s0
	global_store_short v[96:97], v98, off
	v_cvt_pk_bf16_f32 v98, v111, s0
	global_store_short v[96:97], v98, off offset:64
	v_or_b32_e32 v98, 32, v132
	v_or_b32_e32 v96, v98, v181
	v_ashrrev_i32_e32 v97, 31, v96
	v_lshlrev_b64 v[96:97], 11, v[96:97]
	v_lshl_add_u64 v[96:97], v[130:131], 0, v[96:97]
	global_store_short v[96:97], v80, off
	global_store_short v[96:97], v64, off offset:64
	v_or_b32_e32 v96, v98, v182
	v_ashrrev_i32_e32 v97, 31, v96
	v_lshlrev_b64 v[96:97], 11, v[96:97]
	v_lshl_add_u64 v[96:97], v[130:131], 0, v[96:97]
	v_cvt_pk_bf16_f32 v64, v81, s0
	global_store_short v[96:97], v64, off
	v_cvt_pk_bf16_f32 v64, v65, s0
	global_store_short v[96:97], v64, off offset:64
	v_or_b32_e32 v64, v98, v183
	v_ashrrev_i32_e32 v65, 31, v64
	v_lshlrev_b64 v[64:65], 11, v[64:65]
	v_lshl_add_u64 v[64:65], v[130:131], 0, v[64:65]
	v_cvt_pk_bf16_f32 v80, v82, s0
	global_store_short v[64:65], v80, off
	global_store_short v[64:65], v66, off offset:64
	v_or_b32_e32 v64, v98, v184
	v_ashrrev_i32_e32 v65, 31, v64
	v_lshlrev_b64 v[64:65], 11, v[64:65]
	v_lshl_add_u64 v[64:65], v[130:131], 0, v[64:65]
	v_cvt_pk_bf16_f32 v66, v83, s0
	global_store_short v[64:65], v66, off
	v_cvt_pk_bf16_f32 v66, v67, s0
	global_store_short v[64:65], v66, off offset:64
	v_or_b32_e32 v64, v98, v185
	v_ashrrev_i32_e32 v65, 31, v64
	v_lshlrev_b64 v[64:65], 11, v[64:65]
	v_lshl_add_u64 v[64:65], v[130:131], 0, v[64:65]
	v_cvt_pk_bf16_f32 v66, v84, s0
	global_store_short v[64:65], v66, off
	v_cvt_pk_bf16_f32 v66, v68, s0
	global_store_short v[64:65], v66, off offset:64
	v_or_b32_e32 v64, v98, v186
	v_ashrrev_i32_e32 v65, 31, v64
	v_lshlrev_b64 v[64:65], 11, v[64:65]
	v_lshl_add_u64 v[64:65], v[130:131], 0, v[64:65]
	v_cvt_pk_bf16_f32 v66, v85, s0
	global_store_short v[64:65], v66, off
	v_cvt_pk_bf16_f32 v66, v69, s0
	global_store_short v[64:65], v66, off offset:64
	v_or_b32_e32 v64, v98, v187
	v_ashrrev_i32_e32 v65, 31, v64
	v_lshlrev_b64 v[64:65], 11, v[64:65]
	v_lshl_add_u64 v[64:65], v[130:131], 0, v[64:65]
	v_cvt_pk_bf16_f32 v66, v86, s0
	global_store_short v[64:65], v66, off
	v_cvt_pk_bf16_f32 v66, v70, s0
	global_store_short v[64:65], v66, off offset:64
	v_or_b32_e32 v64, v98, v188
	v_ashrrev_i32_e32 v65, 31, v64
	v_lshlrev_b64 v[64:65], 11, v[64:65]
	v_lshl_add_u64 v[64:65], v[130:131], 0, v[64:65]
	v_cvt_pk_bf16_f32 v66, v87, s0
	global_store_short v[64:65], v66, off
	v_cvt_pk_bf16_f32 v66, v71, s0
	global_store_short v[64:65], v66, off offset:64
	v_or_b32_e32 v64, v98, v189
	v_ashrrev_i32_e32 v65, 31, v64
	v_lshlrev_b64 v[64:65], 11, v[64:65]
	v_lshl_add_u64 v[64:65], v[130:131], 0, v[64:65]
	v_cvt_pk_bf16_f32 v66, v88, s0
	global_store_short v[64:65], v66, off
	v_cvt_pk_bf16_f32 v66, v72, s0
	global_store_short v[64:65], v66, off offset:64
	v_or_b32_e32 v64, v98, v190
	v_ashrrev_i32_e32 v65, 31, v64
	v_lshlrev_b64 v[64:65], 11, v[64:65]
	v_lshl_add_u64 v[64:65], v[130:131], 0, v[64:65]
	v_cvt_pk_bf16_f32 v66, v89, s0
	global_store_short v[64:65], v66, off
	v_cvt_pk_bf16_f32 v66, v73, s0
	global_store_short v[64:65], v66, off offset:64
	v_or_b32_e32 v64, v98, v191
	v_ashrrev_i32_e32 v65, 31, v64
	v_lshlrev_b64 v[64:65], 11, v[64:65]
	v_lshl_add_u64 v[64:65], v[130:131], 0, v[64:65]
	v_cvt_pk_bf16_f32 v66, v90, s0
	global_store_short v[64:65], v66, off
	v_cvt_pk_bf16_f32 v66, v74, s0
	global_store_short v[64:65], v66, off offset:64
	v_or_b32_e32 v64, v98, v192
	v_ashrrev_i32_e32 v65, 31, v64
	v_lshlrev_b64 v[64:65], 11, v[64:65]
	v_lshl_add_u64 v[64:65], v[130:131], 0, v[64:65]
	v_cvt_pk_bf16_f32 v66, v91, s0
	global_store_short v[64:65], v66, off
	v_cvt_pk_bf16_f32 v66, v75, s0
	global_store_short v[64:65], v66, off offset:64
	v_or_b32_e32 v64, v98, v193
	v_ashrrev_i32_e32 v65, 31, v64
	v_lshlrev_b64 v[64:65], 11, v[64:65]
	v_lshl_add_u64 v[64:65], v[130:131], 0, v[64:65]
	v_cvt_pk_bf16_f32 v66, v92, s0
	global_store_short v[64:65], v66, off
	v_cvt_pk_bf16_f32 v66, v76, s0
	global_store_short v[64:65], v66, off offset:64
	v_or_b32_e32 v64, v98, v194
	v_ashrrev_i32_e32 v65, 31, v64
	v_lshlrev_b64 v[64:65], 11, v[64:65]
	v_lshl_add_u64 v[64:65], v[130:131], 0, v[64:65]
	v_cvt_pk_bf16_f32 v66, v93, s0
	global_store_short v[64:65], v66, off
	v_cvt_pk_bf16_f32 v66, v77, s0
	global_store_short v[64:65], v66, off offset:64
	v_or_b32_e32 v64, v98, v195
	v_ashrrev_i32_e32 v65, 31, v64
	v_lshlrev_b64 v[64:65], 11, v[64:65]
	v_lshl_add_u64 v[64:65], v[130:131], 0, v[64:65]
	v_cvt_pk_bf16_f32 v66, v94, s0
	global_store_short v[64:65], v66, off
	v_cvt_pk_bf16_f32 v66, v78, s0
	global_store_short v[64:65], v66, off offset:64
	v_or_b32_e32 v64, v98, v196
	v_ashrrev_i32_e32 v65, 31, v64
	v_lshlrev_b64 v[64:65], 11, v[64:65]
	v_lshl_add_u64 v[64:65], v[130:131], 0, v[64:65]
	v_cvt_pk_bf16_f32 v66, v95, s0
	global_store_short v[64:65], v66, off
	v_cvt_pk_bf16_f32 v66, v79, s0
	global_store_short v[64:65], v66, off offset:64
	v_or_b32_e32 v66, 64, v132
	v_or_b32_e32 v64, v66, v181
	v_ashrrev_i32_e32 v65, 31, v64
	v_lshlrev_b64 v[64:65], 11, v[64:65]
	v_lshl_add_u64 v[64:65], v[130:131], 0, v[64:65]
	v_cvt_pk_bf16_f32 v32, v32, s0
	global_store_short v[64:65], v48, off
	global_store_short v[64:65], v32, off offset:64
	v_or_b32_e32 v64, v66, v182
	v_ashrrev_i32_e32 v65, 31, v64
	v_lshlrev_b64 v[64:65], 11, v[64:65]
	v_lshl_add_u64 v[64:65], v[130:131], 0, v[64:65]
	v_cvt_pk_bf16_f32 v32, v49, s0
	global_store_short v[64:65], v32, off
	v_cvt_pk_bf16_f32 v32, v33, s0
	global_store_short v[64:65], v32, off offset:64
	v_or_b32_e32 v32, v66, v183
	v_ashrrev_i32_e32 v33, 31, v32
	v_lshlrev_b64 v[32:33], 11, v[32:33]
	v_lshl_add_u64 v[32:33], v[130:131], 0, v[32:33]
	v_cvt_pk_bf16_f32 v48, v50, s0
	v_cvt_pk_bf16_f32 v34, v34, s0
	global_store_short v[32:33], v48, off
	global_store_short v[32:33], v34, off offset:64
	v_or_b32_e32 v32, v66, v184
	v_ashrrev_i32_e32 v33, 31, v32
	v_lshlrev_b64 v[32:33], 11, v[32:33]
	v_lshl_add_u64 v[32:33], v[130:131], 0, v[32:33]
	v_cvt_pk_bf16_f32 v34, v51, s0
	global_store_short v[32:33], v34, off
	v_cvt_pk_bf16_f32 v34, v35, s0
	global_store_short v[32:33], v34, off offset:64
	v_or_b32_e32 v32, v66, v185
	v_ashrrev_i32_e32 v33, 31, v32
	v_lshlrev_b64 v[32:33], 11, v[32:33]
	v_lshl_add_u64 v[32:33], v[130:131], 0, v[32:33]
	v_cvt_pk_bf16_f32 v34, v52, s0
	global_store_short v[32:33], v34, off
	v_cvt_pk_bf16_f32 v34, v36, s0
	global_store_short v[32:33], v34, off offset:64
	v_or_b32_e32 v32, v66, v186
	v_ashrrev_i32_e32 v33, 31, v32
	v_lshlrev_b64 v[32:33], 11, v[32:33]
	v_lshl_add_u64 v[32:33], v[130:131], 0, v[32:33]
	v_cvt_pk_bf16_f32 v34, v53, s0
	global_store_short v[32:33], v34, off
	v_cvt_pk_bf16_f32 v34, v37, s0
	global_store_short v[32:33], v34, off offset:64
	v_or_b32_e32 v32, v66, v187
	v_ashrrev_i32_e32 v33, 31, v32
	v_lshlrev_b64 v[32:33], 11, v[32:33]
	v_lshl_add_u64 v[32:33], v[130:131], 0, v[32:33]
	v_cvt_pk_bf16_f32 v34, v54, s0
	global_store_short v[32:33], v34, off
	v_cvt_pk_bf16_f32 v34, v38, s0
	global_store_short v[32:33], v34, off offset:64
	v_or_b32_e32 v32, v66, v188
	v_ashrrev_i32_e32 v33, 31, v32
	v_lshlrev_b64 v[32:33], 11, v[32:33]
	v_lshl_add_u64 v[32:33], v[130:131], 0, v[32:33]
	v_cvt_pk_bf16_f32 v34, v55, s0
	global_store_short v[32:33], v34, off
	v_cvt_pk_bf16_f32 v34, v39, s0
	global_store_short v[32:33], v34, off offset:64
	v_or_b32_e32 v32, v66, v189
	v_ashrrev_i32_e32 v33, 31, v32
	v_lshlrev_b64 v[32:33], 11, v[32:33]
	v_lshl_add_u64 v[32:33], v[130:131], 0, v[32:33]
	v_cvt_pk_bf16_f32 v34, v56, s0
	global_store_short v[32:33], v34, off
	v_cvt_pk_bf16_f32 v34, v40, s0
	global_store_short v[32:33], v34, off offset:64
	v_or_b32_e32 v32, v66, v190
	v_ashrrev_i32_e32 v33, 31, v32
	v_lshlrev_b64 v[32:33], 11, v[32:33]
	v_lshl_add_u64 v[32:33], v[130:131], 0, v[32:33]
	v_cvt_pk_bf16_f32 v34, v57, s0
	global_store_short v[32:33], v34, off
	v_cvt_pk_bf16_f32 v34, v41, s0
	global_store_short v[32:33], v34, off offset:64
	v_or_b32_e32 v32, v66, v191
	v_ashrrev_i32_e32 v33, 31, v32
	v_lshlrev_b64 v[32:33], 11, v[32:33]
	v_lshl_add_u64 v[32:33], v[130:131], 0, v[32:33]
	v_cvt_pk_bf16_f32 v34, v58, s0
	global_store_short v[32:33], v34, off
	v_cvt_pk_bf16_f32 v34, v42, s0
	global_store_short v[32:33], v34, off offset:64
	v_or_b32_e32 v32, v66, v192
	v_ashrrev_i32_e32 v33, 31, v32
	v_lshlrev_b64 v[32:33], 11, v[32:33]
	v_lshl_add_u64 v[32:33], v[130:131], 0, v[32:33]
	v_cvt_pk_bf16_f32 v34, v59, s0
	global_store_short v[32:33], v34, off
	v_cvt_pk_bf16_f32 v34, v43, s0
	global_store_short v[32:33], v34, off offset:64
	v_or_b32_e32 v32, v66, v193
	v_ashrrev_i32_e32 v33, 31, v32
	v_lshlrev_b64 v[32:33], 11, v[32:33]
	v_lshl_add_u64 v[32:33], v[130:131], 0, v[32:33]
	v_cvt_pk_bf16_f32 v34, v60, s0
	global_store_short v[32:33], v34, off
	v_cvt_pk_bf16_f32 v34, v44, s0
	global_store_short v[32:33], v34, off offset:64
	v_or_b32_e32 v32, v66, v194
	v_ashrrev_i32_e32 v33, 31, v32
	v_lshlrev_b64 v[32:33], 11, v[32:33]
	v_lshl_add_u64 v[32:33], v[130:131], 0, v[32:33]
	v_cvt_pk_bf16_f32 v34, v61, s0
	global_store_short v[32:33], v34, off
	v_cvt_pk_bf16_f32 v34, v45, s0
	global_store_short v[32:33], v34, off offset:64
	v_or_b32_e32 v32, v66, v195
	v_ashrrev_i32_e32 v33, 31, v32
	v_lshlrev_b64 v[32:33], 11, v[32:33]
	v_lshl_add_u64 v[32:33], v[130:131], 0, v[32:33]
	v_cvt_pk_bf16_f32 v34, v62, s0
	global_store_short v[32:33], v34, off
	v_cvt_pk_bf16_f32 v34, v46, s0
	global_store_short v[32:33], v34, off offset:64
	v_or_b32_e32 v32, v66, v196
	v_ashrrev_i32_e32 v33, 31, v32
	v_lshlrev_b64 v[32:33], 11, v[32:33]
	v_lshl_add_u64 v[32:33], v[130:131], 0, v[32:33]
	v_cvt_pk_bf16_f32 v34, v63, s0
	global_store_short v[32:33], v34, off
	v_cvt_pk_bf16_f32 v34, v47, s0
	global_store_short v[32:33], v34, off offset:64
	v_or_b32_e32 v34, 0x60, v132
	v_or_b32_e32 v32, v34, v181
	v_ashrrev_i32_e32 v33, 31, v32
	v_lshlrev_b64 v[32:33], 11, v[32:33]
	v_lshl_add_u64 v[32:33], v[130:131], 0, v[32:33]
	v_cvt_pk_bf16_f32 v0, v0, s0
	global_store_short v[32:33], v16, off
	global_store_short v[32:33], v0, off offset:64
	v_or_b32_e32 v32, v34, v182
	v_ashrrev_i32_e32 v33, 31, v32
	v_lshlrev_b64 v[32:33], 11, v[32:33]
	v_lshl_add_u64 v[32:33], v[130:131], 0, v[32:33]
	v_cvt_pk_bf16_f32 v0, v17, s0
	global_store_short v[32:33], v0, off
	v_cvt_pk_bf16_f32 v0, v1, s0
	global_store_short v[32:33], v0, off offset:64
	v_or_b32_e32 v0, v34, v183
	v_ashrrev_i32_e32 v1, 31, v0
	v_lshlrev_b64 v[0:1], 11, v[0:1]
	v_lshl_add_u64 v[0:1], v[130:131], 0, v[0:1]
	v_cvt_pk_bf16_f32 v16, v18, s0
	v_cvt_pk_bf16_f32 v2, v2, s0
	global_store_short v[0:1], v16, off
	global_store_short v[0:1], v2, off offset:64
	v_or_b32_e32 v0, v34, v184
	v_ashrrev_i32_e32 v1, 31, v0
	v_lshlrev_b64 v[0:1], 11, v[0:1]
	v_lshl_add_u64 v[0:1], v[130:131], 0, v[0:1]
	v_cvt_pk_bf16_f32 v2, v19, s0
	global_store_short v[0:1], v2, off
	v_cvt_pk_bf16_f32 v2, v3, s0
	global_store_short v[0:1], v2, off offset:64
	v_or_b32_e32 v0, v34, v185
	v_ashrrev_i32_e32 v1, 31, v0
	v_lshlrev_b64 v[0:1], 11, v[0:1]
	v_lshl_add_u64 v[0:1], v[130:131], 0, v[0:1]
	v_cvt_pk_bf16_f32 v2, v20, s0
	global_store_short v[0:1], v2, off
	v_cvt_pk_bf16_f32 v2, v4, s0
	global_store_short v[0:1], v2, off offset:64
	v_or_b32_e32 v0, v34, v186
	v_ashrrev_i32_e32 v1, 31, v0
	v_lshlrev_b64 v[0:1], 11, v[0:1]
	v_lshl_add_u64 v[0:1], v[130:131], 0, v[0:1]
	v_cvt_pk_bf16_f32 v2, v21, s0
	global_store_short v[0:1], v2, off
	v_cvt_pk_bf16_f32 v2, v5, s0
	global_store_short v[0:1], v2, off offset:64
	v_or_b32_e32 v0, v34, v187
	v_ashrrev_i32_e32 v1, 31, v0
	v_lshlrev_b64 v[0:1], 11, v[0:1]
	v_lshl_add_u64 v[0:1], v[130:131], 0, v[0:1]
	v_cvt_pk_bf16_f32 v2, v22, s0
	global_store_short v[0:1], v2, off
	v_cvt_pk_bf16_f32 v2, v6, s0
	global_store_short v[0:1], v2, off offset:64
	v_or_b32_e32 v0, v34, v188
	v_ashrrev_i32_e32 v1, 31, v0
	v_lshlrev_b64 v[0:1], 11, v[0:1]
	v_lshl_add_u64 v[0:1], v[130:131], 0, v[0:1]
	v_cvt_pk_bf16_f32 v2, v23, s0
	global_store_short v[0:1], v2, off
	v_cvt_pk_bf16_f32 v2, v7, s0
	global_store_short v[0:1], v2, off offset:64
	v_or_b32_e32 v0, v34, v189
	v_ashrrev_i32_e32 v1, 31, v0
	v_lshlrev_b64 v[0:1], 11, v[0:1]
	v_lshl_add_u64 v[0:1], v[130:131], 0, v[0:1]
	v_cvt_pk_bf16_f32 v2, v24, s0
	global_store_short v[0:1], v2, off
	v_cvt_pk_bf16_f32 v2, v8, s0
	global_store_short v[0:1], v2, off offset:64
	v_or_b32_e32 v0, v34, v190
	v_ashrrev_i32_e32 v1, 31, v0
	v_lshlrev_b64 v[0:1], 11, v[0:1]
	v_lshl_add_u64 v[0:1], v[130:131], 0, v[0:1]
	v_cvt_pk_bf16_f32 v2, v25, s0
	global_store_short v[0:1], v2, off
	v_cvt_pk_bf16_f32 v2, v9, s0
	global_store_short v[0:1], v2, off offset:64
	v_or_b32_e32 v0, v34, v191
	v_ashrrev_i32_e32 v1, 31, v0
	v_lshlrev_b64 v[0:1], 11, v[0:1]
	v_lshl_add_u64 v[0:1], v[130:131], 0, v[0:1]
	v_cvt_pk_bf16_f32 v2, v26, s0
	global_store_short v[0:1], v2, off
	v_cvt_pk_bf16_f32 v2, v10, s0
	global_store_short v[0:1], v2, off offset:64
	v_or_b32_e32 v0, v34, v192
	v_ashrrev_i32_e32 v1, 31, v0
	v_lshlrev_b64 v[0:1], 11, v[0:1]
	v_lshl_add_u64 v[0:1], v[130:131], 0, v[0:1]
	v_cvt_pk_bf16_f32 v2, v27, s0
	global_store_short v[0:1], v2, off
	v_cvt_pk_bf16_f32 v2, v11, s0
	global_store_short v[0:1], v2, off offset:64
	v_or_b32_e32 v0, v34, v193
	v_ashrrev_i32_e32 v1, 31, v0
	v_lshlrev_b64 v[0:1], 11, v[0:1]
	v_lshl_add_u64 v[0:1], v[130:131], 0, v[0:1]
	v_cvt_pk_bf16_f32 v2, v28, s0
	global_store_short v[0:1], v2, off
	v_cvt_pk_bf16_f32 v2, v12, s0
	global_store_short v[0:1], v2, off offset:64
	v_or_b32_e32 v0, v34, v194
	v_ashrrev_i32_e32 v1, 31, v0
	v_lshlrev_b64 v[0:1], 11, v[0:1]
	v_lshl_add_u64 v[0:1], v[130:131], 0, v[0:1]
	v_cvt_pk_bf16_f32 v2, v29, s0
	global_store_short v[0:1], v2, off
	v_cvt_pk_bf16_f32 v2, v13, s0
	global_store_short v[0:1], v2, off offset:64
	v_or_b32_e32 v0, v34, v195
	v_ashrrev_i32_e32 v1, 31, v0
	v_lshlrev_b64 v[0:1], 11, v[0:1]
	v_lshl_add_u64 v[0:1], v[130:131], 0, v[0:1]
	v_cvt_pk_bf16_f32 v2, v30, s0
	global_store_short v[0:1], v2, off
	v_cvt_pk_bf16_f32 v2, v14, s0
	global_store_short v[0:1], v2, off offset:64
	v_or_b32_e32 v0, v34, v196
	v_ashrrev_i32_e32 v1, 31, v0
	v_lshlrev_b64 v[0:1], 11, v[0:1]
	v_lshl_add_u64 v[0:1], v[130:131], 0, v[0:1]
	v_cvt_pk_bf16_f32 v2, v31, s0
	global_store_short v[0:1], v2, off
	v_cvt_pk_bf16_f32 v2, v15, s0
	s_add_i32 s0, s0, s3
	v_readlane_b32 s3, v252, 8
	s_add_i32 s2, s2, s3
	s_cmp_gt_i32 s4, 31
	global_store_short v[0:1], v2, off offset:64
	s_cbranch_scc0 .LBB0_1101

.LBB0_1161:
	s_waitcnt lgkmcnt(0)
	s_nop 0
	v_mfma_f32_32x32x16_bf16 v[112:127], v[150:153], v[142:145], v[112:127]
	v_mfma_f32_32x32x16_bf16 v[96:111], v[150:153], v[130:133], v[96:111]
	s_and_b32 s21, s20, 0x18000
	v_add_u32_e32 v128, s21, v203
	s_add_i32 s21, s20, 0xfffe8000
	s_and_b32 s21, s21, 0x18000
	v_or_b32_e32 v222, s21, v202
	v_add_u32_e32 v223, s21, v199
	s_waitcnt vmcnt(8)
	s_barrier
	v_add_u32_e32 v180, v222, v200
	v_add_u32_e32 v224, v223, v200
	ds_read_b128 v[176:179], v180 offset:16384
	ds_read_b128 v[180:183], v180 offset:18432
	ds_read_b128 v[184:187], v224
	v_mfma_f32_32x32x16_bf16 v[80:95], v[146:149], v[142:145], v[80:95]
	v_readfirstlane_b32 s21, v128
	s_mov_b32 m0, s21
	v_mfma_f32_32x32x16_bf16 v[64:79], v[146:149], v[130:133], v[64:79]
	ds_read_b128 v[188:191], v224 offset:2048
	global_load_lds_dwordx4 v[172:173], off
	v_mfma_f32_32x32x16_bf16 v[48:63], v[138:141], v[142:145], v[48:63]
	s_add_i32 s22, s21, 0x2000
	v_lshl_add_u64 v[150:151], v[172:173], 0, s[26:27]
	s_mov_b32 m0, s22
	v_mfma_f32_32x32x16_bf16 v[32:47], v[138:141], v[130:133], v[32:47]
	ds_read_b128 v[192:195], v224 offset:4096
	global_load_lds_dwordx4 v[150:151], off
	v_mfma_f32_32x32x16_bf16 v[16:31], v[134:137], v[142:145], v[16:31]
	v_mfma_f32_32x32x16_bf16 v[0:15], v[134:137], v[130:133], v[0:15]
	ds_read_b128 v[240:243], v224 offset:6144
	s_waitcnt lgkmcnt(3)
	v_mfma_f32_32x32x16_bf16 v[112:127], v[184:187], v[176:179], v[112:127]
	v_add_u32_e32 v128, v222, v201
	ds_read_b128 v[142:145], v128 offset:16384
	s_add_i32 s22, s21, 0x6000
	s_addk_i32 s21, 0x4000
	s_mov_b32 m0, s21
	v_mfma_f32_32x32x16_bf16 v[96:111], v[184:187], v[180:183], v[96:111]
	ds_read_b128 v[130:133], v128 offset:18432
	global_load_lds_dwordx4 v[174:175], off
	s_waitcnt lgkmcnt(4)
	v_mfma_f32_32x32x16_bf16 v[80:95], v[188:191], v[176:179], v[80:95]
	v_add_u32_e32 v128, v223, v201
	ds_read_b128 v[150:153], v128
	v_mfma_f32_32x32x16_bf16 v[64:79], v[188:191], v[180:183], v[64:79]
	ds_read_b128 v[146:149], v128 offset:2048
	s_waitcnt lgkmcnt(5)
	v_mfma_f32_32x32x16_bf16 v[48:63], v[192:195], v[176:179], v[48:63]
	ds_read_b128 v[138:141], v128 offset:4096
	v_lshl_add_u64 v[224:225], v[174:175], 0, s[26:27]
	s_mov_b32 m0, s22
	v_mfma_f32_32x32x16_bf16 v[32:47], v[192:195], v[180:183], v[32:47]
	ds_read_b128 v[134:137], v128 offset:6144
	global_load_lds_dwordx4 v[224:225], off
	s_waitcnt lgkmcnt(6)
	v_mfma_f32_32x32x16_bf16 v[16:31], v[240:243], v[176:179], v[16:31]
	s_add_i32 s20, s20, 0x8000
	v_lshl_add_u64 v[172:173], v[172:173], 0, 64
	v_lshl_add_u64 v[174:175], v[174:175], 0, 64
	s_cmp_eq_u32 s20, 0x100000
	v_mfma_f32_32x32x16_bf16 v[0:15], v[240:243], v[180:183], v[0:15]
	s_cbranch_scc0 .LBB0_1161
	s_waitcnt vmcnt(8) lgkmcnt(0)
	s_barrier
	v_add_u32_e32 v128, v202, v200
	ds_read_b128 v[172:175], v128 offset:49152
	ds_read_b128 v[176:179], v128 offset:51200
	v_add_u32_e32 v128, v199, v200
	ds_read_b128 v[180:183], v128 offset:32768
	ds_read_b128 v[184:187], v128 offset:34816
	ds_read_b128 v[188:191], v128 offset:36864
	ds_read_b128 v[192:195], v128 offset:38912
	s_waitcnt lgkmcnt(9)
	v_mfma_f32_32x32x16_bf16 v[112:127], v[150:153], v[142:145], v[112:127]
	v_mfma_f32_32x32x16_bf16 v[96:111], v[150:153], v[130:133], v[96:111]
	s_waitcnt lgkmcnt(8)
	v_mfma_f32_32x32x16_bf16 v[80:95], v[146:149], v[142:145], v[80:95]
	v_mfma_f32_32x32x16_bf16 v[64:79], v[146:149], v[130:133], v[64:79]
	s_waitcnt lgkmcnt(7)
	v_mfma_f32_32x32x16_bf16 v[48:63], v[138:141], v[142:145], v[48:63]
	v_mfma_f32_32x32x16_bf16 v[32:47], v[138:141], v[130:133], v[32:47]
	s_waitcnt lgkmcnt(6)
	v_mfma_f32_32x32x16_bf16 v[16:31], v[134:137], v[142:145], v[16:31]
	v_mfma_f32_32x32x16_bf16 v[0:15], v[134:137], v[130:133], v[0:15]
	v_add_u32_e32 v128, v202, v201
	ds_read_b128 v[130:133], v128 offset:49152
	ds_read_b128 v[134:137], v128 offset:51200
	v_add_u32_e32 v128, v199, v201
	ds_read_b128 v[138:141], v128 offset:32768
	ds_read_b128 v[142:145], v128 offset:34816
	ds_read_b128 v[146:149], v128 offset:36864
	ds_read_b128 v[150:153], v128 offset:38912
	s_waitcnt lgkmcnt(9)
	v_mfma_f32_32x32x16_bf16 v[112:127], v[180:183], v[172:175], v[112:127]
	v_mfma_f32_32x32x16_bf16 v[96:111], v[180:183], v[176:179], v[96:111]
	s_waitcnt lgkmcnt(8)
	v_mfma_f32_32x32x16_bf16 v[80:95], v[184:187], v[172:175], v[80:95]
	v_mfma_f32_32x32x16_bf16 v[64:79], v[184:187], v[176:179], v[64:79]
	s_waitcnt lgkmcnt(7)
	v_mfma_f32_32x32x16_bf16 v[48:63], v[188:191], v[172:175], v[48:63]
	v_mfma_f32_32x32x16_bf16 v[32:47], v[188:191], v[176:179], v[32:47]
	s_waitcnt vmcnt(4) lgkmcnt(0)
	s_barrier
	v_add_u32_e32 v128, v236, v200
	s_waitcnt lgkmcnt(6)
	v_mfma_f32_32x32x16_bf16 v[16:31], v[192:195], v[172:175], v[16:31]
	v_mfma_f32_32x32x16_bf16 v[0:15], v[192:195], v[176:179], v[0:15]
	ds_read_b128 v[172:175], v128 offset:16384
	ds_read_b128 v[176:179], v128 offset:18432
	v_add_u32_e32 v128, v237, v200
	ds_read_b128 v[180:183], v128
	ds_read_b128 v[184:187], v128 offset:2048
	ds_read_b128 v[188:191], v128 offset:4096
	ds_read_b128 v[192:195], v128 offset:6144
	s_waitcnt lgkmcnt(9)
	v_mfma_f32_32x32x16_bf16 v[112:127], v[138:141], v[130:133], v[112:127]
	v_mfma_f32_32x32x16_bf16 v[96:111], v[138:141], v[134:137], v[96:111]
	s_waitcnt lgkmcnt(8)
	v_mfma_f32_32x32x16_bf16 v[80:95], v[142:145], v[130:133], v[80:95]
	v_mfma_f32_32x32x16_bf16 v[64:79], v[142:145], v[134:137], v[64:79]
	s_waitcnt lgkmcnt(7)
	v_mfma_f32_32x32x16_bf16 v[48:63], v[146:149], v[130:133], v[48:63]
	v_mfma_f32_32x32x16_bf16 v[32:47], v[146:149], v[134:137], v[32:47]
	s_waitcnt lgkmcnt(6)
	v_mfma_f32_32x32x16_bf16 v[16:31], v[150:153], v[130:133], v[16:31]
	v_mfma_f32_32x32x16_bf16 v[0:15], v[150:153], v[134:137], v[0:15]
	v_add_u32_e32 v128, v236, v201
	ds_read_b128 v[130:133], v128 offset:16384
	ds_read_b128 v[134:137], v128 offset:18432
	v_add_u32_e32 v128, v237, v201
	ds_read_b128 v[138:141], v128
	ds_read_b128 v[142:145], v128 offset:2048
	ds_read_b128 v[146:149], v128 offset:4096
	ds_read_b128 v[150:153], v128 offset:6144
	s_waitcnt lgkmcnt(9)
	v_mfma_f32_32x32x16_bf16 v[112:127], v[180:183], v[172:175], v[112:127]
	v_mfma_f32_32x32x16_bf16 v[96:111], v[180:183], v[176:179], v[96:111]
	s_waitcnt lgkmcnt(8)
	v_mfma_f32_32x32x16_bf16 v[80:95], v[184:187], v[172:175], v[80:95]
	v_mfma_f32_32x32x16_bf16 v[64:79], v[184:187], v[176:179], v[64:79]
	s_waitcnt lgkmcnt(7)
	v_mfma_f32_32x32x16_bf16 v[48:63], v[188:191], v[172:175], v[48:63]
	v_mfma_f32_32x32x16_bf16 v[32:47], v[188:191], v[176:179], v[32:47]
	s_waitcnt vmcnt(0) lgkmcnt(0)
	s_barrier
	v_add_u32_e32 v128, v234, v200
	s_waitcnt lgkmcnt(6)
	v_mfma_f32_32x32x16_bf16 v[16:31], v[192:195], v[172:175], v[16:31]
	v_mfma_f32_32x32x16_bf16 v[0:15], v[192:195], v[176:179], v[0:15]
	ds_read_b128 v[172:175], v128 offset:16384
	ds_read_b128 v[176:179], v128 offset:18432
	v_add_u32_e32 v128, v235, v200
	ds_read_b128 v[180:183], v128
	ds_read_b128 v[184:187], v128 offset:2048
	ds_read_b128 v[188:191], v128 offset:4096
	ds_read_b128 v[192:195], v128 offset:6144
	s_waitcnt lgkmcnt(9)
	v_mfma_f32_32x32x16_bf16 v[112:127], v[138:141], v[130:133], v[112:127]
	v_mfma_f32_32x32x16_bf16 v[96:111], v[138:141], v[134:137], v[96:111]
	s_waitcnt lgkmcnt(8)
	v_mfma_f32_32x32x16_bf16 v[80:95], v[142:145], v[130:133], v[80:95]
	v_mfma_f32_32x32x16_bf16 v[64:79], v[142:145], v[134:137], v[64:79]
	s_waitcnt lgkmcnt(7)
	v_mfma_f32_32x32x16_bf16 v[48:63], v[146:149], v[130:133], v[48:63]
	v_mfma_f32_32x32x16_bf16 v[32:47], v[146:149], v[134:137], v[32:47]
	s_waitcnt lgkmcnt(6)
	v_mfma_f32_32x32x16_bf16 v[16:31], v[150:153], v[130:133], v[16:31]
	v_mfma_f32_32x32x16_bf16 v[0:15], v[150:153], v[134:137], v[0:15]
	v_add_u32_e32 v128, v234, v201
	ds_read_b128 v[130:133], v128 offset:16384
	ds_read_b128 v[136:139], v128 offset:18432
	v_add_u32_e32 v128, v235, v201
	ds_read_b128 v[140:143], v128
	ds_read_b128 v[144:147], v128 offset:2048
	ds_read_b128 v[148:151], v128 offset:4096
	ds_read_b128 v[240:243], v128 offset:6144
	s_waitcnt lgkmcnt(9)
	v_mfma_f32_32x32x16_bf16 v[112:127], v[180:183], v[172:175], v[112:127]
	v_mfma_f32_32x32x16_bf16 v[96:111], v[180:183], v[176:179], v[96:111]
	s_waitcnt lgkmcnt(8)
	v_mfma_f32_32x32x16_bf16 v[80:95], v[184:187], v[172:175], v[80:95]
	v_mfma_f32_32x32x16_bf16 v[64:79], v[184:187], v[176:179], v[64:79]
	s_waitcnt lgkmcnt(7)
	v_mfma_f32_32x32x16_bf16 v[48:63], v[188:191], v[172:175], v[48:63]
	v_mfma_f32_32x32x16_bf16 v[32:47], v[188:191], v[176:179], v[32:47]
	s_waitcnt lgkmcnt(6)
	v_mfma_f32_32x32x16_bf16 v[16:31], v[192:195], v[172:175], v[16:31]
	v_or_b32_e32 v134, s1, v196
	s_movk_i32 s1, 0x1840
	v_cmp_gt_i32_e32 vcc, s1, v134
	v_mfma_f32_32x32x16_bf16 v[0:15], v[192:195], v[176:179], v[0:15]
	s_waitcnt lgkmcnt(3)
	v_mfma_f32_32x32x16_bf16 v[112:127], v[140:143], v[130:133], v[112:127]
	v_mfma_f32_32x32x16_bf16 v[96:111], v[140:143], v[136:139], v[96:111]
	s_waitcnt lgkmcnt(2)
	v_mfma_f32_32x32x16_bf16 v[80:95], v[144:147], v[130:133], v[80:95]
	v_mfma_f32_32x32x16_bf16 v[64:79], v[144:147], v[136:139], v[64:79]
	s_waitcnt lgkmcnt(1)
	v_mfma_f32_32x32x16_bf16 v[48:63], v[148:151], v[130:133], v[48:63]
	v_mfma_f32_32x32x16_bf16 v[32:47], v[148:151], v[136:139], v[32:47]
	s_waitcnt lgkmcnt(0)
	v_mfma_f32_32x32x16_bf16 v[16:31], v[240:243], v[130:133], v[16:31]
	v_mfma_f32_32x32x16_bf16 v[0:15], v[240:243], v[136:139], v[0:15]
	s_and_saveexec_b64 s[20:21], vcc
	s_cbranch_execz .LBB0_1159
	v_add_u32_e32 v239, s0, v159
	s_movk_i32 s0, 0x7ff
	v_cmp_lt_i32_e32 vcc, s0, v134
	s_and_saveexec_b64 s[0:1], vcc
	s_xor_b64 s[22:23], exec, s[0:1]
	s_cbranch_execz .LBB0_1816
	s_cmpk_lt_u32 s24, 0x1800
	v_or_b32_e32 v130, v134, v197
	s_mov_b64 s[0:1], -1
	s_cbranch_scc0 .LBB0_1302
	v_add_u32_e32 v128, 0xfffff800, v130
	v_lshlrev_b64 v[132:133], 2, v[128:129]
	v_lshl_add_u64 v[134:135], s[16:17], 0, v[132:133]
	v_add_co_u32_e32 v136, vcc, 0x4000, v134
	v_lshl_add_u64 v[132:133], s[18:19], 0, v[132:133]
	s_nop 0
	v_addc_co_u32_e32 v137, vcc, 0, v135, vcc
	v_add_co_u32_e32 v138, vcc, 0x8000, v134
	v_mov_b32_e32 v131, v113
	s_nop 0
	v_addc_co_u32_e32 v139, vcc, 0, v135, vcc
	global_load_dword v188, v[134:135], off
	s_nop 0
	global_load_dword v134, v[136:137], off
	global_load_dword v186, v[138:139], off
	global_load_dword v190, v[132:133], off
	v_ashrrev_i32_e32 v132, 7, v239
	v_ashrrev_i32_e32 v133, 31, v132
	v_lshlrev_b64 v[136:137], 15, v[132:133]
	v_lshl_add_u64 v[178:179], s[2:3], 0, v[136:137]
	v_lshl_add_u64 v[136:137], v[128:129], 1, v[178:179]
	s_and_saveexec_b64 s[0:1], s[6:7]
	s_xor_b64 s[0:1], exec, s[0:1]
	s_cbranch_execz .LBB0_1167
	v_add_co_u32_e32 v138, vcc, 0x4000, v136
	v_cvt_pk_bf16_f32 v131, v30, s0
	s_nop 0
	v_addc_co_u32_e32 v139, vcc, 0, v137, vcc
	global_store_short v[138:139], v131, off
	v_mov_b32_e32 v131, v31

.LBB0_2226:
	s_waitcnt lgkmcnt(0)
	s_nop 0
	v_mfma_f32_32x32x16_bf16 v[112:127], v[150:153], v[142:145], v[112:127]
	v_mfma_f32_32x32x16_bf16 v[96:111], v[150:153], v[130:133], v[96:111]
	s_and_b32 s9, s8, 0x18000
	v_add_u32_e32 v222, s9, v180
	s_add_i32 s9, s8, 0xfffe8000
	s_and_b32 s9, s9, 0x18000
	v_or_b32_e32 v223, s9, v179
	v_add_u32_e32 v233, s9, v176
	s_waitcnt vmcnt(8)
	s_barrier
	v_add_u32_e32 v206, v223, v177
	v_add_u32_e32 v234, v233, v177
	ds_read_b128 v[202:205], v206 offset:16384
	ds_read_b128 v[206:209], v206 offset:18432
	ds_read_b128 v[210:213], v234
	v_mfma_f32_32x32x16_bf16 v[80:95], v[146:149], v[142:145], v[80:95]
	v_readfirstlane_b32 s9, v222
	s_mov_b32 m0, s9
	v_mfma_f32_32x32x16_bf16 v[64:79], v[146:149], v[130:133], v[64:79]
	ds_read_b128 v[214:217], v234 offset:2048
	global_load_lds_dwordx4 v[170:171], off
	v_mfma_f32_32x32x16_bf16 v[48:63], v[138:141], v[142:145], v[48:63]
	s_add_i32 s10, s9, 0x2000
	v_lshl_add_u64 v[150:151], v[170:171], 0, s[12:13]
	s_mov_b32 m0, s10
	v_mfma_f32_32x32x16_bf16 v[32:47], v[138:141], v[130:133], v[32:47]
	ds_read_b128 v[224:227], v234 offset:4096
	global_load_lds_dwordx4 v[150:151], off
	v_mfma_f32_32x32x16_bf16 v[16:31], v[134:137], v[142:145], v[16:31]
	v_mfma_f32_32x32x16_bf16 v[0:15], v[134:137], v[130:133], v[0:15]
	ds_read_b128 v[234:237], v234 offset:6144
	s_waitcnt lgkmcnt(3)
	v_mfma_f32_32x32x16_bf16 v[112:127], v[210:213], v[202:205], v[112:127]
	v_add_u32_e32 v130, v223, v178
	v_add_u32_e32 v134, v233, v178
	ds_read_b128 v[142:145], v130 offset:16384
	s_add_i32 s10, s9, 0x6000
	s_addk_i32 s9, 0x4000
	s_mov_b32 m0, s9
	v_mfma_f32_32x32x16_bf16 v[96:111], v[210:213], v[206:209], v[96:111]
	ds_read_b128 v[130:133], v130 offset:18432
	global_load_lds_dwordx4 v[172:173], off
	s_waitcnt lgkmcnt(4)
	v_mfma_f32_32x32x16_bf16 v[80:95], v[214:217], v[202:205], v[80:95]
	ds_read_b128 v[150:153], v134
	v_mfma_f32_32x32x16_bf16 v[64:79], v[214:217], v[206:209], v[64:79]
	ds_read_b128 v[146:149], v134 offset:2048
	s_waitcnt lgkmcnt(5)
	v_mfma_f32_32x32x16_bf16 v[48:63], v[224:227], v[202:205], v[48:63]
	ds_read_b128 v[138:141], v134 offset:4096
	v_lshl_add_u64 v[222:223], v[172:173], 0, s[12:13]
	s_mov_b32 m0, s10
	v_mfma_f32_32x32x16_bf16 v[32:47], v[224:227], v[206:209], v[32:47]
	ds_read_b128 v[134:137], v134 offset:6144
	global_load_lds_dwordx4 v[222:223], off
	s_waitcnt lgkmcnt(6)
	v_mfma_f32_32x32x16_bf16 v[16:31], v[234:237], v[202:205], v[16:31]
	s_add_i32 s8, s8, 0x8000
	v_lshl_add_u64 v[170:171], v[170:171], 0, 64
	v_lshl_add_u64 v[172:173], v[172:173], 0, 64
	s_cmp_eq_u32 s8, 0x200000
	v_mfma_f32_32x32x16_bf16 v[0:15], v[234:237], v[206:209], v[0:15]
	s_cbranch_scc0 .LBB0_2226
	s_waitcnt vmcnt(8) lgkmcnt(0)
	s_barrier
	v_add_u32_e32 v202, v179, v177
	v_add_u32_e32 v222, v176, v177
	ds_read_b128 v[170:173], v202 offset:49152
	ds_read_b128 v[202:205], v202 offset:51200
	ds_read_b128 v[206:209], v222 offset:32768
	ds_read_b128 v[210:213], v222 offset:34816
	ds_read_b128 v[214:217], v222 offset:36864
	ds_read_b128 v[224:227], v222 offset:38912
	s_waitcnt lgkmcnt(9)
	v_mfma_f32_32x32x16_bf16 v[112:127], v[150:153], v[142:145], v[112:127]
	v_mfma_f32_32x32x16_bf16 v[96:111], v[150:153], v[130:133], v[96:111]
	s_waitcnt lgkmcnt(8)
	v_mfma_f32_32x32x16_bf16 v[80:95], v[146:149], v[142:145], v[80:95]
	v_mfma_f32_32x32x16_bf16 v[64:79], v[146:149], v[130:133], v[64:79]
	s_waitcnt lgkmcnt(7)
	v_mfma_f32_32x32x16_bf16 v[48:63], v[138:141], v[142:145], v[48:63]
	v_mfma_f32_32x32x16_bf16 v[32:47], v[138:141], v[130:133], v[32:47]
	s_waitcnt lgkmcnt(6)
	v_mfma_f32_32x32x16_bf16 v[16:31], v[134:137], v[142:145], v[16:31]
	v_mfma_f32_32x32x16_bf16 v[0:15], v[134:137], v[130:133], v[0:15]
	v_add_u32_e32 v134, v179, v178
	v_add_u32_e32 v150, v176, v178
	ds_read_b128 v[130:133], v134 offset:49152
	ds_read_b128 v[134:137], v134 offset:51200
	ds_read_b128 v[138:141], v150 offset:32768
	ds_read_b128 v[142:145], v150 offset:34816
	ds_read_b128 v[146:149], v150 offset:36864
	ds_read_b128 v[150:153], v150 offset:38912
	s_waitcnt lgkmcnt(9)
	v_mfma_f32_32x32x16_bf16 v[112:127], v[206:209], v[170:173], v[112:127]
	v_mfma_f32_32x32x16_bf16 v[96:111], v[206:209], v[202:205], v[96:111]
	s_waitcnt lgkmcnt(8)
	v_mfma_f32_32x32x16_bf16 v[80:95], v[210:213], v[170:173], v[80:95]
	v_mfma_f32_32x32x16_bf16 v[64:79], v[210:213], v[202:205], v[64:79]
	s_waitcnt lgkmcnt(7)
	v_mfma_f32_32x32x16_bf16 v[48:63], v[214:217], v[170:173], v[48:63]
	v_mfma_f32_32x32x16_bf16 v[32:47], v[214:217], v[202:205], v[32:47]
	s_waitcnt lgkmcnt(6)
	v_mfma_f32_32x32x16_bf16 v[0:15], v[224:227], v[202:205], v[0:15]
	s_waitcnt vmcnt(4) lgkmcnt(0)
	s_barrier
	v_add_u32_e32 v202, v199, v177
	v_add_u32_e32 v222, v200, v177
	v_mfma_f32_32x32x16_bf16 v[16:31], v[224:227], v[170:173], v[16:31]
	ds_read_b128 v[170:173], v202 offset:16384
	ds_read_b128 v[202:205], v202 offset:18432
	ds_read_b128 v[206:209], v222
	ds_read_b128 v[210:213], v222 offset:2048
	ds_read_b128 v[214:217], v222 offset:4096
	ds_read_b128 v[224:227], v222 offset:6144
	s_waitcnt lgkmcnt(9)
	v_mfma_f32_32x32x16_bf16 v[112:127], v[138:141], v[130:133], v[112:127]
	v_mfma_f32_32x32x16_bf16 v[96:111], v[138:141], v[134:137], v[96:111]
	s_waitcnt lgkmcnt(8)
	v_mfma_f32_32x32x16_bf16 v[80:95], v[142:145], v[130:133], v[80:95]
	v_mfma_f32_32x32x16_bf16 v[64:79], v[142:145], v[134:137], v[64:79]
	s_waitcnt lgkmcnt(7)
	v_mfma_f32_32x32x16_bf16 v[48:63], v[146:149], v[130:133], v[48:63]
	v_mfma_f32_32x32x16_bf16 v[32:47], v[146:149], v[134:137], v[32:47]
	s_waitcnt lgkmcnt(6)
	v_mfma_f32_32x32x16_bf16 v[16:31], v[150:153], v[130:133], v[16:31]
	v_mfma_f32_32x32x16_bf16 v[0:15], v[150:153], v[134:137], v[0:15]
	v_add_u32_e32 v134, v199, v178
	v_add_u32_e32 v150, v200, v178
	ds_read_b128 v[130:133], v134 offset:16384
	ds_read_b128 v[134:137], v134 offset:18432
	ds_read_b128 v[138:141], v150
	ds_read_b128 v[142:145], v150 offset:2048
	ds_read_b128 v[146:149], v150 offset:4096
	ds_read_b128 v[150:153], v150 offset:6144
	s_waitcnt lgkmcnt(9)
	v_mfma_f32_32x32x16_bf16 v[112:127], v[206:209], v[170:173], v[112:127]
	v_mfma_f32_32x32x16_bf16 v[96:111], v[206:209], v[202:205], v[96:111]
	s_waitcnt lgkmcnt(8)
	v_mfma_f32_32x32x16_bf16 v[80:95], v[210:213], v[170:173], v[80:95]
	v_mfma_f32_32x32x16_bf16 v[64:79], v[210:213], v[202:205], v[64:79]
	s_waitcnt lgkmcnt(7)
	v_mfma_f32_32x32x16_bf16 v[48:63], v[214:217], v[170:173], v[48:63]
	v_mfma_f32_32x32x16_bf16 v[32:47], v[214:217], v[202:205], v[32:47]
	s_waitcnt lgkmcnt(6)
	v_mfma_f32_32x32x16_bf16 v[0:15], v[224:227], v[202:205], v[0:15]
	s_waitcnt vmcnt(0) lgkmcnt(0)
	s_barrier
	v_add_u32_e32 v202, v197, v177
	v_add_u32_e32 v222, v198, v177
	v_mfma_f32_32x32x16_bf16 v[16:31], v[224:227], v[170:173], v[16:31]
	ds_read_b128 v[170:173], v202 offset:16384
	ds_read_b128 v[202:205], v202 offset:18432
	ds_read_b128 v[206:209], v222
	ds_read_b128 v[210:213], v222 offset:2048
	ds_read_b128 v[214:217], v222 offset:4096
	ds_read_b128 v[224:227], v222 offset:6144
	s_waitcnt lgkmcnt(9)
	v_mfma_f32_32x32x16_bf16 v[112:127], v[138:141], v[130:133], v[112:127]
	v_mfma_f32_32x32x16_bf16 v[96:111], v[138:141], v[134:137], v[96:111]
	s_waitcnt lgkmcnt(8)
	v_mfma_f32_32x32x16_bf16 v[80:95], v[142:145], v[130:133], v[80:95]
	v_mfma_f32_32x32x16_bf16 v[64:79], v[142:145], v[134:137], v[64:79]
	s_waitcnt lgkmcnt(7)
	v_mfma_f32_32x32x16_bf16 v[48:63], v[146:149], v[130:133], v[48:63]
	v_mfma_f32_32x32x16_bf16 v[32:47], v[146:149], v[134:137], v[32:47]
	s_waitcnt lgkmcnt(6)
	v_mfma_f32_32x32x16_bf16 v[16:31], v[150:153], v[130:133], v[16:31]
	v_mfma_f32_32x32x16_bf16 v[0:15], v[150:153], v[134:137], v[0:15]
	v_add_u32_e32 v134, v197, v178
	v_add_u32_e32 v150, v198, v178
	ds_read_b128 v[130:133], v134 offset:16384
	ds_read_b128 v[134:137], v134 offset:18432
	ds_read_b128 v[138:141], v150
	ds_read_b128 v[142:145], v150 offset:2048
	ds_read_b128 v[146:149], v150 offset:4096
	ds_read_b128 v[150:153], v150 offset:6144
	s_waitcnt lgkmcnt(9)
	v_mfma_f32_32x32x16_bf16 v[112:127], v[206:209], v[170:173], v[112:127]
	v_mfma_f32_32x32x16_bf16 v[96:111], v[206:209], v[202:205], v[96:111]
	s_waitcnt lgkmcnt(8)
	v_mfma_f32_32x32x16_bf16 v[80:95], v[210:213], v[170:173], v[80:95]
	v_mfma_f32_32x32x16_bf16 v[64:79], v[210:213], v[202:205], v[64:79]
	s_waitcnt lgkmcnt(7)
	v_mfma_f32_32x32x16_bf16 v[48:63], v[214:217], v[170:173], v[48:63]
	v_mfma_f32_32x32x16_bf16 v[32:47], v[214:217], v[202:205], v[32:47]
	s_waitcnt lgkmcnt(6)
	v_mfma_f32_32x32x16_bf16 v[16:31], v[224:227], v[170:173], v[16:31]
	v_mfma_f32_32x32x16_bf16 v[0:15], v[224:227], v[202:205], v[0:15]
	s_waitcnt lgkmcnt(3)
	v_mfma_f32_32x32x16_bf16 v[112:127], v[138:141], v[130:133], v[112:127]
	s_waitcnt lgkmcnt(2)
	v_mfma_f32_32x32x16_bf16 v[80:95], v[142:145], v[130:133], v[80:95]
	s_waitcnt lgkmcnt(1)
	v_mfma_f32_32x32x16_bf16 v[48:63], v[146:149], v[130:133], v[48:63]
	s_waitcnt lgkmcnt(0)
	v_mfma_f32_32x32x16_bf16 v[16:31], v[150:153], v[130:133], v[16:31]
	v_add_u32_e32 v132, s6, v174
	v_or_b32_e32 v130, s7, v128
	v_ashrrev_i32_e32 v131, 31, v130
	v_lshl_add_u64 v[130:131], v[130:131], 1, v[158:159]
	v_readlane_b32 s6, v252, 7
	s_add_i32 s4, s4, s6
	s_add_i32 s2, s2, s6
	v_mfma_f32_32x32x16_bf16 v[96:111], v[138:141], v[134:137], v[96:111]
	v_or_b32_e32 v138, v132, v181
	v_ashrrev_i32_e32 v139, 31, v138
	v_readlane_b32 s6, v252, 8
	s_add_i32 s5, s5, s6
	s_cmp_gt_i32 s4, 31
	v_mfma_f32_32x32x16_bf16 v[64:79], v[142:145], v[134:137], v[64:79]
	v_mfma_f32_32x32x16_bf16 v[32:47], v[146:149], v[134:137], v[32:47]
	v_mfma_f32_32x32x16_bf16 v[0:15], v[150:153], v[134:137], v[0:15]
	v_and_b32_e32 v134, 0xff, v138
	v_lshl_add_u32 v134, v134, 2, v250
	ds_read_b96 v[134:136], v134
	v_lshlrev_b64 v[138:139], 11, v[138:139]
	v_lshl_add_u64 v[138:139], v[130:131], 0, v[138:139]
	s_waitcnt lgkmcnt(0)
	v_mul_f32_e32 v112, v112, v134
	v_mul_f32_e32 v96, v96, v134
	v_cvt_pk_bf16_f32 v112, v112, s0
	v_cvt_pk_bf16_f32 v96, v96, s0
	global_store_short v[138:139], v112, off
	global_store_short v[138:139], v96, off offset:64
	v_or_b32_e32 v138, v132, v182
	v_ashrrev_i32_e32 v139, 31, v138
	v_lshlrev_b64 v[138:139], 11, v[138:139]
	v_mul_f32_e32 v96, v113, v135
	v_lshl_add_u64 v[138:139], v[130:131], 0, v[138:139]
	v_cvt_pk_bf16_f32 v96, v96, s0
	global_store_short v[138:139], v96, off
	v_mul_f32_e32 v96, v97, v135
	v_cvt_pk_bf16_f32 v96, v96, s0
	global_store_short v[138:139], v96, off offset:64
	v_or_b32_e32 v96, v132, v183
	v_ashrrev_i32_e32 v97, 31, v96
	v_lshlrev_b64 v[96:97], 11, v[96:97]
	v_mul_f32_e32 v112, v114, v136
	v_mul_f32_e32 v98, v98, v136
	v_lshl_add_u64 v[96:97], v[130:131], 0, v[96:97]
	v_cvt_pk_bf16_f32 v112, v112, s0
	v_cvt_pk_bf16_f32 v98, v98, s0
	global_store_short v[96:97], v112, off
	global_store_short v[96:97], v98, off offset:64
	v_or_b32_e32 v96, v132, v184
	v_ashrrev_i32_e32 v97, 31, v96
	v_and_b32_e32 v112, 0xff, v96
	v_lshl_add_u32 v112, v112, 2, v250
	ds_read_b32 v98, v112
	v_lshlrev_b64 v[96:97], 11, v[96:97]
	v_lshl_add_u64 v[96:97], v[130:131], 0, v[96:97]
	s_waitcnt lgkmcnt(0)
	v_mul_f32_e32 v112, v115, v98
	v_cvt_pk_bf16_f32 v112, v112, s0
	global_store_short v[96:97], v112, off
	v_mul_f32_e32 v98, v99, v98
	v_or_b32_e32 v112, v132, v185
	v_cvt_pk_bf16_f32 v98, v98, s0
	v_ashrrev_i32_e32 v113, 31, v112
	global_store_short v[96:97], v98, off offset:64
	v_and_b32_e32 v96, 0xff, v112
	v_lshl_add_u32 v96, v96, 2, v250
	ds_read_b96 v[96:98], v96
	v_lshlrev_b64 v[112:113], 11, v[112:113]
	v_lshl_add_u64 v[112:113], v[130:131], 0, v[112:113]
	s_waitcnt lgkmcnt(0)
	v_mul_f32_e32 v99, v116, v96
	v_mul_f32_e32 v96, v100, v96
	v_cvt_pk_bf16_f32 v99, v99, s0
	v_cvt_pk_bf16_f32 v96, v96, s0
	global_store_short v[112:113], v99, off
	global_store_short v[112:113], v96, off offset:64
	v_or_b32_e32 v112, v132, v186
	v_ashrrev_i32_e32 v113, 31, v112
	v_lshlrev_b64 v[112:113], 11, v[112:113]
	v_mul_f32_e32 v96, v117, v97
	v_lshl_add_u64 v[112:113], v[130:131], 0, v[112:113]
	v_cvt_pk_bf16_f32 v96, v96, s0
	global_store_short v[112:113], v96, off
	v_mul_f32_e32 v96, v101, v97
	v_cvt_pk_bf16_f32 v96, v96, s0
	global_store_short v[112:113], v96, off offset:64
	v_or_b32_e32 v96, v132, v187
	v_ashrrev_i32_e32 v97, 31, v96
	v_lshlrev_b64 v[96:97], 11, v[96:97]
	v_mul_f32_e32 v99, v118, v98
	v_mul_f32_e32 v98, v102, v98
	v_lshl_add_u64 v[96:97], v[130:131], 0, v[96:97]
	v_cvt_pk_bf16_f32 v99, v99, s0
	v_cvt_pk_bf16_f32 v98, v98, s0
	global_store_short v[96:97], v99, off
	global_store_short v[96:97], v98, off offset:64
	v_or_b32_e32 v96, v132, v188
	v_ashrrev_i32_e32 v97, 31, v96
	v_and_b32_e32 v98, 0xff, v96
	v_lshl_add_u32 v98, v98, 2, v250
	ds_read_b32 v98, v98
	v_lshlrev_b64 v[96:97], 11, v[96:97]
	v_or_b32_e32 v100, v132, v189
	v_lshl_add_u64 v[96:97], v[130:131], 0, v[96:97]
	v_ashrrev_i32_e32 v101, 31, v100
	s_waitcnt lgkmcnt(0)
	v_mul_f32_e32 v99, v119, v98
	v_mul_f32_e32 v98, v103, v98
	v_cvt_pk_bf16_f32 v99, v99, s0
	v_cvt_pk_bf16_f32 v98, v98, s0
	global_store_short v[96:97], v99, off
	global_store_short v[96:97], v98, off offset:64
	v_and_b32_e32 v96, 0xff, v100
	v_lshl_add_u32 v96, v96, 2, v250
	ds_read_b96 v[96:98], v96
	v_lshlrev_b64 v[100:101], 11, v[100:101]
	v_lshl_add_u64 v[100:101], v[130:131], 0, v[100:101]
	s_waitcnt lgkmcnt(0)
	v_mul_f32_e32 v99, v120, v96
	v_mul_f32_e32 v96, v104, v96
	v_cvt_pk_bf16_f32 v99, v99, s0
	v_cvt_pk_bf16_f32 v96, v96, s0
	global_store_short v[100:101], v99, off
	global_store_short v[100:101], v96, off offset:64
	v_or_b32_e32 v100, v132, v190
	v_ashrrev_i32_e32 v101, 31, v100
	v_lshlrev_b64 v[100:101], 11, v[100:101]
	v_mul_f32_e32 v96, v121, v97
	v_lshl_add_u64 v[100:101], v[130:131], 0, v[100:101]
	v_cvt_pk_bf16_f32 v96, v96, s0
	global_store_short v[100:101], v96, off
	v_mul_f32_e32 v96, v105, v97
	v_cvt_pk_bf16_f32 v96, v96, s0
	global_store_short v[100:101], v96, off offset:64
	v_or_b32_e32 v96, v132, v191
	v_ashrrev_i32_e32 v97, 31, v96
	v_lshlrev_b64 v[96:97], 11, v[96:97]
	v_mul_f32_e32 v99, v122, v98
	v_mul_f32_e32 v98, v106, v98
	v_lshl_add_u64 v[96:97], v[130:131], 0, v[96:97]
	v_cvt_pk_bf16_f32 v99, v99, s0
	v_cvt_pk_bf16_f32 v98, v98, s0
	global_store_short v[96:97], v99, off
	global_store_short v[96:97], v98, off offset:64
	v_or_b32_e32 v96, v132, v192
	v_ashrrev_i32_e32 v97, 31, v96
	v_and_b32_e32 v98, 0xff, v96
	v_lshl_add_u32 v98, v98, 2, v250
	ds_read_b32 v98, v98
	v_lshlrev_b64 v[96:97], 11, v[96:97]
	v_or_b32_e32 v100, v132, v193
	v_lshl_add_u64 v[96:97], v[130:131], 0, v[96:97]
	v_ashrrev_i32_e32 v101, 31, v100
	s_waitcnt lgkmcnt(0)
	v_mul_f32_e32 v99, v123, v98
	v_mul_f32_e32 v98, v107, v98
	v_cvt_pk_bf16_f32 v99, v99, s0
	v_cvt_pk_bf16_f32 v98, v98, s0
	global_store_short v[96:97], v99, off
	global_store_short v[96:97], v98, off offset:64
	v_and_b32_e32 v96, 0xff, v100
	v_lshl_add_u32 v96, v96, 2, v250
	ds_read_b96 v[96:98], v96
	v_lshlrev_b64 v[100:101], 11, v[100:101]
	v_lshl_add_u64 v[100:101], v[130:131], 0, v[100:101]
	s_waitcnt lgkmcnt(0)
	v_mul_f32_e32 v99, v124, v96
	v_mul_f32_e32 v96, v108, v96
	v_cvt_pk_bf16_f32 v99, v99, s0
	v_cvt_pk_bf16_f32 v96, v96, s0
	global_store_short v[100:101], v99, off
	global_store_short v[100:101], v96, off offset:64
	v_or_b32_e32 v100, v132, v194
	v_ashrrev_i32_e32 v101, 31, v100
	v_lshlrev_b64 v[100:101], 11, v[100:101]
	v_mul_f32_e32 v96, v125, v97
	v_lshl_add_u64 v[100:101], v[130:131], 0, v[100:101]
	v_cvt_pk_bf16_f32 v96, v96, s0
	global_store_short v[100:101], v96, off
	v_mul_f32_e32 v96, v109, v97
	v_cvt_pk_bf16_f32 v96, v96, s0
	global_store_short v[100:101], v96, off offset:64
	v_or_b32_e32 v96, v132, v195
	v_ashrrev_i32_e32 v97, 31, v96
	v_lshlrev_b64 v[96:97], 11, v[96:97]
	v_mul_f32_e32 v99, v126, v98
	v_mul_f32_e32 v98, v110, v98
	v_lshl_add_u64 v[96:97], v[130:131], 0, v[96:97]
	v_cvt_pk_bf16_f32 v99, v99, s0
	v_cvt_pk_bf16_f32 v98, v98, s0
	global_store_short v[96:97], v99, off
	global_store_short v[96:97], v98, off offset:64
	v_or_b32_e32 v96, v132, v196
	v_ashrrev_i32_e32 v97, 31, v96
	v_and_b32_e32 v98, 0xff, v96
	v_lshl_add_u32 v98, v98, 2, v250
	ds_read_b32 v98, v98
	v_lshlrev_b64 v[96:97], 11, v[96:97]
	v_lshl_add_u64 v[96:97], v[130:131], 0, v[96:97]
	s_waitcnt lgkmcnt(0)
	v_mul_f32_e32 v99, v127, v98
	v_mul_f32_e32 v98, v111, v98
	v_cvt_pk_bf16_f32 v99, v99, s0
	v_cvt_pk_bf16_f32 v98, v98, s0
	global_store_short v[96:97], v99, off
	global_store_short v[96:97], v98, off offset:64
	v_or_b32_e32 v96, 32, v132
	v_or_b32_e32 v102, v96, v181
	v_ashrrev_i32_e32 v103, 31, v102
	v_and_b32_e32 v98, 0xff, v102
	v_lshl_add_u32 v98, v98, 2, v250
	ds_read_b96 v[98:100], v98
	v_lshlrev_b64 v[102:103], 11, v[102:103]
	v_lshl_add_u64 v[102:103], v[130:131], 0, v[102:103]
	s_waitcnt lgkmcnt(0)
	v_mul_f32_e32 v80, v80, v98
	v_mul_f32_e32 v64, v64, v98
	v_cvt_pk_bf16_f32 v80, v80, s0
	v_cvt_pk_bf16_f32 v64, v64, s0
	global_store_short v[102:103], v80, off
	global_store_short v[102:103], v64, off offset:64
	v_or_b32_e32 v102, v96, v182
	v_ashrrev_i32_e32 v103, 31, v102
	v_lshlrev_b64 v[102:103], 11, v[102:103]
	v_mul_f32_e32 v64, v81, v99
	v_lshl_add_u64 v[102:103], v[130:131], 0, v[102:103]
	v_cvt_pk_bf16_f32 v64, v64, s0
	global_store_short v[102:103], v64, off
	v_mul_f32_e32 v64, v65, v99
	v_cvt_pk_bf16_f32 v64, v64, s0
	global_store_short v[102:103], v64, off offset:64
	v_or_b32_e32 v64, v96, v183
	v_ashrrev_i32_e32 v65, 31, v64
	v_lshlrev_b64 v[64:65], 11, v[64:65]
	v_mul_f32_e32 v80, v82, v100
	v_mul_f32_e32 v66, v66, v100
	v_lshl_add_u64 v[64:65], v[130:131], 0, v[64:65]
	v_cvt_pk_bf16_f32 v80, v80, s0
	v_cvt_pk_bf16_f32 v66, v66, s0
	global_store_short v[64:65], v80, off
	global_store_short v[64:65], v66, off offset:64
	v_or_b32_e32 v64, v96, v184
	v_ashrrev_i32_e32 v65, 31, v64
	v_and_b32_e32 v80, 0xff, v64
	v_lshl_add_u32 v80, v80, 2, v250
	ds_read_b32 v66, v80
	v_lshlrev_b64 v[64:65], 11, v[64:65]
	v_lshl_add_u64 v[64:65], v[130:131], 0, v[64:65]
	s_waitcnt lgkmcnt(0)
	v_mul_f32_e32 v80, v83, v66
	v_cvt_pk_bf16_f32 v80, v80, s0
	global_store_short v[64:65], v80, off
	v_mul_f32_e32 v66, v67, v66
	v_or_b32_e32 v80, v96, v185
	v_cvt_pk_bf16_f32 v66, v66, s0
	v_ashrrev_i32_e32 v81, 31, v80
	global_store_short v[64:65], v66, off offset:64
	v_and_b32_e32 v64, 0xff, v80
	v_lshl_add_u32 v64, v64, 2, v250
	ds_read_b96 v[64:66], v64
	v_lshlrev_b64 v[80:81], 11, v[80:81]
	v_lshl_add_u64 v[80:81], v[130:131], 0, v[80:81]
	s_waitcnt lgkmcnt(0)
	v_mul_f32_e32 v67, v84, v64
	v_mul_f32_e32 v64, v68, v64
	v_cvt_pk_bf16_f32 v67, v67, s0
	v_cvt_pk_bf16_f32 v64, v64, s0
	global_store_short v[80:81], v67, off
	global_store_short v[80:81], v64, off offset:64
	v_or_b32_e32 v80, v96, v186
	v_ashrrev_i32_e32 v81, 31, v80
	v_lshlrev_b64 v[80:81], 11, v[80:81]
	v_mul_f32_e32 v64, v85, v65
	v_lshl_add_u64 v[80:81], v[130:131], 0, v[80:81]
	v_cvt_pk_bf16_f32 v64, v64, s0
	global_store_short v[80:81], v64, off
	v_mul_f32_e32 v64, v69, v65
	v_cvt_pk_bf16_f32 v64, v64, s0
	global_store_short v[80:81], v64, off offset:64
	v_or_b32_e32 v64, v96, v187
	v_ashrrev_i32_e32 v65, 31, v64
	v_lshlrev_b64 v[64:65], 11, v[64:65]
	v_mul_f32_e32 v67, v86, v66
	v_mul_f32_e32 v66, v70, v66
	v_lshl_add_u64 v[64:65], v[130:131], 0, v[64:65]
	v_cvt_pk_bf16_f32 v67, v67, s0
	v_cvt_pk_bf16_f32 v66, v66, s0
	global_store_short v[64:65], v67, off
	global_store_short v[64:65], v66, off offset:64
	v_or_b32_e32 v64, v96, v188
	v_ashrrev_i32_e32 v65, 31, v64
	v_and_b32_e32 v66, 0xff, v64
	v_lshl_add_u32 v66, v66, 2, v250
	ds_read_b32 v66, v66
	v_lshlrev_b64 v[64:65], 11, v[64:65]
	v_or_b32_e32 v68, v96, v189
	v_lshl_add_u64 v[64:65], v[130:131], 0, v[64:65]
	v_ashrrev_i32_e32 v69, 31, v68
	s_waitcnt lgkmcnt(0)
	v_mul_f32_e32 v67, v87, v66
	v_mul_f32_e32 v66, v71, v66
	v_cvt_pk_bf16_f32 v67, v67, s0
	v_cvt_pk_bf16_f32 v66, v66, s0
	global_store_short v[64:65], v67, off
	global_store_short v[64:65], v66, off offset:64
	v_and_b32_e32 v64, 0xff, v68
	v_lshl_add_u32 v64, v64, 2, v250
	ds_read_b96 v[64:66], v64
	v_lshlrev_b64 v[68:69], 11, v[68:69]
	v_lshl_add_u64 v[68:69], v[130:131], 0, v[68:69]
	s_waitcnt lgkmcnt(0)
	v_mul_f32_e32 v67, v88, v64
	v_mul_f32_e32 v64, v72, v64
	v_cvt_pk_bf16_f32 v67, v67, s0
	v_cvt_pk_bf16_f32 v64, v64, s0
	global_store_short v[68:69], v67, off
	global_store_short v[68:69], v64, off offset:64
	v_or_b32_e32 v68, v96, v190
	v_ashrrev_i32_e32 v69, 31, v68
	v_lshlrev_b64 v[68:69], 11, v[68:69]
	v_mul_f32_e32 v64, v89, v65
	v_lshl_add_u64 v[68:69], v[130:131], 0, v[68:69]
	v_cvt_pk_bf16_f32 v64, v64, s0
	global_store_short v[68:69], v64, off
	v_mul_f32_e32 v64, v73, v65
	v_cvt_pk_bf16_f32 v64, v64, s0
	global_store_short v[68:69], v64, off offset:64
	v_or_b32_e32 v64, v96, v191
	v_ashrrev_i32_e32 v65, 31, v64
	v_lshlrev_b64 v[64:65], 11, v[64:65]
	v_mul_f32_e32 v67, v90, v66
	v_mul_f32_e32 v66, v74, v66
	v_lshl_add_u64 v[64:65], v[130:131], 0, v[64:65]
	v_cvt_pk_bf16_f32 v67, v67, s0
	v_cvt_pk_bf16_f32 v66, v66, s0
	global_store_short v[64:65], v67, off
	global_store_short v[64:65], v66, off offset:64
	v_or_b32_e32 v64, v96, v192
	v_ashrrev_i32_e32 v65, 31, v64
	v_and_b32_e32 v66, 0xff, v64
	v_lshl_add_u32 v66, v66, 2, v250
	ds_read_b32 v66, v66
	v_lshlrev_b64 v[64:65], 11, v[64:65]
	v_or_b32_e32 v68, v96, v193
	v_lshl_add_u64 v[64:65], v[130:131], 0, v[64:65]
	v_ashrrev_i32_e32 v69, 31, v68
	s_waitcnt lgkmcnt(0)
	v_mul_f32_e32 v67, v91, v66
	v_mul_f32_e32 v66, v75, v66
	v_cvt_pk_bf16_f32 v67, v67, s0
	v_cvt_pk_bf16_f32 v66, v66, s0
	global_store_short v[64:65], v67, off
	global_store_short v[64:65], v66, off offset:64
	v_and_b32_e32 v64, 0xff, v68
	v_lshl_add_u32 v64, v64, 2, v250
	ds_read_b96 v[64:66], v64
	v_lshlrev_b64 v[68:69], 11, v[68:69]
	v_lshl_add_u64 v[68:69], v[130:131], 0, v[68:69]
	s_waitcnt lgkmcnt(0)
	v_mul_f32_e32 v67, v92, v64
	v_mul_f32_e32 v64, v76, v64
	v_cvt_pk_bf16_f32 v67, v67, s0
	v_cvt_pk_bf16_f32 v64, v64, s0
	global_store_short v[68:69], v67, off
	global_store_short v[68:69], v64, off offset:64
	v_or_b32_e32 v68, v96, v194
	v_ashrrev_i32_e32 v69, 31, v68
	v_lshlrev_b64 v[68:69], 11, v[68:69]
	v_mul_f32_e32 v64, v93, v65
	v_lshl_add_u64 v[68:69], v[130:131], 0, v[68:69]
	v_cvt_pk_bf16_f32 v64, v64, s0
	global_store_short v[68:69], v64, off
	v_mul_f32_e32 v64, v77, v65
	v_cvt_pk_bf16_f32 v64, v64, s0
	global_store_short v[68:69], v64, off offset:64
	v_or_b32_e32 v64, v96, v195
	v_ashrrev_i32_e32 v65, 31, v64
	v_lshlrev_b64 v[64:65], 11, v[64:65]
	v_mul_f32_e32 v67, v94, v66
	v_mul_f32_e32 v66, v78, v66
	v_lshl_add_u64 v[64:65], v[130:131], 0, v[64:65]
	v_cvt_pk_bf16_f32 v67, v67, s0
	v_cvt_pk_bf16_f32 v66, v66, s0
	global_store_short v[64:65], v67, off
	global_store_short v[64:65], v66, off offset:64
	v_or_b32_e32 v64, v96, v196
	v_ashrrev_i32_e32 v65, 31, v64
	v_and_b32_e32 v66, 0xff, v64
	v_lshl_add_u32 v66, v66, 2, v250
	ds_read_b32 v66, v66
	v_lshlrev_b64 v[64:65], 11, v[64:65]
	v_lshl_add_u64 v[64:65], v[130:131], 0, v[64:65]
	s_waitcnt lgkmcnt(0)
	v_mul_f32_e32 v67, v95, v66
	v_mul_f32_e32 v66, v79, v66
	v_cvt_pk_bf16_f32 v67, v67, s0
	v_cvt_pk_bf16_f32 v66, v66, s0
	global_store_short v[64:65], v67, off
	global_store_short v[64:65], v66, off offset:64
	v_or_b32_e32 v64, 64, v132
	v_or_b32_e32 v70, v64, v181
	v_ashrrev_i32_e32 v71, 31, v70
	v_and_b32_e32 v66, 0xff, v70
	v_lshl_add_u32 v66, v66, 2, v250
	ds_read_b96 v[66:68], v66
	v_lshlrev_b64 v[70:71], 11, v[70:71]
	v_lshl_add_u64 v[70:71], v[130:131], 0, v[70:71]
	s_waitcnt lgkmcnt(0)
	v_mul_f32_e32 v48, v48, v66
	v_mul_f32_e32 v32, v32, v66
	v_cvt_pk_bf16_f32 v48, v48, s0
	v_cvt_pk_bf16_f32 v32, v32, s0
	global_store_short v[70:71], v48, off
	global_store_short v[70:71], v32, off offset:64
	v_or_b32_e32 v70, v64, v182
	v_ashrrev_i32_e32 v71, 31, v70
	v_lshlrev_b64 v[70:71], 11, v[70:71]
	v_mul_f32_e32 v32, v49, v67
	v_lshl_add_u64 v[70:71], v[130:131], 0, v[70:71]
	v_cvt_pk_bf16_f32 v32, v32, s0
	global_store_short v[70:71], v32, off
	v_mul_f32_e32 v32, v33, v67
	v_cvt_pk_bf16_f32 v32, v32, s0
	global_store_short v[70:71], v32, off offset:64
	v_or_b32_e32 v32, v64, v183
	v_ashrrev_i32_e32 v33, 31, v32
	v_lshlrev_b64 v[32:33], 11, v[32:33]
	v_mul_f32_e32 v48, v50, v68
	v_mul_f32_e32 v34, v34, v68
	v_lshl_add_u64 v[32:33], v[130:131], 0, v[32:33]
	v_cvt_pk_bf16_f32 v48, v48, s0
	v_cvt_pk_bf16_f32 v34, v34, s0
	global_store_short v[32:33], v48, off
	global_store_short v[32:33], v34, off offset:64
	v_or_b32_e32 v32, v64, v184
	v_ashrrev_i32_e32 v33, 31, v32
	v_and_b32_e32 v48, 0xff, v32
	v_lshl_add_u32 v48, v48, 2, v250
	ds_read_b32 v34, v48
	v_lshlrev_b64 v[32:33], 11, v[32:33]
	v_lshl_add_u64 v[32:33], v[130:131], 0, v[32:33]
	s_waitcnt lgkmcnt(0)
	v_mul_f32_e32 v48, v51, v34
	v_cvt_pk_bf16_f32 v48, v48, s0
	global_store_short v[32:33], v48, off
	v_mul_f32_e32 v34, v35, v34
	v_or_b32_e32 v48, v64, v185
	v_cvt_pk_bf16_f32 v34, v34, s0
	v_ashrrev_i32_e32 v49, 31, v48
	global_store_short v[32:33], v34, off offset:64
	v_and_b32_e32 v32, 0xff, v48
	v_lshl_add_u32 v32, v32, 2, v250
	ds_read_b96 v[32:34], v32
	v_lshlrev_b64 v[48:49], 11, v[48:49]
	v_lshl_add_u64 v[48:49], v[130:131], 0, v[48:49]
	s_waitcnt lgkmcnt(0)
	v_mul_f32_e32 v35, v52, v32
	v_mul_f32_e32 v32, v36, v32
	v_cvt_pk_bf16_f32 v35, v35, s0
	v_cvt_pk_bf16_f32 v32, v32, s0
	global_store_short v[48:49], v35, off
	global_store_short v[48:49], v32, off offset:64
	v_or_b32_e32 v48, v64, v186
	v_ashrrev_i32_e32 v49, 31, v48
	v_lshlrev_b64 v[48:49], 11, v[48:49]
	v_mul_f32_e32 v32, v53, v33
	v_lshl_add_u64 v[48:49], v[130:131], 0, v[48:49]
	v_cvt_pk_bf16_f32 v32, v32, s0
	global_store_short v[48:49], v32, off
	v_mul_f32_e32 v32, v37, v33
	v_cvt_pk_bf16_f32 v32, v32, s0
	global_store_short v[48:49], v32, off offset:64
	v_or_b32_e32 v32, v64, v187
	v_ashrrev_i32_e32 v33, 31, v32
	v_lshlrev_b64 v[32:33], 11, v[32:33]
	v_mul_f32_e32 v35, v54, v34
	v_mul_f32_e32 v34, v38, v34
	v_lshl_add_u64 v[32:33], v[130:131], 0, v[32:33]
	v_cvt_pk_bf16_f32 v35, v35, s0
	v_cvt_pk_bf16_f32 v34, v34, s0
	global_store_short v[32:33], v35, off
	global_store_short v[32:33], v34, off offset:64
	v_or_b32_e32 v32, v64, v188
	v_ashrrev_i32_e32 v33, 31, v32
	v_and_b32_e32 v34, 0xff, v32
	v_lshl_add_u32 v34, v34, 2, v250
	ds_read_b32 v34, v34
	v_lshlrev_b64 v[32:33], 11, v[32:33]
	v_or_b32_e32 v36, v64, v189
	v_lshl_add_u64 v[32:33], v[130:131], 0, v[32:33]
	v_ashrrev_i32_e32 v37, 31, v36
	s_waitcnt lgkmcnt(0)
	v_mul_f32_e32 v35, v55, v34
	v_mul_f32_e32 v34, v39, v34
	v_cvt_pk_bf16_f32 v35, v35, s0
	v_cvt_pk_bf16_f32 v34, v34, s0
	global_store_short v[32:33], v35, off
	global_store_short v[32:33], v34, off offset:64
	v_and_b32_e32 v32, 0xff, v36
	v_lshl_add_u32 v32, v32, 2, v250
	ds_read_b96 v[32:34], v32
	v_lshlrev_b64 v[36:37], 11, v[36:37]
	v_lshl_add_u64 v[36:37], v[130:131], 0, v[36:37]
	s_waitcnt lgkmcnt(0)
	v_mul_f32_e32 v35, v56, v32
	v_mul_f32_e32 v32, v40, v32
	v_cvt_pk_bf16_f32 v35, v35, s0
	v_cvt_pk_bf16_f32 v32, v32, s0
	global_store_short v[36:37], v35, off
	global_store_short v[36:37], v32, off offset:64
	v_or_b32_e32 v36, v64, v190
	v_ashrrev_i32_e32 v37, 31, v36
	v_lshlrev_b64 v[36:37], 11, v[36:37]
	v_mul_f32_e32 v32, v57, v33
	v_lshl_add_u64 v[36:37], v[130:131], 0, v[36:37]
	v_cvt_pk_bf16_f32 v32, v32, s0
	global_store_short v[36:37], v32, off
	v_mul_f32_e32 v32, v41, v33
	v_cvt_pk_bf16_f32 v32, v32, s0
	global_store_short v[36:37], v32, off offset:64
	v_or_b32_e32 v32, v64, v191
	v_ashrrev_i32_e32 v33, 31, v32
	v_lshlrev_b64 v[32:33], 11, v[32:33]
	v_mul_f32_e32 v35, v58, v34
	v_mul_f32_e32 v34, v42, v34
	v_lshl_add_u64 v[32:33], v[130:131], 0, v[32:33]
	v_cvt_pk_bf16_f32 v35, v35, s0
	v_cvt_pk_bf16_f32 v34, v34, s0
	global_store_short v[32:33], v35, off
	global_store_short v[32:33], v34, off offset:64
	v_or_b32_e32 v32, v64, v192
	v_ashrrev_i32_e32 v33, 31, v32
	v_and_b32_e32 v34, 0xff, v32
	v_lshl_add_u32 v34, v34, 2, v250
	ds_read_b32 v34, v34
	v_lshlrev_b64 v[32:33], 11, v[32:33]
	v_or_b32_e32 v36, v64, v193
	v_lshl_add_u64 v[32:33], v[130:131], 0, v[32:33]
	v_ashrrev_i32_e32 v37, 31, v36
	s_waitcnt lgkmcnt(0)
	v_mul_f32_e32 v35, v59, v34
	v_mul_f32_e32 v34, v43, v34
	v_cvt_pk_bf16_f32 v35, v35, s0
	v_cvt_pk_bf16_f32 v34, v34, s0
	global_store_short v[32:33], v35, off
	global_store_short v[32:33], v34, off offset:64
	v_and_b32_e32 v32, 0xff, v36
	v_lshl_add_u32 v32, v32, 2, v250
	ds_read_b96 v[32:34], v32
	v_lshlrev_b64 v[36:37], 11, v[36:37]
	v_lshl_add_u64 v[36:37], v[130:131], 0, v[36:37]
	s_waitcnt lgkmcnt(0)
	v_mul_f32_e32 v35, v60, v32
	v_mul_f32_e32 v32, v44, v32
	v_cvt_pk_bf16_f32 v35, v35, s0
	v_cvt_pk_bf16_f32 v32, v32, s0
	global_store_short v[36:37], v35, off
	global_store_short v[36:37], v32, off offset:64
	v_or_b32_e32 v36, v64, v194
	v_ashrrev_i32_e32 v37, 31, v36
	v_lshlrev_b64 v[36:37], 11, v[36:37]
	v_mul_f32_e32 v32, v61, v33
	v_lshl_add_u64 v[36:37], v[130:131], 0, v[36:37]
	v_cvt_pk_bf16_f32 v32, v32, s0
	global_store_short v[36:37], v32, off
	v_mul_f32_e32 v32, v45, v33
	v_cvt_pk_bf16_f32 v32, v32, s0
	global_store_short v[36:37], v32, off offset:64
	v_or_b32_e32 v32, v64, v195
	v_ashrrev_i32_e32 v33, 31, v32
	v_lshlrev_b64 v[32:33], 11, v[32:33]
	v_mul_f32_e32 v35, v62, v34
	v_mul_f32_e32 v34, v46, v34
	v_lshl_add_u64 v[32:33], v[130:131], 0, v[32:33]
	v_cvt_pk_bf16_f32 v35, v35, s0
	v_cvt_pk_bf16_f32 v34, v34, s0
	global_store_short v[32:33], v35, off
	global_store_short v[32:33], v34, off offset:64
	v_or_b32_e32 v32, v64, v196
	v_ashrrev_i32_e32 v33, 31, v32
	v_and_b32_e32 v34, 0xff, v32
	v_lshl_add_u32 v34, v34, 2, v250
	ds_read_b32 v34, v34
	v_lshlrev_b64 v[32:33], 11, v[32:33]
	v_lshl_add_u64 v[32:33], v[130:131], 0, v[32:33]
	s_waitcnt lgkmcnt(0)
	v_mul_f32_e32 v35, v63, v34
	v_mul_f32_e32 v34, v47, v34
	v_cvt_pk_bf16_f32 v35, v35, s0
	v_cvt_pk_bf16_f32 v34, v34, s0
	global_store_short v[32:33], v35, off
	global_store_short v[32:33], v34, off offset:64
	v_or_b32_e32 v32, 0x60, v132
	v_or_b32_e32 v38, v32, v181
	v_ashrrev_i32_e32 v39, 31, v38
	v_and_b32_e32 v34, 0xff, v38
	v_lshl_add_u32 v34, v34, 2, v250
	ds_read_b96 v[34:36], v34
	v_lshlrev_b64 v[38:39], 11, v[38:39]
	v_lshl_add_u64 v[38:39], v[130:131], 0, v[38:39]
	s_waitcnt lgkmcnt(0)
	v_mul_f32_e32 v16, v16, v34
	v_mul_f32_e32 v0, v0, v34
	v_cvt_pk_bf16_f32 v16, v16, s0
	v_cvt_pk_bf16_f32 v0, v0, s0
	global_store_short v[38:39], v16, off
	global_store_short v[38:39], v0, off offset:64
	v_or_b32_e32 v38, v32, v182
	v_ashrrev_i32_e32 v39, 31, v38
	v_lshlrev_b64 v[38:39], 11, v[38:39]
	v_mul_f32_e32 v0, v17, v35
	v_lshl_add_u64 v[38:39], v[130:131], 0, v[38:39]
	v_cvt_pk_bf16_f32 v0, v0, s0
	global_store_short v[38:39], v0, off
	v_mul_f32_e32 v0, v1, v35
	v_cvt_pk_bf16_f32 v0, v0, s0
	global_store_short v[38:39], v0, off offset:64
	v_or_b32_e32 v0, v32, v183
	v_ashrrev_i32_e32 v1, 31, v0
	v_lshlrev_b64 v[0:1], 11, v[0:1]
	v_mul_f32_e32 v16, v18, v36
	v_mul_f32_e32 v2, v2, v36
	v_lshl_add_u64 v[0:1], v[130:131], 0, v[0:1]
	v_cvt_pk_bf16_f32 v16, v16, s0
	v_cvt_pk_bf16_f32 v2, v2, s0
	global_store_short v[0:1], v16, off
	global_store_short v[0:1], v2, off offset:64
	v_or_b32_e32 v0, v32, v184
	v_ashrrev_i32_e32 v1, 31, v0
	v_and_b32_e32 v16, 0xff, v0
	v_lshl_add_u32 v16, v16, 2, v250
	ds_read_b32 v2, v16
	v_lshlrev_b64 v[0:1], 11, v[0:1]
	v_lshl_add_u64 v[0:1], v[130:131], 0, v[0:1]
	s_waitcnt lgkmcnt(0)
	v_mul_f32_e32 v16, v19, v2
	v_cvt_pk_bf16_f32 v16, v16, s0
	global_store_short v[0:1], v16, off
	v_mul_f32_e32 v2, v3, v2
	v_or_b32_e32 v16, v32, v185
	v_cvt_pk_bf16_f32 v2, v2, s0
	v_ashrrev_i32_e32 v17, 31, v16
	global_store_short v[0:1], v2, off offset:64
	v_and_b32_e32 v0, 0xff, v16
	v_lshl_add_u32 v0, v0, 2, v250
	ds_read_b96 v[0:2], v0
	v_lshlrev_b64 v[16:17], 11, v[16:17]
	v_lshl_add_u64 v[16:17], v[130:131], 0, v[16:17]
	s_waitcnt lgkmcnt(0)
	v_mul_f32_e32 v3, v20, v0
	v_mul_f32_e32 v0, v4, v0
	v_cvt_pk_bf16_f32 v3, v3, s0
	v_cvt_pk_bf16_f32 v0, v0, s0
	global_store_short v[16:17], v3, off
	global_store_short v[16:17], v0, off offset:64
	v_or_b32_e32 v16, v32, v186
	v_ashrrev_i32_e32 v17, 31, v16
	v_lshlrev_b64 v[16:17], 11, v[16:17]
	v_mul_f32_e32 v0, v21, v1
	v_lshl_add_u64 v[16:17], v[130:131], 0, v[16:17]
	v_cvt_pk_bf16_f32 v0, v0, s0
	global_store_short v[16:17], v0, off
	v_mul_f32_e32 v0, v5, v1
	v_cvt_pk_bf16_f32 v0, v0, s0
	global_store_short v[16:17], v0, off offset:64
	v_or_b32_e32 v0, v32, v187
	v_ashrrev_i32_e32 v1, 31, v0
	v_lshlrev_b64 v[0:1], 11, v[0:1]
	v_mul_f32_e32 v3, v22, v2
	v_mul_f32_e32 v2, v6, v2
	v_lshl_add_u64 v[0:1], v[130:131], 0, v[0:1]
	v_cvt_pk_bf16_f32 v3, v3, s0
	v_cvt_pk_bf16_f32 v2, v2, s0
	global_store_short v[0:1], v3, off
	global_store_short v[0:1], v2, off offset:64
	v_or_b32_e32 v0, v32, v188
	v_ashrrev_i32_e32 v1, 31, v0
	v_and_b32_e32 v2, 0xff, v0
	v_lshl_add_u32 v2, v2, 2, v250
	ds_read_b32 v2, v2
	v_lshlrev_b64 v[0:1], 11, v[0:1]
	v_or_b32_e32 v4, v32, v189
	v_lshl_add_u64 v[0:1], v[130:131], 0, v[0:1]
	v_ashrrev_i32_e32 v5, 31, v4
	s_waitcnt lgkmcnt(0)
	v_mul_f32_e32 v3, v23, v2
	v_mul_f32_e32 v2, v7, v2
	v_cvt_pk_bf16_f32 v3, v3, s0
	v_cvt_pk_bf16_f32 v2, v2, s0
	global_store_short v[0:1], v3, off
	global_store_short v[0:1], v2, off offset:64
	v_and_b32_e32 v0, 0xff, v4
	v_lshl_add_u32 v0, v0, 2, v250
	ds_read_b96 v[0:2], v0
	v_lshlrev_b64 v[4:5], 11, v[4:5]
	v_lshl_add_u64 v[4:5], v[130:131], 0, v[4:5]
	s_waitcnt lgkmcnt(0)
	v_mul_f32_e32 v3, v24, v0
	v_mul_f32_e32 v0, v8, v0
	v_cvt_pk_bf16_f32 v3, v3, s0
	v_cvt_pk_bf16_f32 v0, v0, s0
	global_store_short v[4:5], v3, off
	global_store_short v[4:5], v0, off offset:64
	v_or_b32_e32 v4, v32, v190
	v_ashrrev_i32_e32 v5, 31, v4
	v_lshlrev_b64 v[4:5], 11, v[4:5]
	v_mul_f32_e32 v0, v25, v1
	v_lshl_add_u64 v[4:5], v[130:131], 0, v[4:5]
	v_cvt_pk_bf16_f32 v0, v0, s0
	global_store_short v[4:5], v0, off
	v_mul_f32_e32 v0, v9, v1
	v_cvt_pk_bf16_f32 v0, v0, s0
	global_store_short v[4:5], v0, off offset:64
	v_or_b32_e32 v0, v32, v191
	v_ashrrev_i32_e32 v1, 31, v0
	v_lshlrev_b64 v[0:1], 11, v[0:1]
	v_mul_f32_e32 v3, v26, v2
	v_mul_f32_e32 v2, v10, v2
	v_lshl_add_u64 v[0:1], v[130:131], 0, v[0:1]
	v_cvt_pk_bf16_f32 v3, v3, s0
	v_cvt_pk_bf16_f32 v2, v2, s0
	global_store_short v[0:1], v3, off
	global_store_short v[0:1], v2, off offset:64
	v_or_b32_e32 v0, v32, v192
	v_ashrrev_i32_e32 v1, 31, v0
	v_and_b32_e32 v2, 0xff, v0
	v_lshl_add_u32 v2, v2, 2, v250
	ds_read_b32 v2, v2
	v_lshlrev_b64 v[0:1], 11, v[0:1]
	v_or_b32_e32 v4, v32, v193
	v_lshl_add_u64 v[0:1], v[130:131], 0, v[0:1]
	v_ashrrev_i32_e32 v5, 31, v4
	s_waitcnt lgkmcnt(0)
	v_mul_f32_e32 v3, v27, v2
	v_mul_f32_e32 v2, v11, v2
	v_cvt_pk_bf16_f32 v3, v3, s0
	v_cvt_pk_bf16_f32 v2, v2, s0
	global_store_short v[0:1], v3, off
	global_store_short v[0:1], v2, off offset:64
	v_and_b32_e32 v0, 0xff, v4
	v_lshl_add_u32 v0, v0, 2, v250
	ds_read_b96 v[0:2], v0
	v_lshlrev_b64 v[4:5], 11, v[4:5]
	v_lshl_add_u64 v[4:5], v[130:131], 0, v[4:5]
	s_waitcnt lgkmcnt(0)
	v_mul_f32_e32 v3, v28, v0
	v_mul_f32_e32 v0, v12, v0
	v_cvt_pk_bf16_f32 v3, v3, s0
	v_cvt_pk_bf16_f32 v0, v0, s0
	global_store_short v[4:5], v3, off
	global_store_short v[4:5], v0, off offset:64
	v_or_b32_e32 v4, v32, v194
	v_ashrrev_i32_e32 v5, 31, v4
	v_lshlrev_b64 v[4:5], 11, v[4:5]
	v_mul_f32_e32 v0, v29, v1
	v_lshl_add_u64 v[4:5], v[130:131], 0, v[4:5]
	v_cvt_pk_bf16_f32 v0, v0, s0
	global_store_short v[4:5], v0, off
	v_mul_f32_e32 v0, v13, v1
	v_cvt_pk_bf16_f32 v0, v0, s0
	global_store_short v[4:5], v0, off offset:64
	v_or_b32_e32 v0, v32, v195
	v_ashrrev_i32_e32 v1, 31, v0
	v_lshlrev_b64 v[0:1], 11, v[0:1]
	v_mul_f32_e32 v3, v30, v2
	v_mul_f32_e32 v2, v14, v2
	v_lshl_add_u64 v[0:1], v[130:131], 0, v[0:1]
	v_cvt_pk_bf16_f32 v3, v3, s0
	v_cvt_pk_bf16_f32 v2, v2, s0
	global_store_short v[0:1], v3, off
	global_store_short v[0:1], v2, off offset:64
	v_or_b32_e32 v0, v32, v196
	v_ashrrev_i32_e32 v1, 31, v0
	v_and_b32_e32 v2, 0xff, v0
	v_lshl_add_u32 v2, v2, 2, v250
	ds_read_b32 v2, v2
	v_lshlrev_b64 v[0:1], 11, v[0:1]
	v_lshl_add_u64 v[0:1], v[130:131], 0, v[0:1]
	s_waitcnt lgkmcnt(0)
	v_mul_f32_e32 v3, v31, v2
	v_mul_f32_e32 v2, v15, v2
	v_cvt_pk_bf16_f32 v3, v3, s0
	v_cvt_pk_bf16_f32 v2, v2, s0
	global_store_short v[0:1], v3, off
	global_store_short v[0:1], v2, off offset:64
	s_cbranch_scc0 .LBB0_2225

.LBB0_2340:
	s_waitcnt lgkmcnt(0)
	s_nop 0
	v_mfma_f32_32x32x16_bf16 v[112:127], v[150:153], v[142:145], v[112:127]
	v_mfma_f32_32x32x16_bf16 v[96:111], v[150:153], v[130:133], v[96:111]
	s_and_b32 s19, s18, 0x18000
	v_add_u32_e32 v187, s19, v180
	s_add_i32 s19, s18, 0xfffe8000
	s_and_b32 s19, s19, 0x18000
	v_or_b32_e32 v212, s19, v179
	v_add_u32_e32 v213, s19, v176
	s_waitcnt vmcnt(8)
	s_barrier
	v_add_u32_e32 v192, v212, v177
	v_add_u32_e32 v208, v213, v177
	ds_read_b128 v[188:191], v192 offset:16384
	ds_read_b128 v[192:195], v192 offset:18432
	ds_read_b128 v[196:199], v208
	v_mfma_f32_32x32x16_bf16 v[80:95], v[146:149], v[142:145], v[80:95]
	v_readfirstlane_b32 s19, v187
	s_mov_b32 m0, s19
	v_mfma_f32_32x32x16_bf16 v[64:79], v[146:149], v[130:133], v[64:79]
	ds_read_b128 v[200:203], v208 offset:2048
	global_load_lds_dwordx4 v[170:171], off
	v_mfma_f32_32x32x16_bf16 v[48:63], v[138:141], v[142:145], v[48:63]
	s_add_i32 s20, s19, 0x2000
	v_lshl_add_u64 v[150:151], v[170:171], 0, s[34:35]
	s_mov_b32 m0, s20
	v_mfma_f32_32x32x16_bf16 v[32:47], v[138:141], v[130:133], v[32:47]
	ds_read_b128 v[204:207], v208 offset:4096
	global_load_lds_dwordx4 v[150:151], off
	v_mfma_f32_32x32x16_bf16 v[16:31], v[134:137], v[142:145], v[16:31]
	v_mfma_f32_32x32x16_bf16 v[0:15], v[134:137], v[130:133], v[0:15]
	ds_read_b128 v[208:211], v208 offset:6144
	s_waitcnt lgkmcnt(3)
	v_mfma_f32_32x32x16_bf16 v[112:127], v[196:199], v[188:191], v[112:127]
	v_add_u32_e32 v130, v212, v178
	v_add_u32_e32 v134, v213, v178
	ds_read_b128 v[142:145], v130 offset:16384
	s_add_i32 s20, s19, 0x6000
	s_addk_i32 s19, 0x4000
	s_mov_b32 m0, s19
	v_mfma_f32_32x32x16_bf16 v[96:111], v[196:199], v[192:195], v[96:111]
	ds_read_b128 v[130:133], v130 offset:18432
	global_load_lds_dwordx4 v[172:173], off
	s_waitcnt lgkmcnt(4)
	v_mfma_f32_32x32x16_bf16 v[80:95], v[200:203], v[188:191], v[80:95]
	ds_read_b128 v[150:153], v134
	v_mfma_f32_32x32x16_bf16 v[64:79], v[200:203], v[192:195], v[64:79]
	ds_read_b128 v[146:149], v134 offset:2048
	s_waitcnt lgkmcnt(5)
	v_mfma_f32_32x32x16_bf16 v[48:63], v[204:207], v[188:191], v[48:63]
	ds_read_b128 v[138:141], v134 offset:4096
	v_lshl_add_u64 v[212:213], v[172:173], 0, s[34:35]
	s_mov_b32 m0, s20
	v_mfma_f32_32x32x16_bf16 v[32:47], v[204:207], v[192:195], v[32:47]
	ds_read_b128 v[134:137], v134 offset:6144
	global_load_lds_dwordx4 v[212:213], off
	s_waitcnt lgkmcnt(6)
	v_mfma_f32_32x32x16_bf16 v[16:31], v[208:211], v[188:191], v[16:31]
	s_add_i32 s18, s18, 0x8000
	v_lshl_add_u64 v[170:171], v[170:171], 0, 64
	v_lshl_add_u64 v[172:173], v[172:173], 0, 64
	s_cmp_eq_u32 s18, 0x100000
	v_mfma_f32_32x32x16_bf16 v[0:15], v[208:211], v[192:195], v[0:15]
	s_cbranch_scc0 .LBB0_2340
	s_waitcnt vmcnt(8) lgkmcnt(0)
	s_barrier
	v_add_u32_e32 v187, v179, v177
	ds_read_b128 v[170:173], v187 offset:49152
	ds_read_b128 v[188:191], v187 offset:51200
	v_add_u32_e32 v187, v176, v177
	ds_read_b128 v[192:195], v187 offset:32768
	ds_read_b128 v[196:199], v187 offset:34816
	ds_read_b128 v[200:203], v187 offset:36864
	ds_read_b128 v[204:207], v187 offset:38912
	s_waitcnt lgkmcnt(9)
	v_mfma_f32_32x32x16_bf16 v[112:127], v[150:153], v[142:145], v[112:127]
	v_mfma_f32_32x32x16_bf16 v[96:111], v[150:153], v[130:133], v[96:111]
	s_waitcnt lgkmcnt(8)
	v_mfma_f32_32x32x16_bf16 v[80:95], v[146:149], v[142:145], v[80:95]
	v_mfma_f32_32x32x16_bf16 v[64:79], v[146:149], v[130:133], v[64:79]
	s_waitcnt lgkmcnt(7)
	v_mfma_f32_32x32x16_bf16 v[48:63], v[138:141], v[142:145], v[48:63]
	v_mfma_f32_32x32x16_bf16 v[32:47], v[138:141], v[130:133], v[32:47]
	s_waitcnt lgkmcnt(6)
	v_mfma_f32_32x32x16_bf16 v[16:31], v[134:137], v[142:145], v[16:31]
	v_mfma_f32_32x32x16_bf16 v[0:15], v[134:137], v[130:133], v[0:15]
	v_add_u32_e32 v134, v179, v178
	v_add_u32_e32 v150, v176, v178
	ds_read_b128 v[130:133], v134 offset:49152
	ds_read_b128 v[134:137], v134 offset:51200
	ds_read_b128 v[138:141], v150 offset:32768
	ds_read_b128 v[142:145], v150 offset:34816
	ds_read_b128 v[146:149], v150 offset:36864
	ds_read_b128 v[150:153], v150 offset:38912
	s_waitcnt lgkmcnt(9)
	v_mfma_f32_32x32x16_bf16 v[112:127], v[192:195], v[170:173], v[112:127]
	v_mfma_f32_32x32x16_bf16 v[96:111], v[192:195], v[188:191], v[96:111]
	s_waitcnt lgkmcnt(8)
	v_mfma_f32_32x32x16_bf16 v[80:95], v[196:199], v[170:173], v[80:95]
	v_mfma_f32_32x32x16_bf16 v[64:79], v[196:199], v[188:191], v[64:79]
	s_waitcnt lgkmcnt(7)
	v_mfma_f32_32x32x16_bf16 v[48:63], v[200:203], v[170:173], v[48:63]
	v_mfma_f32_32x32x16_bf16 v[32:47], v[200:203], v[188:191], v[32:47]
	s_waitcnt vmcnt(4) lgkmcnt(0)
	s_barrier
	v_add_u32_e32 v187, v184, v177
	s_waitcnt lgkmcnt(6)
	v_mfma_f32_32x32x16_bf16 v[16:31], v[204:207], v[170:173], v[16:31]
	v_mfma_f32_32x32x16_bf16 v[0:15], v[204:207], v[188:191], v[0:15]
	ds_read_b128 v[170:173], v187 offset:16384
	ds_read_b128 v[188:191], v187 offset:18432
	v_add_u32_e32 v187, v185, v177
	ds_read_b128 v[192:195], v187
	ds_read_b128 v[196:199], v187 offset:2048
	ds_read_b128 v[200:203], v187 offset:4096
	ds_read_b128 v[204:207], v187 offset:6144
	s_waitcnt lgkmcnt(9)
	v_mfma_f32_32x32x16_bf16 v[112:127], v[138:141], v[130:133], v[112:127]
	v_mfma_f32_32x32x16_bf16 v[96:111], v[138:141], v[134:137], v[96:111]
	s_waitcnt lgkmcnt(8)
	v_mfma_f32_32x32x16_bf16 v[80:95], v[142:145], v[130:133], v[80:95]
	v_mfma_f32_32x32x16_bf16 v[64:79], v[142:145], v[134:137], v[64:79]
	s_waitcnt lgkmcnt(7)
	v_mfma_f32_32x32x16_bf16 v[48:63], v[146:149], v[130:133], v[48:63]
	v_mfma_f32_32x32x16_bf16 v[32:47], v[146:149], v[134:137], v[32:47]
	s_waitcnt lgkmcnt(6)
	v_mfma_f32_32x32x16_bf16 v[16:31], v[150:153], v[130:133], v[16:31]
	v_mfma_f32_32x32x16_bf16 v[0:15], v[150:153], v[134:137], v[0:15]
	v_add_u32_e32 v134, v184, v178
	v_add_u32_e32 v150, v185, v178
	ds_read_b128 v[130:133], v134 offset:16384
	ds_read_b128 v[134:137], v134 offset:18432
	ds_read_b128 v[138:141], v150
	ds_read_b128 v[142:145], v150 offset:2048
	ds_read_b128 v[146:149], v150 offset:4096
	ds_read_b128 v[150:153], v150 offset:6144
	s_waitcnt lgkmcnt(9)
	v_mfma_f32_32x32x16_bf16 v[112:127], v[192:195], v[170:173], v[112:127]
	v_mfma_f32_32x32x16_bf16 v[96:111], v[192:195], v[188:191], v[96:111]
	s_waitcnt lgkmcnt(8)
	v_mfma_f32_32x32x16_bf16 v[80:95], v[196:199], v[170:173], v[80:95]
	v_mfma_f32_32x32x16_bf16 v[64:79], v[196:199], v[188:191], v[64:79]
	s_waitcnt lgkmcnt(7)
	v_mfma_f32_32x32x16_bf16 v[48:63], v[200:203], v[170:173], v[48:63]
	v_mfma_f32_32x32x16_bf16 v[32:47], v[200:203], v[188:191], v[32:47]
	s_waitcnt vmcnt(0) lgkmcnt(0)
	s_barrier
	v_add_u32_e32 v187, v182, v177
	s_waitcnt lgkmcnt(6)
	v_mfma_f32_32x32x16_bf16 v[16:31], v[204:207], v[170:173], v[16:31]
	v_mfma_f32_32x32x16_bf16 v[0:15], v[204:207], v[188:191], v[0:15]
	ds_read_b128 v[170:173], v187 offset:16384
	ds_read_b128 v[188:191], v187 offset:18432
	v_add_u32_e32 v187, v183, v177
	ds_read_b128 v[192:195], v187
	ds_read_b128 v[196:199], v187 offset:2048
	ds_read_b128 v[200:203], v187 offset:4096
	ds_read_b128 v[204:207], v187 offset:6144
	s_waitcnt lgkmcnt(9)
	v_mfma_f32_32x32x16_bf16 v[112:127], v[138:141], v[130:133], v[112:127]
	v_mfma_f32_32x32x16_bf16 v[96:111], v[138:141], v[134:137], v[96:111]
	s_waitcnt lgkmcnt(8)
	v_mfma_f32_32x32x16_bf16 v[80:95], v[142:145], v[130:133], v[80:95]
	v_mfma_f32_32x32x16_bf16 v[64:79], v[142:145], v[134:137], v[64:79]
	s_waitcnt lgkmcnt(7)
	v_mfma_f32_32x32x16_bf16 v[48:63], v[146:149], v[130:133], v[48:63]
	v_mfma_f32_32x32x16_bf16 v[32:47], v[146:149], v[134:137], v[32:47]
	s_waitcnt lgkmcnt(6)
	v_mfma_f32_32x32x16_bf16 v[16:31], v[150:153], v[130:133], v[16:31]
	v_mfma_f32_32x32x16_bf16 v[0:15], v[150:153], v[134:137], v[0:15]
	v_add_u32_e32 v134, v182, v178
	v_add_u32_e32 v150, v183, v178
	ds_read_b128 v[130:133], v134 offset:16384
	ds_read_b128 v[134:137], v134 offset:18432
	ds_read_b128 v[138:141], v150
	ds_read_b128 v[142:145], v150 offset:2048
	ds_read_b128 v[146:149], v150 offset:4096
	ds_read_b128 v[150:153], v150 offset:6144
	s_waitcnt lgkmcnt(9)
	v_mfma_f32_32x32x16_bf16 v[112:127], v[192:195], v[170:173], v[112:127]
	v_mfma_f32_32x32x16_bf16 v[96:111], v[192:195], v[188:191], v[96:111]
	s_waitcnt lgkmcnt(8)
	v_mfma_f32_32x32x16_bf16 v[80:95], v[196:199], v[170:173], v[80:95]
	v_mfma_f32_32x32x16_bf16 v[64:79], v[196:199], v[188:191], v[64:79]
	s_waitcnt lgkmcnt(7)
	v_mfma_f32_32x32x16_bf16 v[48:63], v[200:203], v[170:173], v[48:63]
	v_mfma_f32_32x32x16_bf16 v[32:47], v[200:203], v[188:191], v[32:47]
	s_waitcnt lgkmcnt(6)
	v_mfma_f32_32x32x16_bf16 v[16:31], v[204:207], v[170:173], v[16:31]
	v_mfma_f32_32x32x16_bf16 v[0:15], v[204:207], v[188:191], v[0:15]
	s_waitcnt lgkmcnt(3)
	v_mfma_f32_32x32x16_bf16 v[112:127], v[138:141], v[130:133], v[112:127]
	s_waitcnt lgkmcnt(2)
	v_mfma_f32_32x32x16_bf16 v[80:95], v[142:145], v[130:133], v[80:95]
	s_waitcnt lgkmcnt(1)
	v_mfma_f32_32x32x16_bf16 v[48:63], v[146:149], v[130:133], v[48:63]
	s_waitcnt lgkmcnt(0)
	v_mfma_f32_32x32x16_bf16 v[16:31], v[150:153], v[130:133], v[16:31]
	v_or_b32_e32 v132, s12, v174
	v_ashrrev_i32_e32 v130, 1, v132
	v_or_b32_e32 v130, v130, v154
	v_ashrrev_i32_e32 v131, 31, v130
	s_movk_i32 s12, 0x5000
	v_mfma_f32_32x32x16_bf16 v[96:111], v[138:141], v[134:137], v[96:111]
	v_mfma_f32_32x32x16_bf16 v[64:79], v[142:145], v[134:137], v[64:79]
	v_add_u32_e32 v142, s13, v155
	s_mov_b32 s13, 0xb000
	v_ashrrev_i32_e32 v133, 7, v142
	v_mfma_f32_32x32x16_bf16 v[32:47], v[146:149], v[134:137], v[32:47]
	v_mfma_f32_32x32x16_bf16 v[0:15], v[150:153], v[134:137], v[0:15]
	v_lshl_add_u64 v[134:135], v[130:131], 2, s[10:11]
	v_add_co_u32_e32 v138, vcc, s12, v134
	s_mov_b32 s12, 0x8000
	s_nop 0
	v_addc_co_u32_e32 v139, vcc, 0, v135, vcc
	global_load_dword v137, v[138:139], off offset:2048
	v_add_co_u32_e32 v138, vcc, s13, v134
	global_load_dword v136, v[134:135], off
	s_nop 0
	v_addc_co_u32_e32 v139, vcc, 0, v135, vcc
	v_add_co_u32_e32 v140, vcc, s47, v134
	global_load_dword v139, v[138:139], off
	s_nop 0
	v_addc_co_u32_e32 v141, vcc, 0, v135, vcc
	global_load_dword v138, v[140:141], off offset:3072
	v_add_co_u32_e32 v140, vcc, s12, v134
	s_mov_b32 s12, 0xd000
	s_nop 0
	v_addc_co_u32_e32 v141, vcc, 0, v135, vcc
	v_add_co_u32_e32 v134, vcc, s12, v134
	global_load_dword v140, v[140:141], off offset:1024
	s_nop 0
	v_addc_co_u32_e32 v135, vcc, 0, v135, vcc
	global_load_dword v141, v[134:135], off offset:3072
	v_readlane_b32 s100, v252, 7
	s_add_i32 s100, s14, s100
	s_cmpk_lt_i32 s100, 0xb0
	s_cbranch_scc0 .Lpf_none_up
	s_and_b32 vcc_lo, s100, 7
	s_or_b32 vcc_lo, vcc_lo, s16
	s_lshl_b32 vcc_lo, vcc_lo, 8
	v_add_u32_e32 v238, vcc_lo, v175
	v_ashrrev_i32_e32 v239, 31, v238
	v_lshlrev_b64 v[238:239], 11, v[238:239]
	v_lshl_add_u64 v[238:239], v[156:157], 0, v[238:239]
	s_lshl_b32 vcc_lo, s100, 5
	s_and_b32 vcc_lo, vcc_lo, 0xffffff00
	v_add_u32_e32 v240, vcc_lo, v175
	v_ashrrev_i32_e32 v241, 31, v240
	v_lshlrev_b64 v[240:241], 11, v[240:241]
	v_lshl_add_u64 v[240:241], v[158:159], 0, v[240:241]
	v_readfirstlane_b32 s100, v180
	s_mov_b32 m0, s100
	s_nop 0
	global_load_lds_dwordx4 v[238:239], off
	v_lshl_add_u64 v[242:243], v[238:239], 0, s[34:35]
	s_add_i32 m0, s100, 0x2000
	s_nop 0
	global_load_lds_dwordx4 v[242:243], off
	s_add_i32 m0, s100, 0x4000
	s_nop 0
	global_load_lds_dwordx4 v[240:241], off
	v_lshl_add_u64 v[242:243], v[240:241], 0, s[34:35]
	s_add_i32 m0, s100, 0x6000
	s_nop 0
	global_load_lds_dwordx4 v[242:243], off
	v_lshl_add_u64 v[242:243], v[238:239], 0, 64
	s_add_i32 m0, s100, 0x8000
	s_nop 0
	global_load_lds_dwordx4 v[242:243], off
	s_mov_b64 vcc, 0x40040
	v_lshl_add_u64 v[242:243], v[238:239], 0, vcc
	s_add_i32 m0, s100, 0xa000
	s_nop 0
	global_load_lds_dwordx4 v[242:243], off
	v_lshl_add_u64 v[242:243], v[240:241], 0, 64
	s_add_i32 m0, s100, 0xc000
	s_nop 0
	global_load_lds_dwordx4 v[242:243], off
	s_mov_b64 vcc, 0x40040
	v_lshl_add_u64 v[242:243], v[240:241], 0, vcc
	s_add_i32 m0, s100, 0xe000
	s_nop 0
	global_load_lds_dwordx4 v[242:243], off
	s_mov_b64 vcc, 0x80
	v_lshl_add_u64 v[242:243], v[238:239], 0, vcc
	s_add_i32 m0, s100, 0x10000
	s_nop 0
	global_load_lds_dwordx4 v[242:243], off
	s_mov_b64 vcc, 0x40080
	v_lshl_add_u64 v[242:243], v[238:239], 0, vcc
	s_add_i32 m0, s100, 0x12000
	s_nop 0
	global_load_lds_dwordx4 v[242:243], off
	s_mov_b64 vcc, 0x80
	v_lshl_add_u64 v[242:243], v[240:241], 0, vcc
	s_add_i32 m0, s100, 0x14000
	s_nop 0
	global_load_lds_dwordx4 v[242:243], off
	s_mov_b64 vcc, 0x40080
	v_lshl_add_u64 v[242:243], v[240:241], 0, vcc
	s_add_i32 m0, s100, 0x16000
	s_nop 0
	global_load_lds_dwordx4 v[242:243], off
	s_mov_b32 s101, 1
	s_branch .Lpf_done_up

.LBB0_2551:
	s_waitcnt lgkmcnt(0)
	s_nop 0
	v_mfma_f32_32x32x16_bf16 v[112:127], v[150:153], v[142:145], v[112:127]
	v_mfma_f32_32x32x16_bf16 v[96:111], v[150:153], v[130:133], v[96:111]
	s_and_b32 s7, s5, 0x18000
	v_add_u32_e32 v222, s7, v180
	s_add_i32 s7, s5, 0xfffe8000
	s_and_b32 s7, s7, 0x18000
	v_or_b32_e32 v223, s7, v179
	v_add_u32_e32 v233, s7, v176
	s_waitcnt vmcnt(8)
	s_barrier
	v_add_u32_e32 v206, v223, v177
	v_add_u32_e32 v234, v233, v177
	ds_read_b128 v[202:205], v206 offset:16384
	ds_read_b128 v[206:209], v206 offset:18432
	ds_read_b128 v[210:213], v234
	v_mfma_f32_32x32x16_bf16 v[80:95], v[146:149], v[142:145], v[80:95]
	v_readfirstlane_b32 s7, v222
	s_mov_b32 m0, s7
	v_mfma_f32_32x32x16_bf16 v[64:79], v[146:149], v[130:133], v[64:79]
	ds_read_b128 v[214:217], v234 offset:2048
	global_load_lds_dwordx4 v[170:171], off
	v_mfma_f32_32x32x16_bf16 v[48:63], v[138:141], v[142:145], v[48:63]
	s_add_i32 s8, s7, 0x2000
	v_lshl_add_u64 v[150:151], v[170:171], 0, s[10:11]
	s_mov_b32 m0, s8
	v_mfma_f32_32x32x16_bf16 v[32:47], v[138:141], v[130:133], v[32:47]
	ds_read_b128 v[224:227], v234 offset:4096
	global_load_lds_dwordx4 v[150:151], off
	v_mfma_f32_32x32x16_bf16 v[16:31], v[134:137], v[142:145], v[16:31]
	v_mfma_f32_32x32x16_bf16 v[0:15], v[134:137], v[130:133], v[0:15]
	ds_read_b128 v[234:237], v234 offset:6144
	s_waitcnt lgkmcnt(3)
	v_mfma_f32_32x32x16_bf16 v[112:127], v[210:213], v[202:205], v[112:127]
	v_add_u32_e32 v130, v223, v178
	v_add_u32_e32 v134, v233, v178
	ds_read_b128 v[142:145], v130 offset:16384
	s_add_i32 s8, s7, 0x6000
	s_addk_i32 s7, 0x4000
	s_mov_b32 m0, s7
	v_mfma_f32_32x32x16_bf16 v[96:111], v[210:213], v[206:209], v[96:111]
	ds_read_b128 v[130:133], v130 offset:18432
	global_load_lds_dwordx4 v[172:173], off
	s_waitcnt lgkmcnt(4)
	v_mfma_f32_32x32x16_bf16 v[80:95], v[214:217], v[202:205], v[80:95]
	ds_read_b128 v[150:153], v134
	v_mfma_f32_32x32x16_bf16 v[64:79], v[214:217], v[206:209], v[64:79]
	ds_read_b128 v[146:149], v134 offset:2048
	s_waitcnt lgkmcnt(5)
	v_mfma_f32_32x32x16_bf16 v[48:63], v[224:227], v[202:205], v[48:63]
	ds_read_b128 v[138:141], v134 offset:4096
	v_lshl_add_u64 v[222:223], v[172:173], 0, s[10:11]
	s_mov_b32 m0, s8
	v_mfma_f32_32x32x16_bf16 v[32:47], v[224:227], v[206:209], v[32:47]
	ds_read_b128 v[134:137], v134 offset:6144
	global_load_lds_dwordx4 v[222:223], off
	s_waitcnt lgkmcnt(6)
	v_mfma_f32_32x32x16_bf16 v[16:31], v[234:237], v[202:205], v[16:31]
	s_add_i32 s5, s5, 0x8000
	v_lshl_add_u64 v[170:171], v[170:171], 0, 64
	v_lshl_add_u64 v[172:173], v[172:173], 0, 64
	s_cmp_eq_u32 s5, 0x2c0000
	v_mfma_f32_32x32x16_bf16 v[0:15], v[234:237], v[206:209], v[0:15]
	s_cbranch_scc0 .LBB0_2551
	s_waitcnt vmcnt(8) lgkmcnt(0)
	s_barrier
	v_add_u32_e32 v202, v179, v177
	v_add_u32_e32 v222, v176, v177
	ds_read_b128 v[170:173], v202 offset:49152
	ds_read_b128 v[202:205], v202 offset:51200
	ds_read_b128 v[206:209], v222 offset:32768
	ds_read_b128 v[210:213], v222 offset:34816
	ds_read_b128 v[214:217], v222 offset:36864
	ds_read_b128 v[224:227], v222 offset:38912
	s_waitcnt lgkmcnt(9)
	v_mfma_f32_32x32x16_bf16 v[112:127], v[150:153], v[142:145], v[112:127]
	v_mfma_f32_32x32x16_bf16 v[96:111], v[150:153], v[130:133], v[96:111]
	s_waitcnt lgkmcnt(8)
	v_mfma_f32_32x32x16_bf16 v[80:95], v[146:149], v[142:145], v[80:95]
	v_mfma_f32_32x32x16_bf16 v[64:79], v[146:149], v[130:133], v[64:79]
	s_waitcnt lgkmcnt(7)
	v_mfma_f32_32x32x16_bf16 v[48:63], v[138:141], v[142:145], v[48:63]
	v_mfma_f32_32x32x16_bf16 v[32:47], v[138:141], v[130:133], v[32:47]
	s_waitcnt lgkmcnt(6)
	v_mfma_f32_32x32x16_bf16 v[16:31], v[134:137], v[142:145], v[16:31]
	v_mfma_f32_32x32x16_bf16 v[0:15], v[134:137], v[130:133], v[0:15]
	v_add_u32_e32 v134, v179, v178
	v_add_u32_e32 v150, v176, v178
	ds_read_b128 v[130:133], v134 offset:49152
	ds_read_b128 v[134:137], v134 offset:51200
	ds_read_b128 v[138:141], v150 offset:32768
	ds_read_b128 v[142:145], v150 offset:34816
	ds_read_b128 v[146:149], v150 offset:36864
	ds_read_b128 v[150:153], v150 offset:38912
	s_waitcnt lgkmcnt(9)
	v_mfma_f32_32x32x16_bf16 v[112:127], v[206:209], v[170:173], v[112:127]
	v_mfma_f32_32x32x16_bf16 v[96:111], v[206:209], v[202:205], v[96:111]
	s_waitcnt lgkmcnt(8)
	v_mfma_f32_32x32x16_bf16 v[80:95], v[210:213], v[170:173], v[80:95]
	v_mfma_f32_32x32x16_bf16 v[64:79], v[210:213], v[202:205], v[64:79]
	s_waitcnt lgkmcnt(7)
	v_mfma_f32_32x32x16_bf16 v[48:63], v[214:217], v[170:173], v[48:63]
	v_mfma_f32_32x32x16_bf16 v[32:47], v[214:217], v[202:205], v[32:47]
	s_waitcnt lgkmcnt(6)
	v_mfma_f32_32x32x16_bf16 v[0:15], v[224:227], v[202:205], v[0:15]
	s_waitcnt vmcnt(4) lgkmcnt(0)
	s_barrier
	v_add_u32_e32 v202, v199, v177
	v_add_u32_e32 v222, v200, v177
	v_mfma_f32_32x32x16_bf16 v[16:31], v[224:227], v[170:173], v[16:31]
	ds_read_b128 v[170:173], v202 offset:16384
	ds_read_b128 v[202:205], v202 offset:18432
	ds_read_b128 v[206:209], v222
	ds_read_b128 v[210:213], v222 offset:2048
	ds_read_b128 v[214:217], v222 offset:4096
	ds_read_b128 v[224:227], v222 offset:6144
	s_waitcnt lgkmcnt(9)
	v_mfma_f32_32x32x16_bf16 v[112:127], v[138:141], v[130:133], v[112:127]
	v_mfma_f32_32x32x16_bf16 v[96:111], v[138:141], v[134:137], v[96:111]
	s_waitcnt lgkmcnt(8)
	v_mfma_f32_32x32x16_bf16 v[80:95], v[142:145], v[130:133], v[80:95]
	v_mfma_f32_32x32x16_bf16 v[64:79], v[142:145], v[134:137], v[64:79]
	s_waitcnt lgkmcnt(7)
	v_mfma_f32_32x32x16_bf16 v[48:63], v[146:149], v[130:133], v[48:63]
	v_mfma_f32_32x32x16_bf16 v[32:47], v[146:149], v[134:137], v[32:47]
	s_waitcnt lgkmcnt(6)
	v_mfma_f32_32x32x16_bf16 v[16:31], v[150:153], v[130:133], v[16:31]
	v_mfma_f32_32x32x16_bf16 v[0:15], v[150:153], v[134:137], v[0:15]
	v_add_u32_e32 v134, v199, v178
	v_add_u32_e32 v150, v200, v178
	ds_read_b128 v[130:133], v134 offset:16384
	ds_read_b128 v[134:137], v134 offset:18432
	ds_read_b128 v[138:141], v150
	ds_read_b128 v[142:145], v150 offset:2048
	ds_read_b128 v[146:149], v150 offset:4096
	ds_read_b128 v[150:153], v150 offset:6144
	s_waitcnt lgkmcnt(9)
	v_mfma_f32_32x32x16_bf16 v[112:127], v[206:209], v[170:173], v[112:127]
	v_mfma_f32_32x32x16_bf16 v[96:111], v[206:209], v[202:205], v[96:111]
	s_waitcnt lgkmcnt(8)
	v_mfma_f32_32x32x16_bf16 v[80:95], v[210:213], v[170:173], v[80:95]
	v_mfma_f32_32x32x16_bf16 v[64:79], v[210:213], v[202:205], v[64:79]
	s_waitcnt lgkmcnt(7)
	v_mfma_f32_32x32x16_bf16 v[48:63], v[214:217], v[170:173], v[48:63]
	v_mfma_f32_32x32x16_bf16 v[32:47], v[214:217], v[202:205], v[32:47]
	s_waitcnt lgkmcnt(6)
	v_mfma_f32_32x32x16_bf16 v[0:15], v[224:227], v[202:205], v[0:15]
	s_waitcnt vmcnt(0) lgkmcnt(0)
	s_barrier
	v_add_u32_e32 v202, v197, v177
	v_add_u32_e32 v222, v198, v177
	v_mfma_f32_32x32x16_bf16 v[16:31], v[224:227], v[170:173], v[16:31]
	ds_read_b128 v[170:173], v202 offset:16384
	ds_read_b128 v[202:205], v202 offset:18432
	ds_read_b128 v[206:209], v222
	ds_read_b128 v[210:213], v222 offset:2048
	ds_read_b128 v[214:217], v222 offset:4096
	ds_read_b128 v[224:227], v222 offset:6144
	s_waitcnt lgkmcnt(9)
	v_mfma_f32_32x32x16_bf16 v[112:127], v[138:141], v[130:133], v[112:127]
	v_mfma_f32_32x32x16_bf16 v[96:111], v[138:141], v[134:137], v[96:111]
	s_waitcnt lgkmcnt(8)
	v_mfma_f32_32x32x16_bf16 v[80:95], v[142:145], v[130:133], v[80:95]
	v_mfma_f32_32x32x16_bf16 v[64:79], v[142:145], v[134:137], v[64:79]
	s_waitcnt lgkmcnt(7)
	v_mfma_f32_32x32x16_bf16 v[48:63], v[146:149], v[130:133], v[48:63]
	v_mfma_f32_32x32x16_bf16 v[32:47], v[146:149], v[134:137], v[32:47]
	s_waitcnt lgkmcnt(6)
	v_mfma_f32_32x32x16_bf16 v[16:31], v[150:153], v[130:133], v[16:31]
	v_mfma_f32_32x32x16_bf16 v[0:15], v[150:153], v[134:137], v[0:15]
	v_add_u32_e32 v134, v197, v178
	v_add_u32_e32 v150, v198, v178
	ds_read_b128 v[130:133], v134 offset:16384
	ds_read_b128 v[134:137], v134 offset:18432
	ds_read_b128 v[138:141], v150
	ds_read_b128 v[142:145], v150 offset:2048
	ds_read_b128 v[146:149], v150 offset:4096
	ds_read_b128 v[150:153], v150 offset:6144
	s_waitcnt lgkmcnt(9)
	v_mfma_f32_32x32x16_bf16 v[112:127], v[206:209], v[170:173], v[112:127]
	v_mfma_f32_32x32x16_bf16 v[96:111], v[206:209], v[202:205], v[96:111]
	s_waitcnt lgkmcnt(8)
	v_mfma_f32_32x32x16_bf16 v[80:95], v[210:213], v[170:173], v[80:95]
	v_mfma_f32_32x32x16_bf16 v[64:79], v[210:213], v[202:205], v[64:79]
	s_waitcnt lgkmcnt(7)
	v_mfma_f32_32x32x16_bf16 v[48:63], v[214:217], v[170:173], v[48:63]
	v_mfma_f32_32x32x16_bf16 v[32:47], v[214:217], v[202:205], v[32:47]
	s_waitcnt lgkmcnt(6)
	v_mfma_f32_32x32x16_bf16 v[16:31], v[224:227], v[170:173], v[16:31]
	s_movk_i32 s7, 0x1600
	v_mfma_f32_32x32x16_bf16 v[0:15], v[224:227], v[202:205], v[0:15]
	s_waitcnt lgkmcnt(3)
	v_mfma_f32_32x32x16_bf16 v[112:127], v[138:141], v[130:133], v[112:127]
	v_mfma_f32_32x32x16_bf16 v[96:111], v[138:141], v[134:137], v[96:111]
	s_nop 10
	v_cvt_pk_bf16_f32 v112, v112, s0
	s_waitcnt lgkmcnt(2)
	v_mfma_f32_32x32x16_bf16 v[80:95], v[142:145], v[130:133], v[80:95]
	v_cvt_pk_bf16_f32 v96, v96, s0
	v_cvt_pk_bf16_f32 v98, v98, s0
	s_waitcnt lgkmcnt(1)
	v_mfma_f32_32x32x16_bf16 v[48:63], v[146:149], v[130:133], v[48:63]
	s_nop 7
	v_cvt_pk_bf16_f32 v80, v80, s0
	s_waitcnt lgkmcnt(0)
	v_mfma_f32_32x32x16_bf16 v[16:31], v[150:153], v[130:133], v[16:31]
	v_add_u32_e32 v132, s3, v128
	v_or_b32_e32 v130, s4, v174
	v_ashrrev_i32_e32 v131, 31, v130
	v_lshl_add_u64 v[130:131], v[130:131], 1, v[158:159]
	v_cvt_pk_bf16_f32 v48, v48, s0
	v_readlane_b32 s3, v252, 7
	s_add_i32 s6, s6, s3
	v_mfma_f32_32x32x16_bf16 v[64:79], v[142:145], v[134:137], v[64:79]
	s_nop 3
	v_cvt_pk_bf16_f32 v16, v16, s0
	v_mfma_f32_32x32x16_bf16 v[32:47], v[146:149], v[134:137], v[32:47]
	s_nop 5
	v_cvt_pk_bf16_f32 v64, v64, s0
	v_cvt_pk_bf16_f32 v66, v66, s0
	v_mfma_f32_32x32x16_bf16 v[0:15], v[150:153], v[134:137], v[0:15]
	v_or_b32_e32 v134, v132, v181
	v_ashrrev_i32_e32 v135, 31, v134
	v_lshlrev_b64 v[134:135], 11, v[134:135]
	v_lshl_add_u64 v[134:135], v[130:131], 0, v[134:135]
	global_store_short v[134:135], v112, off
	global_store_short v[134:135], v96, off offset:64
	v_or_b32_e32 v134, v132, v182
	v_ashrrev_i32_e32 v135, 31, v134
	v_lshlrev_b64 v[134:135], 11, v[134:135]
	v_lshl_add_u64 v[134:135], v[130:131], 0, v[134:135]
	v_cvt_pk_bf16_f32 v96, v113, s0
	global_store_short v[134:135], v96, off
	v_cvt_pk_bf16_f32 v96, v97, s0
	global_store_short v[134:135], v96, off offset:64
	v_or_b32_e32 v96, v132, v183
	v_ashrrev_i32_e32 v97, 31, v96
	v_lshlrev_b64 v[96:97], 11, v[96:97]
	v_lshl_add_u64 v[96:97], v[130:131], 0, v[96:97]
	v_cvt_pk_bf16_f32 v112, v114, s0
	global_store_short v[96:97], v112, off
	global_store_short v[96:97], v98, off offset:64
	v_or_b32_e32 v96, v132, v184
	v_ashrrev_i32_e32 v97, 31, v96
	v_lshlrev_b64 v[96:97], 11, v[96:97]
	v_lshl_add_u64 v[96:97], v[130:131], 0, v[96:97]
	v_cvt_pk_bf16_f32 v98, v115, s0
	global_store_short v[96:97], v98, off
	v_cvt_pk_bf16_f32 v98, v99, s0
	global_store_short v[96:97], v98, off offset:64
	v_or_b32_e32 v96, v132, v185
	v_ashrrev_i32_e32 v97, 31, v96
	v_lshlrev_b64 v[96:97], 11, v[96:97]
	v_lshl_add_u64 v[96:97], v[130:131], 0, v[96:97]
	v_cvt_pk_bf16_f32 v98, v116, s0
	global_store_short v[96:97], v98, off
	v_cvt_pk_bf16_f32 v98, v100, s0
	global_store_short v[96:97], v98, off offset:64
	v_or_b32_e32 v96, v132, v186
	v_ashrrev_i32_e32 v97, 31, v96
	v_lshlrev_b64 v[96:97], 11, v[96:97]
	v_lshl_add_u64 v[96:97], v[130:131], 0, v[96:97]
	v_cvt_pk_bf16_f32 v98, v117, s0
	global_store_short v[96:97], v98, off
	v_cvt_pk_bf16_f32 v98, v101, s0
	global_store_short v[96:97], v98, off offset:64
	v_or_b32_e32 v96, v132, v187
	v_ashrrev_i32_e32 v97, 31, v96
	v_lshlrev_b64 v[96:97], 11, v[96:97]
	v_lshl_add_u64 v[96:97], v[130:131], 0, v[96:97]
	v_cvt_pk_bf16_f32 v98, v118, s0
	global_store_short v[96:97], v98, off
	v_cvt_pk_bf16_f32 v98, v102, s0
	global_store_short v[96:97], v98, off offset:64
	v_or_b32_e32 v96, v132, v188
	v_ashrrev_i32_e32 v97, 31, v96
	v_lshlrev_b64 v[96:97], 11, v[96:97]
	v_lshl_add_u64 v[96:97], v[130:131], 0, v[96:97]
	v_cvt_pk_bf16_f32 v98, v119, s0
	global_store_short v[96:97], v98, off
	v_cvt_pk_bf16_f32 v98, v103, s0
	global_store_short v[96:97], v98, off offset:64
	v_or_b32_e32 v96, v132, v189
	v_ashrrev_i32_e32 v97, 31, v96
	v_lshlrev_b64 v[96:97], 11, v[96:97]
	v_lshl_add_u64 v[96:97], v[130:131], 0, v[96:97]
	v_cvt_pk_bf16_f32 v98, v120, s0
	global_store_short v[96:97], v98, off
	v_cvt_pk_bf16_f32 v98, v104, s0
	global_store_short v[96:97], v98, off offset:64
	v_or_b32_e32 v96, v132, v190
	v_ashrrev_i32_e32 v97, 31, v96
	v_lshlrev_b64 v[96:97], 11, v[96:97]
	v_lshl_add_u64 v[96:97], v[130:131], 0, v[96:97]
	v_cvt_pk_bf16_f32 v98, v121, s0
	global_store_short v[96:97], v98, off
	v_cvt_pk_bf16_f32 v98, v105, s0
	global_store_short v[96:97], v98, off offset:64
	v_or_b32_e32 v96, v132, v191
	v_ashrrev_i32_e32 v97, 31, v96
	v_lshlrev_b64 v[96:97], 11, v[96:97]
	v_lshl_add_u64 v[96:97], v[130:131], 0, v[96:97]
	v_cvt_pk_bf16_f32 v98, v122, s0
	global_store_short v[96:97], v98, off
	v_cvt_pk_bf16_f32 v98, v106, s0
	global_store_short v[96:97], v98, off offset:64
	v_or_b32_e32 v96, v132, v192
	v_ashrrev_i32_e32 v97, 31, v96
	v_lshlrev_b64 v[96:97], 11, v[96:97]
	v_lshl_add_u64 v[96:97], v[130:131], 0, v[96:97]
	v_cvt_pk_bf16_f32 v98, v123, s0
	global_store_short v[96:97], v98, off
	v_cvt_pk_bf16_f32 v98, v107, s0
	global_store_short v[96:97], v98, off offset:64
	v_or_b32_e32 v96, v132, v193
	v_ashrrev_i32_e32 v97, 31, v96
	v_lshlrev_b64 v[96:97], 11, v[96:97]
	v_lshl_add_u64 v[96:97], v[130:131], 0, v[96:97]
	v_cvt_pk_bf16_f32 v98, v124, s0
	global_store_short v[96:97], v98, off
	v_cvt_pk_bf16_f32 v98, v108, s0
	global_store_short v[96:97], v98, off offset:64
	v_or_b32_e32 v96, v132, v194
	v_ashrrev_i32_e32 v97, 31, v96
	v_lshlrev_b64 v[96:97], 11, v[96:97]
	v_lshl_add_u64 v[96:97], v[130:131], 0, v[96:97]
	v_cvt_pk_bf16_f32 v98, v125, s0
	global_store_short v[96:97], v98, off
	v_cvt_pk_bf16_f32 v98, v109, s0
	global_store_short v[96:97], v98, off offset:64
	v_or_b32_e32 v96, v132, v195
	v_ashrrev_i32_e32 v97, 31, v96
	v_lshlrev_b64 v[96:97], 11, v[96:97]
	v_lshl_add_u64 v[96:97], v[130:131], 0, v[96:97]
	v_cvt_pk_bf16_f32 v98, v126, s0
	global_store_short v[96:97], v98, off
	v_cvt_pk_bf16_f32 v98, v110, s0
	global_store_short v[96:97], v98, off offset:64
	v_or_b32_e32 v96, v132, v196
	v_ashrrev_i32_e32 v97, 31, v96
	v_lshlrev_b64 v[96:97], 11, v[96:97]
	v_lshl_add_u64 v[96:97], v[130:131], 0, v[96:97]
	v_cvt_pk_bf16_f32 v98, v127, s0
	global_store_short v[96:97], v98, off
	v_cvt_pk_bf16_f32 v98, v111, s0
	global_store_short v[96:97], v98, off offset:64
	v_or_b32_e32 v98, 32, v132
	v_or_b32_e32 v96, v98, v181
	v_ashrrev_i32_e32 v97, 31, v96
	v_lshlrev_b64 v[96:97], 11, v[96:97]
	v_lshl_add_u64 v[96:97], v[130:131], 0, v[96:97]
	global_store_short v[96:97], v80, off
	global_store_short v[96:97], v64, off offset:64
	v_or_b32_e32 v96, v98, v182
	v_ashrrev_i32_e32 v97, 31, v96
	v_lshlrev_b64 v[96:97], 11, v[96:97]
	v_lshl_add_u64 v[96:97], v[130:131], 0, v[96:97]
	v_cvt_pk_bf16_f32 v64, v81, s0
	global_store_short v[96:97], v64, off
	v_cvt_pk_bf16_f32 v64, v65, s0
	global_store_short v[96:97], v64, off offset:64
	v_or_b32_e32 v64, v98, v183
	v_ashrrev_i32_e32 v65, 31, v64
	v_lshlrev_b64 v[64:65], 11, v[64:65]
	v_lshl_add_u64 v[64:65], v[130:131], 0, v[64:65]
	v_cvt_pk_bf16_f32 v80, v82, s0
	global_store_short v[64:65], v80, off
	global_store_short v[64:65], v66, off offset:64
	v_or_b32_e32 v64, v98, v184
	v_ashrrev_i32_e32 v65, 31, v64
	v_lshlrev_b64 v[64:65], 11, v[64:65]
	v_lshl_add_u64 v[64:65], v[130:131], 0, v[64:65]
	v_cvt_pk_bf16_f32 v66, v83, s0
	global_store_short v[64:65], v66, off
	v_cvt_pk_bf16_f32 v66, v67, s0
	global_store_short v[64:65], v66, off offset:64
	v_or_b32_e32 v64, v98, v185
	v_ashrrev_i32_e32 v65, 31, v64
	v_lshlrev_b64 v[64:65], 11, v[64:65]
	v_lshl_add_u64 v[64:65], v[130:131], 0, v[64:65]
	v_cvt_pk_bf16_f32 v66, v84, s0
	global_store_short v[64:65], v66, off
	v_cvt_pk_bf16_f32 v66, v68, s0
	global_store_short v[64:65], v66, off offset:64
	v_or_b32_e32 v64, v98, v186
	v_ashrrev_i32_e32 v65, 31, v64
	v_lshlrev_b64 v[64:65], 11, v[64:65]
	v_lshl_add_u64 v[64:65], v[130:131], 0, v[64:65]
	v_cvt_pk_bf16_f32 v66, v85, s0
	global_store_short v[64:65], v66, off
	v_cvt_pk_bf16_f32 v66, v69, s0
	global_store_short v[64:65], v66, off offset:64
	v_or_b32_e32 v64, v98, v187
	v_ashrrev_i32_e32 v65, 31, v64
	v_lshlrev_b64 v[64:65], 11, v[64:65]
	v_lshl_add_u64 v[64:65], v[130:131], 0, v[64:65]
	v_cvt_pk_bf16_f32 v66, v86, s0
	global_store_short v[64:65], v66, off
	v_cvt_pk_bf16_f32 v66, v70, s0
	global_store_short v[64:65], v66, off offset:64
	v_or_b32_e32 v64, v98, v188
	v_ashrrev_i32_e32 v65, 31, v64
	v_lshlrev_b64 v[64:65], 11, v[64:65]
	v_lshl_add_u64 v[64:65], v[130:131], 0, v[64:65]
	v_cvt_pk_bf16_f32 v66, v87, s0
	global_store_short v[64:65], v66, off
	v_cvt_pk_bf16_f32 v66, v71, s0
	global_store_short v[64:65], v66, off offset:64
	v_or_b32_e32 v64, v98, v189
	v_ashrrev_i32_e32 v65, 31, v64
	v_lshlrev_b64 v[64:65], 11, v[64:65]
	v_lshl_add_u64 v[64:65], v[130:131], 0, v[64:65]
	v_cvt_pk_bf16_f32 v66, v88, s0
	global_store_short v[64:65], v66, off
	v_cvt_pk_bf16_f32 v66, v72, s0
	global_store_short v[64:65], v66, off offset:64
	v_or_b32_e32 v64, v98, v190
	v_ashrrev_i32_e32 v65, 31, v64
	v_lshlrev_b64 v[64:65], 11, v[64:65]
	v_lshl_add_u64 v[64:65], v[130:131], 0, v[64:65]
	v_cvt_pk_bf16_f32 v66, v89, s0
	global_store_short v[64:65], v66, off
	v_cvt_pk_bf16_f32 v66, v73, s0
	global_store_short v[64:65], v66, off offset:64
	v_or_b32_e32 v64, v98, v191
	v_ashrrev_i32_e32 v65, 31, v64
	v_lshlrev_b64 v[64:65], 11, v[64:65]
	v_lshl_add_u64 v[64:65], v[130:131], 0, v[64:65]
	v_cvt_pk_bf16_f32 v66, v90, s0
	global_store_short v[64:65], v66, off
	v_cvt_pk_bf16_f32 v66, v74, s0
	global_store_short v[64:65], v66, off offset:64
	v_or_b32_e32 v64, v98, v192
	v_ashrrev_i32_e32 v65, 31, v64
	v_lshlrev_b64 v[64:65], 11, v[64:65]
	v_lshl_add_u64 v[64:65], v[130:131], 0, v[64:65]
	v_cvt_pk_bf16_f32 v66, v91, s0
	global_store_short v[64:65], v66, off
	v_cvt_pk_bf16_f32 v66, v75, s0
	global_store_short v[64:65], v66, off offset:64
	v_or_b32_e32 v64, v98, v193
	v_ashrrev_i32_e32 v65, 31, v64
	v_lshlrev_b64 v[64:65], 11, v[64:65]
	v_lshl_add_u64 v[64:65], v[130:131], 0, v[64:65]
	v_cvt_pk_bf16_f32 v66, v92, s0
	global_store_short v[64:65], v66, off
	v_cvt_pk_bf16_f32 v66, v76, s0
	global_store_short v[64:65], v66, off offset:64
	v_or_b32_e32 v64, v98, v194
	v_ashrrev_i32_e32 v65, 31, v64
	v_lshlrev_b64 v[64:65], 11, v[64:65]
	v_lshl_add_u64 v[64:65], v[130:131], 0, v[64:65]
	v_cvt_pk_bf16_f32 v66, v93, s0
	global_store_short v[64:65], v66, off
	v_cvt_pk_bf16_f32 v66, v77, s0
	global_store_short v[64:65], v66, off offset:64
	v_or_b32_e32 v64, v98, v195
	v_ashrrev_i32_e32 v65, 31, v64
	v_lshlrev_b64 v[64:65], 11, v[64:65]
	v_lshl_add_u64 v[64:65], v[130:131], 0, v[64:65]
	v_cvt_pk_bf16_f32 v66, v94, s0
	global_store_short v[64:65], v66, off
	v_cvt_pk_bf16_f32 v66, v78, s0
	global_store_short v[64:65], v66, off offset:64
	v_or_b32_e32 v64, v98, v196
	v_ashrrev_i32_e32 v65, 31, v64
	v_lshlrev_b64 v[64:65], 11, v[64:65]
	v_lshl_add_u64 v[64:65], v[130:131], 0, v[64:65]
	v_cvt_pk_bf16_f32 v66, v95, s0
	global_store_short v[64:65], v66, off
	v_cvt_pk_bf16_f32 v66, v79, s0
	global_store_short v[64:65], v66, off offset:64
	v_or_b32_e32 v66, 64, v132
	v_or_b32_e32 v64, v66, v181
	v_ashrrev_i32_e32 v65, 31, v64
	v_lshlrev_b64 v[64:65], 11, v[64:65]
	v_lshl_add_u64 v[64:65], v[130:131], 0, v[64:65]
	v_cvt_pk_bf16_f32 v32, v32, s0
	global_store_short v[64:65], v48, off
	global_store_short v[64:65], v32, off offset:64
	v_or_b32_e32 v64, v66, v182
	v_ashrrev_i32_e32 v65, 31, v64
	v_lshlrev_b64 v[64:65], 11, v[64:65]
	v_lshl_add_u64 v[64:65], v[130:131], 0, v[64:65]
	v_cvt_pk_bf16_f32 v32, v49, s0
	global_store_short v[64:65], v32, off
	v_cvt_pk_bf16_f32 v32, v33, s0
	global_store_short v[64:65], v32, off offset:64
	v_or_b32_e32 v32, v66, v183
	v_ashrrev_i32_e32 v33, 31, v32
	v_lshlrev_b64 v[32:33], 11, v[32:33]
	v_lshl_add_u64 v[32:33], v[130:131], 0, v[32:33]
	v_cvt_pk_bf16_f32 v48, v50, s0
	v_cvt_pk_bf16_f32 v34, v34, s0
	global_store_short v[32:33], v48, off
	global_store_short v[32:33], v34, off offset:64
	v_or_b32_e32 v32, v66, v184
	v_ashrrev_i32_e32 v33, 31, v32
	v_lshlrev_b64 v[32:33], 11, v[32:33]
	v_lshl_add_u64 v[32:33], v[130:131], 0, v[32:33]
	v_cvt_pk_bf16_f32 v34, v51, s0
	global_store_short v[32:33], v34, off
	v_cvt_pk_bf16_f32 v34, v35, s0
	global_store_short v[32:33], v34, off offset:64
	v_or_b32_e32 v32, v66, v185
	v_ashrrev_i32_e32 v33, 31, v32
	v_lshlrev_b64 v[32:33], 11, v[32:33]
	v_lshl_add_u64 v[32:33], v[130:131], 0, v[32:33]
	v_cvt_pk_bf16_f32 v34, v52, s0
	global_store_short v[32:33], v34, off
	v_cvt_pk_bf16_f32 v34, v36, s0
	global_store_short v[32:33], v34, off offset:64
	v_or_b32_e32 v32, v66, v186
	v_ashrrev_i32_e32 v33, 31, v32
	v_lshlrev_b64 v[32:33], 11, v[32:33]
	v_lshl_add_u64 v[32:33], v[130:131], 0, v[32:33]
	v_cvt_pk_bf16_f32 v34, v53, s0
	global_store_short v[32:33], v34, off
	v_cvt_pk_bf16_f32 v34, v37, s0
	global_store_short v[32:33], v34, off offset:64
	v_or_b32_e32 v32, v66, v187
	v_ashrrev_i32_e32 v33, 31, v32
	v_lshlrev_b64 v[32:33], 11, v[32:33]
	v_lshl_add_u64 v[32:33], v[130:131], 0, v[32:33]
	v_cvt_pk_bf16_f32 v34, v54, s0
	global_store_short v[32:33], v34, off
	v_cvt_pk_bf16_f32 v34, v38, s0
	global_store_short v[32:33], v34, off offset:64
	v_or_b32_e32 v32, v66, v188
	v_ashrrev_i32_e32 v33, 31, v32
	v_lshlrev_b64 v[32:33], 11, v[32:33]
	v_lshl_add_u64 v[32:33], v[130:131], 0, v[32:33]
	v_cvt_pk_bf16_f32 v34, v55, s0
	global_store_short v[32:33], v34, off
	v_cvt_pk_bf16_f32 v34, v39, s0
	global_store_short v[32:33], v34, off offset:64
	v_or_b32_e32 v32, v66, v189
	v_ashrrev_i32_e32 v33, 31, v32
	v_lshlrev_b64 v[32:33], 11, v[32:33]
	v_lshl_add_u64 v[32:33], v[130:131], 0, v[32:33]
	v_cvt_pk_bf16_f32 v34, v56, s0
	global_store_short v[32:33], v34, off
	v_cvt_pk_bf16_f32 v34, v40, s0
	global_store_short v[32:33], v34, off offset:64
	v_or_b32_e32 v32, v66, v190
	v_ashrrev_i32_e32 v33, 31, v32
	v_lshlrev_b64 v[32:33], 11, v[32:33]
	v_lshl_add_u64 v[32:33], v[130:131], 0, v[32:33]
	v_cvt_pk_bf16_f32 v34, v57, s0
	global_store_short v[32:33], v34, off
	v_cvt_pk_bf16_f32 v34, v41, s0
	global_store_short v[32:33], v34, off offset:64
	v_or_b32_e32 v32, v66, v191
	v_ashrrev_i32_e32 v33, 31, v32
	v_lshlrev_b64 v[32:33], 11, v[32:33]
	v_lshl_add_u64 v[32:33], v[130:131], 0, v[32:33]
	v_cvt_pk_bf16_f32 v34, v58, s0
	global_store_short v[32:33], v34, off
	v_cvt_pk_bf16_f32 v34, v42, s0
	global_store_short v[32:33], v34, off offset:64
	v_or_b32_e32 v32, v66, v192
	v_ashrrev_i32_e32 v33, 31, v32
	v_lshlrev_b64 v[32:33], 11, v[32:33]
	v_lshl_add_u64 v[32:33], v[130:131], 0, v[32:33]
	v_cvt_pk_bf16_f32 v34, v59, s0
	global_store_short v[32:33], v34, off
	v_cvt_pk_bf16_f32 v34, v43, s0
	global_store_short v[32:33], v34, off offset:64
	v_or_b32_e32 v32, v66, v193
	v_ashrrev_i32_e32 v33, 31, v32
	v_lshlrev_b64 v[32:33], 11, v[32:33]
	v_lshl_add_u64 v[32:33], v[130:131], 0, v[32:33]
	v_cvt_pk_bf16_f32 v34, v60, s0
	global_store_short v[32:33], v34, off
	v_cvt_pk_bf16_f32 v34, v44, s0
	global_store_short v[32:33], v34, off offset:64
	v_or_b32_e32 v32, v66, v194
	v_ashrrev_i32_e32 v33, 31, v32
	v_lshlrev_b64 v[32:33], 11, v[32:33]
	v_lshl_add_u64 v[32:33], v[130:131], 0, v[32:33]
	v_cvt_pk_bf16_f32 v34, v61, s0
	global_store_short v[32:33], v34, off
	v_cvt_pk_bf16_f32 v34, v45, s0
	global_store_short v[32:33], v34, off offset:64
	v_or_b32_e32 v32, v66, v195
	v_ashrrev_i32_e32 v33, 31, v32
	v_lshlrev_b64 v[32:33], 11, v[32:33]
	v_lshl_add_u64 v[32:33], v[130:131], 0, v[32:33]
	v_cvt_pk_bf16_f32 v34, v62, s0
	global_store_short v[32:33], v34, off
	v_cvt_pk_bf16_f32 v34, v46, s0
	global_store_short v[32:33], v34, off offset:64
	v_or_b32_e32 v32, v66, v196
	v_ashrrev_i32_e32 v33, 31, v32
	v_lshlrev_b64 v[32:33], 11, v[32:33]
	v_lshl_add_u64 v[32:33], v[130:131], 0, v[32:33]
	v_cvt_pk_bf16_f32 v34, v63, s0
	global_store_short v[32:33], v34, off
	v_cvt_pk_bf16_f32 v34, v47, s0
	global_store_short v[32:33], v34, off offset:64
	v_or_b32_e32 v34, 0x60, v132
	v_or_b32_e32 v32, v34, v181
	v_ashrrev_i32_e32 v33, 31, v32
	v_lshlrev_b64 v[32:33], 11, v[32:33]
	v_lshl_add_u64 v[32:33], v[130:131], 0, v[32:33]
	v_cvt_pk_bf16_f32 v0, v0, s0
	global_store_short v[32:33], v16, off
	global_store_short v[32:33], v0, off offset:64
	v_or_b32_e32 v32, v34, v182
	v_ashrrev_i32_e32 v33, 31, v32
	v_lshlrev_b64 v[32:33], 11, v[32:33]
	v_lshl_add_u64 v[32:33], v[130:131], 0, v[32:33]
	v_cvt_pk_bf16_f32 v0, v17, s0
	global_store_short v[32:33], v0, off
	v_cvt_pk_bf16_f32 v0, v1, s0
	global_store_short v[32:33], v0, off offset:64
	v_or_b32_e32 v0, v34, v183
	v_ashrrev_i32_e32 v1, 31, v0
	v_lshlrev_b64 v[0:1], 11, v[0:1]
	v_lshl_add_u64 v[0:1], v[130:131], 0, v[0:1]
	v_cvt_pk_bf16_f32 v16, v18, s0
	v_cvt_pk_bf16_f32 v2, v2, s0
	global_store_short v[0:1], v16, off
	global_store_short v[0:1], v2, off offset:64
	v_or_b32_e32 v0, v34, v184
	v_ashrrev_i32_e32 v1, 31, v0
	v_lshlrev_b64 v[0:1], 11, v[0:1]
	v_lshl_add_u64 v[0:1], v[130:131], 0, v[0:1]
	v_cvt_pk_bf16_f32 v2, v19, s0
	global_store_short v[0:1], v2, off
	v_cvt_pk_bf16_f32 v2, v3, s0
	global_store_short v[0:1], v2, off offset:64
	v_or_b32_e32 v0, v34, v185
	v_ashrrev_i32_e32 v1, 31, v0
	v_lshlrev_b64 v[0:1], 11, v[0:1]
	v_lshl_add_u64 v[0:1], v[130:131], 0, v[0:1]
	v_cvt_pk_bf16_f32 v2, v20, s0
	global_store_short v[0:1], v2, off
	v_cvt_pk_bf16_f32 v2, v4, s0
	global_store_short v[0:1], v2, off offset:64
	v_or_b32_e32 v0, v34, v186
	v_ashrrev_i32_e32 v1, 31, v0
	v_lshlrev_b64 v[0:1], 11, v[0:1]
	v_lshl_add_u64 v[0:1], v[130:131], 0, v[0:1]
	v_cvt_pk_bf16_f32 v2, v21, s0
	global_store_short v[0:1], v2, off
	v_cvt_pk_bf16_f32 v2, v5, s0
	global_store_short v[0:1], v2, off offset:64
	v_or_b32_e32 v0, v34, v187
	v_ashrrev_i32_e32 v1, 31, v0
	v_lshlrev_b64 v[0:1], 11, v[0:1]
	v_lshl_add_u64 v[0:1], v[130:131], 0, v[0:1]
	v_cvt_pk_bf16_f32 v2, v22, s0
	global_store_short v[0:1], v2, off
	v_cvt_pk_bf16_f32 v2, v6, s0
	global_store_short v[0:1], v2, off offset:64
	v_or_b32_e32 v0, v34, v188
	v_ashrrev_i32_e32 v1, 31, v0
	v_lshlrev_b64 v[0:1], 11, v[0:1]
	v_lshl_add_u64 v[0:1], v[130:131], 0, v[0:1]
	v_cvt_pk_bf16_f32 v2, v23, s0
	global_store_short v[0:1], v2, off
	v_cvt_pk_bf16_f32 v2, v7, s0
	global_store_short v[0:1], v2, off offset:64
	v_or_b32_e32 v0, v34, v189
	v_ashrrev_i32_e32 v1, 31, v0
	v_lshlrev_b64 v[0:1], 11, v[0:1]
	v_lshl_add_u64 v[0:1], v[130:131], 0, v[0:1]
	v_cvt_pk_bf16_f32 v2, v24, s0
	global_store_short v[0:1], v2, off
	v_cvt_pk_bf16_f32 v2, v8, s0
	global_store_short v[0:1], v2, off offset:64
	v_or_b32_e32 v0, v34, v190
	v_ashrrev_i32_e32 v1, 31, v0
	v_lshlrev_b64 v[0:1], 11, v[0:1]
	v_lshl_add_u64 v[0:1], v[130:131], 0, v[0:1]
	v_cvt_pk_bf16_f32 v2, v25, s0
	global_store_short v[0:1], v2, off
	v_cvt_pk_bf16_f32 v2, v9, s0
	global_store_short v[0:1], v2, off offset:64
	v_or_b32_e32 v0, v34, v191
	v_ashrrev_i32_e32 v1, 31, v0
	v_lshlrev_b64 v[0:1], 11, v[0:1]
	v_lshl_add_u64 v[0:1], v[130:131], 0, v[0:1]
	v_cvt_pk_bf16_f32 v2, v26, s0
	global_store_short v[0:1], v2, off
	v_cvt_pk_bf16_f32 v2, v10, s0
	global_store_short v[0:1], v2, off offset:64
	v_or_b32_e32 v0, v34, v192
	v_ashrrev_i32_e32 v1, 31, v0
	v_lshlrev_b64 v[0:1], 11, v[0:1]
	v_lshl_add_u64 v[0:1], v[130:131], 0, v[0:1]
	v_cvt_pk_bf16_f32 v2, v27, s0
	global_store_short v[0:1], v2, off
	v_cvt_pk_bf16_f32 v2, v11, s0
	global_store_short v[0:1], v2, off offset:64
	v_or_b32_e32 v0, v34, v193
	v_ashrrev_i32_e32 v1, 31, v0
	v_lshlrev_b64 v[0:1], 11, v[0:1]
	v_lshl_add_u64 v[0:1], v[130:131], 0, v[0:1]
	v_cvt_pk_bf16_f32 v2, v28, s0
	global_store_short v[0:1], v2, off
	v_cvt_pk_bf16_f32 v2, v12, s0
	global_store_short v[0:1], v2, off offset:64
	v_or_b32_e32 v0, v34, v194
	v_ashrrev_i32_e32 v1, 31, v0
	v_lshlrev_b64 v[0:1], 11, v[0:1]
	v_lshl_add_u64 v[0:1], v[130:131], 0, v[0:1]
	v_cvt_pk_bf16_f32 v2, v29, s0
	global_store_short v[0:1], v2, off
	v_cvt_pk_bf16_f32 v2, v13, s0
	global_store_short v[0:1], v2, off offset:64
	v_or_b32_e32 v0, v34, v195
	v_ashrrev_i32_e32 v1, 31, v0
	v_lshlrev_b64 v[0:1], 11, v[0:1]
	v_lshl_add_u64 v[0:1], v[130:131], 0, v[0:1]
	v_cvt_pk_bf16_f32 v2, v30, s0
	global_store_short v[0:1], v2, off
	v_cvt_pk_bf16_f32 v2, v14, s0
	global_store_short v[0:1], v2, off offset:64
	v_or_b32_e32 v0, v34, v196
	v_ashrrev_i32_e32 v1, 31, v0
	v_lshlrev_b64 v[0:1], 11, v[0:1]
	v_lshl_add_u64 v[0:1], v[130:131], 0, v[0:1]
	v_cvt_pk_bf16_f32 v2, v31, s0
	global_store_short v[0:1], v2, off
	v_cvt_pk_bf16_f32 v2, v15, s0
	s_add_i32 s0, s0, s3
	v_readlane_b32 s3, v252, 8
	s_add_i32 s2, s2, s3
	s_cmp_gt_i32 s6, 31
	global_store_short v[0:1], v2, off offset:64
	s_cbranch_scc0 .LBB0_2550
